# K-loop load segments reordered: LDS-DMA issue before the ds_reads (on top of v22)
# baseline (speedup 1.0000x reference)
; #define PG8_WAIT_V(n) asm volatile("s_waitcnt vmcnt(" #n ")" ::: "memory")
; #define PG8_WAIT_L(n) asm volatile("s_waitcnt lgkmcnt(" #n ")" ::: "memory")
; template <class Epi, class Sched, bool ALIGN_EPI = false, bool SP2 = false>
; __device__ __forceinline__ void gemm_phase(PG8_LAS unsigned char* lds, const Gemm g, const Sched& S, const Epi& E) {
;     ...
;         const bool has_next = S.next(ui + 1, nxt);
;         const char* nA = has_next ? (const char*)g.A + (size_t)nxt.pm * tstep : cA; const char* nB = has_next ? (const char*)g.Bt + (size_t)nxt.pn * tstep : cB;
;         constexpr int NSEG = (Epi::MID_T >= 0) ? 2 : 1;
; #pragma unroll 1
;         for (int seg = 0; seg < NSEG; ++seg) {
;         const int t_lo = (seg == 0) ? 0 : Epi::MID_T, t_hi = (NSEG == 2 && seg == 0) ? Epi::MID_T : nt;
;         if constexpr (Epi::MID_T >= 0) { if (seg == 1) E.mid(acc, ui, wr, fr); }
;         for (int t = t_lo; t < t_hi; t += 2) {
;             const bool last = (t == nt - 2);
;             const char* a1 = cA + (size_t)(t + 1) * kstep;
;             const char* a2 = last ? nA : cA + (size_t)(t + 2) * kstep; const char* b2 = last ? nB : cB + (size_t)(t + 2) * kstep;
;             const char* a3 = a2 + kstep; const char* b3 = b2 + kstep;
;             if (last && has_next) S.a_ready_inloop(nxt, ui + 1);
;             if constexpr (SP2) {
;             PG8_LDB(B0, 0, 0); PG8_LDB(B1, 0, 1); PG8_SCHED; PG8_LDA(At, 0, 0); PG8_STAGE(PG8_SA(1, 1), a1 + hstep, voffA);
;             PG8_WAIT_V(8); PG8_WAIT_L(0); PG8_BAR; PG8_MMA(0, 0, At, B0); PG8_MMA(0, 1, At, B1); PG8_BAR; PG8_SCHED;
;             PG8_LDA(At, 0, 1); PG8_STAGE(PG8_SB(0, 0), b2, voffB); PG8_STAGE(PG8_SB(0, 1), b2 + hstep, voffB); PG8_STAGE(PG8_SA(0, 0), a2, voffA);
;             PG8_WAIT_V(8); PG8_WAIT_L(0); PG8_BAR; PG8_MMA(1, 0, At, B0); PG8_MMA(1, 1, At, B1); PG8_BAR; PG8_SCHED;
;             PG8_LDB(B0, 1, 0); PG8_LDB(B1, 1, 1); PG8_SCHED; PG8_LDA(At, 1, 0); PG8_STAGE(PG8_SA(0, 1), a2 + hstep, voffA);
;             PG8_WAIT_V(8); PG8_WAIT_L(0); PG8_BAR; PG8_MMA(0, 0, At, B0); PG8_MMA(0, 1, At, B1); PG8_BAR; PG8_SCHED;
;             PG8_LDA(At, 1, 1); PG8_STAGE(PG8_SB(1, 0), b3, voffB); PG8_STAGE(PG8_SB(1, 1), b3 + hstep, voffB); PG8_STAGE(PG8_SA(1, 0), a3, voffA);
;             PG8_WAIT_V(8); PG8_WAIT_L(0); PG8_BAR; PG8_MMA(1, 0, At, B0); PG8_MMA(1, 1, At, B1); PG8_BAR; PG8_SCHED;
.LBB0_120:
	s_ashr_i32 s13, s12, 31
	s_lshl_b64 s[16:17], s[12:13], 19
	s_add_u32 s16, s28, s16
	s_addc_u32 s17, s29, s17
	s_and_b64 s[18:19], s[2:3], exec
	s_cselect_b32 s13, s17, s21
	s_cselect_b32 s52, s16, s20
	s_ashr_i32 s15, s14, 31
	s_lshl_b64 s[18:19], s[14:15], 19
	s_add_u32 s18, s30, s18
	s_addc_u32 s19, s31, s19
	s_and_b64 s[24:25], s[2:3], exec
	s_cselect_b32 s15, s19, s23
	s_cselect_b32 s53, s18, s22
	s_add_u32 s20, s20, 0x40080
	s_addc_u32 s21, s21, 0
	s_add_u32 s62, s22, 0x100
	s_addc_u32 s63, s23, 0
	s_mov_b32 s64, -2
	s_add_u32 s22, s20, 0xfffc0080
	s_addc_u32 s23, s21, -1
	s_add_i32 s90, 0, 0x10000
	s_cmp_eq_u32 s64, 12
	s_cselect_b32 s25, s13, s23
	s_cselect_b32 s24, s52, s22
	s_cselect_b32 s23, s15, s63
	s_cselect_b32 s22, s53, s62
	s_add_u32 s98, s22, s46
	s_addc_u32 s99, s23, s47
	s_add_u32 s100, s24, s46
	s_addc_u32 s101, s25, s47
	s_add_i32 s81, 0, 0x14000
	s_add_i32 m0, s35, 0xc000
	s_nop 0
	global_load_lds_dwordx4 v154, s[20:21]
	s_add_i32 m0, s35, 0xe000
	s_nop 0
	global_load_lds_dwordx4 v156, s[20:21]
	v_add_u32_e32 v158, s90, v160
	ds_read_b128 v[164:167], v158
	ds_read_b128 v[168:171], v158 offset:1024
	ds_read_b128 v[172:175], v158 offset:2048
	ds_read_b128 v[176:179], v158 offset:3072
	v_add_u32_e32 v158, s81, v160
	ds_read_b128 v[180:183], v158
	ds_read_b128 v[184:187], v158 offset:1024
	ds_read_b128 v[188:191], v158 offset:2048
	ds_read_b128 v[192:195], v158 offset:3072
	ds_read_b128 v[196:199], v163
	ds_read_b128 v[200:203], v163 offset:1024
	ds_read_b128 v[216:219], v163 offset:2048
	ds_read_b128 v[220:223], v163 offset:3072
	ds_read_b128 v[224:227], v163 offset:4096
	ds_read_b128 v[228:231], v163 offset:5120
	ds_read_b128 v[232:235], v163 offset:6144
	ds_read_b128 v[236:239], v163 offset:7168
	s_waitcnt vmcnt(8) lgkmcnt(0)
	s_barrier
	s_setprio 1
	v_mfma_f32_16x16x32_bf16 v[142:145], v[164:167], v[196:199], 0
	v_mfma_f32_16x16x32_bf16 v[138:141], v[172:175], v[196:199], 0
	v_mfma_f32_16x16x32_bf16 v[126:129], v[164:167], v[216:219], 0
	v_mfma_f32_16x16x32_bf16 v[122:125], v[172:175], v[216:219], 0
	v_mfma_f32_16x16x32_bf16 v[110:113], v[164:167], v[224:227], 0
	v_mfma_f32_16x16x32_bf16 v[106:109], v[172:175], v[224:227], 0
	v_mfma_f32_16x16x32_bf16 v[94:97], v[164:167], v[232:235], 0
	v_mfma_f32_16x16x32_bf16 v[90:93], v[172:175], v[232:235], 0
	v_mfma_f32_16x16x32_bf16 v[142:145], v[168:171], v[200:203], v[142:145]
	v_mfma_f32_16x16x32_bf16 v[138:141], v[176:179], v[200:203], v[138:141]
	v_mfma_f32_16x16x32_bf16 v[126:129], v[168:171], v[220:223], v[126:129]
	v_mfma_f32_16x16x32_bf16 v[122:125], v[176:179], v[220:223], v[122:125]
	v_mfma_f32_16x16x32_bf16 v[110:113], v[168:171], v[228:231], v[110:113]
	v_mfma_f32_16x16x32_bf16 v[106:109], v[176:179], v[228:231], v[106:109]
	v_mfma_f32_16x16x32_bf16 v[94:97], v[168:171], v[236:239], v[94:97]
	v_mfma_f32_16x16x32_bf16 v[90:93], v[176:179], v[236:239], v[90:93]
	v_mfma_f32_16x16x32_bf16 v[134:137], v[180:183], v[196:199], 0
	v_mfma_f32_16x16x32_bf16 v[130:133], v[188:191], v[196:199], 0
	v_mfma_f32_16x16x32_bf16 v[118:121], v[180:183], v[216:219], 0
	v_mfma_f32_16x16x32_bf16 v[114:117], v[188:191], v[216:219], 0
	v_mfma_f32_16x16x32_bf16 v[102:105], v[180:183], v[224:227], 0
	v_mfma_f32_16x16x32_bf16 v[98:101], v[188:191], v[224:227], 0
	v_mfma_f32_16x16x32_bf16 v[86:89], v[180:183], v[232:235], 0
	v_mfma_f32_16x16x32_bf16 v[82:85], v[188:191], v[232:235], 0
	v_mfma_f32_16x16x32_bf16 v[134:137], v[184:187], v[200:203], v[134:137]
	v_mfma_f32_16x16x32_bf16 v[130:133], v[192:195], v[200:203], v[130:133]
	v_mfma_f32_16x16x32_bf16 v[118:121], v[184:187], v[220:223], v[118:121]
	v_mfma_f32_16x16x32_bf16 v[114:117], v[192:195], v[220:223], v[114:117]
	v_mfma_f32_16x16x32_bf16 v[102:105], v[184:187], v[228:231], v[102:105]
	v_mfma_f32_16x16x32_bf16 v[98:101], v[192:195], v[228:231], v[98:101]
	v_mfma_f32_16x16x32_bf16 v[86:89], v[184:187], v[236:239], v[86:89]
	v_mfma_f32_16x16x32_bf16 v[82:85], v[192:195], v[236:239], v[82:85]
	s_setprio 0
	s_barrier
	s_add_i32 s65, s90, s34
	s_mov_b32 m0, s65
	s_nop 0
	global_load_lds_dwordx4 v148, s[22:23]
	s_add_i32 m0, s65, 0x2000
	s_add_u32 s66, s22, 0x40000
	s_addc_u32 s67, s23, 0
	s_add_i32 s65, s81, s34
	global_load_lds_dwordx4 v152, s[22:23]
	s_mov_b32 m0, s65
	s_nop 0
	global_load_lds_dwordx4 v148, s[66:67]
	s_add_i32 m0, s65, 0x2000
	s_nop 0
	global_load_lds_dwordx4 v152, s[66:67]
	s_mov_b32 m0, s35
	s_nop 0
	global_load_lds_dwordx4 v146, s[24:25]
	s_mov_b32 m0, s36
	s_nop 0
	global_load_lds_dwordx4 v150, s[24:25]
	ds_read_b128 v[196:199], v163 offset:16384
	ds_read_b128 v[200:203], v163 offset:17408
	ds_read_b128 v[216:219], v163 offset:18432
	ds_read_b128 v[220:223], v163 offset:19456
	ds_read_b128 v[224:227], v163 offset:20480
	ds_read_b128 v[228:231], v163 offset:21504
	ds_read_b128 v[232:235], v163 offset:22528
	ds_read_b128 v[236:239], v163 offset:23552
	s_waitcnt vmcnt(8) lgkmcnt(0)
	s_barrier
; #define PG8_STAGE(bufoff, gbase, voff) do { _Pragma("unroll") for (int _i = 0; _i < 2; ++_i) \
;         __builtin_amdgcn_global_load_lds((const unsigned*)((const char*)(gbase) + (voff)[_i]), (PG8_LAS unsigned*)(lds + (bufoff) + ldsw + _i * 8192), 16, 0, 0); } while (0)
; #define PG8_LDA(dst, b, h) do { _Pragma("unroll") for (int m = 0; m < 4; ++m) _Pragma("unroll") for (int k = 0; k < 2; ++k) dst[m][k] = *(const PG8_LAS bf16x8*)(lds + PG8_SA(b, h) + aoff + m * 2048 + k * 1024); } while (0)
; #define PG8_LDB(dst, b, h) do { _Pragma("unroll") for (int n = 0; n < 2; ++n) _Pragma("unroll") for (int k = 0; k < 2; ++k) dst[n][k] = *(const PG8_LAS bf16x8*)(lds + PG8_SB(b, h) + boff + n * 2048 + k * 1024); } while (0)
; #define PG8_MMA(ai, bj, At, Bt) do { __builtin_amdgcn_s_setprio(1); _Pragma("unroll") for (int m = 0; m < 4; ++m) _Pragma("unroll") for (int n = 0; n < 2; ++n) _Pragma("unroll") for (int k = 0; k < 2; ++k) \
;         acc[ai][bj][m][n] = __builtin_amdgcn_mfma_f32_16x16x32_bf16(Bt[n][k], At[m][k], acc[ai][bj][m][n], 0, 0, 0); __builtin_amdgcn_s_setprio(0); } while (0)
; #define PG8_WAIT_V(n) asm volatile("s_waitcnt vmcnt(" #n ")" ::: "memory")
; template <class Epi, class Sched, bool ALIGN_EPI = false, bool SP2 = false>
; __device__ __forceinline__ void gemm_phase(PG8_LAS unsigned char* lds, const Gemm g, const Sched& S, const Epi& E) {
;     ...
;             PG8_LDB(B0, 0, 0); PG8_LDB(B1, 0, 1); PG8_SCHED; PG8_LDA(At, 0, 0); PG8_STAGE(PG8_SA(1, 1), a1 + hstep, voffA);
;             PG8_WAIT_V(8); PG8_WAIT_L(0); PG8_BAR; PG8_MMA(0, 0, At, B0); PG8_MMA(0, 1, At, B1); PG8_BAR; PG8_SCHED;
;             PG8_LDA(At, 0, 1); PG8_STAGE(PG8_SB(0, 0), b2, voffB); PG8_STAGE(PG8_SB(0, 1), b2 + hstep, voffB); PG8_STAGE(PG8_SA(0, 0), a2, voffA);
;             PG8_WAIT_V(8); PG8_WAIT_L(0); PG8_BAR; PG8_MMA(1, 0, At, B0); PG8_MMA(1, 1, At, B1); PG8_BAR; PG8_SCHED;
;             PG8_LDB(B0, 1, 0); PG8_LDB(B1, 1, 1); PG8_SCHED; PG8_LDA(At, 1, 0); PG8_STAGE(PG8_SA(0, 1), a2 + hstep, voffA);
;             PG8_WAIT_V(8); PG8_WAIT_L(0); PG8_BAR; PG8_MMA(0, 0, At, B0); PG8_MMA(0, 1, At, B1); PG8_BAR; PG8_SCHED;
;             PG8_LDA(At, 1, 1); PG8_STAGE(PG8_SB(1, 0), b3, voffB); PG8_STAGE(PG8_SB(1, 1), b3 + hstep, voffB); PG8_STAGE(PG8_SA(1, 0), a3, voffA);
;             PG8_WAIT_V(8); PG8_WAIT_L(0); PG8_BAR; PG8_MMA(1, 0, At, B0); PG8_MMA(1, 1, At, B1); PG8_BAR; PG8_SCHED;
	s_setprio 1
	v_mfma_f32_16x16x32_bf16 v[78:81], v[164:167], v[196:199], 0
	v_mfma_f32_16x16x32_bf16 v[74:77], v[172:175], v[196:199], 0
	v_mfma_f32_16x16x32_bf16 v[62:65], v[164:167], v[216:219], 0
	v_mfma_f32_16x16x32_bf16 v[58:61], v[172:175], v[216:219], 0
	v_mfma_f32_16x16x32_bf16 v[46:49], v[164:167], v[224:227], 0
	v_mfma_f32_16x16x32_bf16 v[42:45], v[172:175], v[224:227], 0
	v_mfma_f32_16x16x32_bf16 v[30:33], v[164:167], v[232:235], 0
	v_mfma_f32_16x16x32_bf16 v[26:29], v[172:175], v[232:235], 0
	v_mfma_f32_16x16x32_bf16 v[78:81], v[168:171], v[200:203], v[78:81]
	v_mfma_f32_16x16x32_bf16 v[74:77], v[176:179], v[200:203], v[74:77]
	v_mfma_f32_16x16x32_bf16 v[62:65], v[168:171], v[220:223], v[62:65]
	v_mfma_f32_16x16x32_bf16 v[58:61], v[176:179], v[220:223], v[58:61]
	v_mfma_f32_16x16x32_bf16 v[46:49], v[168:171], v[228:231], v[46:49]
	v_mfma_f32_16x16x32_bf16 v[42:45], v[176:179], v[228:231], v[42:45]
	v_mfma_f32_16x16x32_bf16 v[30:33], v[168:171], v[236:239], v[30:33]
	v_mfma_f32_16x16x32_bf16 v[26:29], v[176:179], v[236:239], v[26:29]
	v_mfma_f32_16x16x32_bf16 v[70:73], v[180:183], v[196:199], 0
	v_mfma_f32_16x16x32_bf16 v[66:69], v[188:191], v[196:199], 0
	v_mfma_f32_16x16x32_bf16 v[54:57], v[180:183], v[216:219], 0
	v_mfma_f32_16x16x32_bf16 v[50:53], v[188:191], v[216:219], 0
	v_mfma_f32_16x16x32_bf16 v[38:41], v[180:183], v[224:227], 0
	v_mfma_f32_16x16x32_bf16 v[34:37], v[188:191], v[224:227], 0
	v_mfma_f32_16x16x32_bf16 v[22:25], v[180:183], v[232:235], 0
	v_mfma_f32_16x16x32_bf16 v[18:21], v[188:191], v[232:235], 0
	v_mfma_f32_16x16x32_bf16 v[70:73], v[184:187], v[200:203], v[70:73]
	v_mfma_f32_16x16x32_bf16 v[66:69], v[192:195], v[200:203], v[66:69]
	v_mfma_f32_16x16x32_bf16 v[54:57], v[184:187], v[220:223], v[54:57]
	v_mfma_f32_16x16x32_bf16 v[50:53], v[192:195], v[220:223], v[50:53]
	v_mfma_f32_16x16x32_bf16 v[38:41], v[184:187], v[228:231], v[38:41]
	v_mfma_f32_16x16x32_bf16 v[34:37], v[192:195], v[228:231], v[34:37]
	v_mfma_f32_16x16x32_bf16 v[22:25], v[184:187], v[236:239], v[22:25]
	v_mfma_f32_16x16x32_bf16 v[18:21], v[192:195], v[236:239], v[18:21]
	s_setprio 0
	s_barrier
	s_add_i32 s82, 0, 0x18000
	s_add_i32 s83, 0, 0x1c000
	s_add_u32 s24, s24, 0x40000
	s_addc_u32 s25, s25, 0
	s_mov_b32 m0, s37
	s_nop 0
	global_load_lds_dwordx4 v146, s[24:25]
	s_mov_b32 m0, s38
	s_nop 0
	global_load_lds_dwordx4 v150, s[24:25]
	v_add_u32_e32 v176, s82, v160
	v_add_u32_e32 v192, s83, v160
	ds_read_b128 v[164:167], v176
	ds_read_b128 v[168:171], v176 offset:1024
	ds_read_b128 v[172:175], v176 offset:2048
	ds_read_b128 v[176:179], v176 offset:3072
	ds_read_b128 v[180:183], v192
	ds_read_b128 v[184:187], v192 offset:1024
	ds_read_b128 v[188:191], v192 offset:2048
	ds_read_b128 v[192:195], v192 offset:3072
	ds_read_b128 v[196:199], v163 offset:32768
	ds_read_b128 v[200:203], v163 offset:33792
	ds_read_b128 v[216:219], v163 offset:34816
	ds_read_b128 v[220:223], v163 offset:35840
	ds_read_b128 v[224:227], v163 offset:36864
	ds_read_b128 v[228:231], v163 offset:37888
	ds_read_b128 v[232:235], v163 offset:38912
	ds_read_b128 v[236:239], v163 offset:39936
	s_waitcnt vmcnt(8) lgkmcnt(0)
	s_barrier
	s_setprio 1
	v_mfma_f32_16x16x32_bf16 v[142:145], v[164:167], v[196:199], v[142:145]
	v_mfma_f32_16x16x32_bf16 v[138:141], v[172:175], v[196:199], v[138:141]
	v_mfma_f32_16x16x32_bf16 v[126:129], v[164:167], v[216:219], v[126:129]
	v_mfma_f32_16x16x32_bf16 v[122:125], v[172:175], v[216:219], v[122:125]
	v_mfma_f32_16x16x32_bf16 v[110:113], v[164:167], v[224:227], v[110:113]
	v_mfma_f32_16x16x32_bf16 v[106:109], v[172:175], v[224:227], v[106:109]
	v_mfma_f32_16x16x32_bf16 v[94:97], v[164:167], v[232:235], v[94:97]
	v_mfma_f32_16x16x32_bf16 v[90:93], v[172:175], v[232:235], v[90:93]
	v_mfma_f32_16x16x32_bf16 v[142:145], v[168:171], v[200:203], v[142:145]
	v_mfma_f32_16x16x32_bf16 v[138:141], v[176:179], v[200:203], v[138:141]
	v_mfma_f32_16x16x32_bf16 v[126:129], v[168:171], v[220:223], v[126:129]
	v_mfma_f32_16x16x32_bf16 v[122:125], v[176:179], v[220:223], v[122:125]
	v_mfma_f32_16x16x32_bf16 v[110:113], v[168:171], v[228:231], v[110:113]
	v_mfma_f32_16x16x32_bf16 v[106:109], v[176:179], v[228:231], v[106:109]
	v_mfma_f32_16x16x32_bf16 v[94:97], v[168:171], v[236:239], v[94:97]
	v_mfma_f32_16x16x32_bf16 v[90:93], v[176:179], v[236:239], v[90:93]
	v_mfma_f32_16x16x32_bf16 v[134:137], v[180:183], v[196:199], v[134:137]
	v_mfma_f32_16x16x32_bf16 v[130:133], v[188:191], v[196:199], v[130:133]
	v_mfma_f32_16x16x32_bf16 v[118:121], v[180:183], v[216:219], v[118:121]
	v_mfma_f32_16x16x32_bf16 v[114:117], v[188:191], v[216:219], v[114:117]
	v_mfma_f32_16x16x32_bf16 v[102:105], v[180:183], v[224:227], v[102:105]
	v_mfma_f32_16x16x32_bf16 v[98:101], v[188:191], v[224:227], v[98:101]
	v_mfma_f32_16x16x32_bf16 v[86:89], v[180:183], v[232:235], v[86:89]
	v_mfma_f32_16x16x32_bf16 v[82:85], v[188:191], v[232:235], v[82:85]
	v_mfma_f32_16x16x32_bf16 v[134:137], v[184:187], v[200:203], v[134:137]
	v_mfma_f32_16x16x32_bf16 v[130:133], v[192:195], v[200:203], v[130:133]
	v_mfma_f32_16x16x32_bf16 v[118:121], v[184:187], v[220:223], v[118:121]
	v_mfma_f32_16x16x32_bf16 v[114:117], v[192:195], v[220:223], v[114:117]
	v_mfma_f32_16x16x32_bf16 v[102:105], v[184:187], v[228:231], v[102:105]
	v_mfma_f32_16x16x32_bf16 v[98:101], v[192:195], v[228:231], v[98:101]
	v_mfma_f32_16x16x32_bf16 v[86:89], v[184:187], v[236:239], v[86:89]
	v_mfma_f32_16x16x32_bf16 v[82:85], v[192:195], v[236:239], v[82:85]
	s_setprio 0
	s_barrier
; #define PG8_STAGE(bufoff, gbase, voff) do { _Pragma("unroll") for (int _i = 0; _i < 2; ++_i) \
;         __builtin_amdgcn_global_load_lds((const unsigned*)((const char*)(gbase) + (voff)[_i]), (PG8_LAS unsigned*)(lds + (bufoff) + ldsw + _i * 8192), 16, 0, 0); } while (0)
; #define PG8_LDA(dst, b, h) do { _Pragma("unroll") for (int m = 0; m < 4; ++m) _Pragma("unroll") for (int k = 0; k < 2; ++k) dst[m][k] = *(const PG8_LAS bf16x8*)(lds + PG8_SA(b, h) + aoff + m * 2048 + k * 1024); } while (0)
; #define PG8_WAIT_V(n) asm volatile("s_waitcnt vmcnt(" #n ")" ::: "memory")
; #define PG8_WAIT_L(n) asm volatile("s_waitcnt lgkmcnt(" #n ")" ::: "memory")
; #define PG8_BAR __builtin_amdgcn_s_barrier()
; template <class Epi, class Sched, bool ALIGN_EPI = false, bool SP2 = false>
; __device__ __forceinline__ void gemm_phase(PG8_LAS unsigned char* lds, const Gemm g, const Sched& S, const Epi& E) {
;     ...
;         for (int t = t_lo; t < t_hi; t += 2) {
;             const bool last = (t == nt - 2);
;             const char* a1 = cA + (size_t)(t + 1) * kstep;
;             const char* a2 = last ? nA : cA + (size_t)(t + 2) * kstep; const char* b2 = last ? nB : cB + (size_t)(t + 2) * kstep;
;             const char* a3 = a2 + kstep; const char* b3 = b2 + kstep;
;             if (last && has_next) S.a_ready_inloop(nxt, ui + 1);
;             if constexpr (SP2) {
;             PG8_LDB(B0, 0, 0); PG8_LDB(B1, 0, 1); PG8_SCHED; PG8_LDA(At, 0, 0); PG8_STAGE(PG8_SA(1, 1), a1 + hstep, voffA);
;             PG8_WAIT_V(8); PG8_WAIT_L(0); PG8_BAR; PG8_MMA(0, 0, At, B0); PG8_MMA(0, 1, At, B1); PG8_BAR; PG8_SCHED;
;             PG8_LDA(At, 0, 1); PG8_STAGE(PG8_SB(0, 0), b2, voffB); PG8_STAGE(PG8_SB(0, 1), b2 + hstep, voffB); PG8_STAGE(PG8_SA(0, 0), a2, voffA);
;             PG8_WAIT_V(8); PG8_WAIT_L(0); PG8_BAR; PG8_MMA(1, 0, At, B0); PG8_MMA(1, 1, At, B1); PG8_BAR; PG8_SCHED;
;             PG8_LDB(B0, 1, 0); PG8_LDB(B1, 1, 1); PG8_SCHED; PG8_LDA(At, 1, 0); PG8_STAGE(PG8_SA(0, 1), a2 + hstep, voffA);
;             PG8_WAIT_V(8); PG8_WAIT_L(0); PG8_BAR; PG8_MMA(0, 0, At, B0); PG8_MMA(0, 1, At, B1); PG8_BAR; PG8_SCHED;
;             PG8_LDA(At, 1, 1); PG8_STAGE(PG8_SB(1, 0), b3, voffB); PG8_STAGE(PG8_SB(1, 1), b3 + hstep, voffB); PG8_STAGE(PG8_SA(1, 0), a3, voffA);
;             PG8_WAIT_V(8); PG8_WAIT_L(0); PG8_BAR; PG8_MMA(1, 0, At, B0); PG8_MMA(1, 1, At, B1); PG8_BAR; PG8_SCHED;
	s_add_i32 s24, s82, s34
	s_mov_b32 m0, s24
	s_nop 0
	global_load_lds_dwordx4 v148, s[98:99]
	s_add_i32 m0, s24, 0x2000
	s_add_u32 s22, s22, 0x40080
	s_addc_u32 s23, s23, 0
	s_add_i32 s24, s83, s34
	global_load_lds_dwordx4 v152, s[98:99]
	s_mov_b32 m0, s24
	s_nop 0
	global_load_lds_dwordx4 v148, s[22:23]
	s_add_i32 m0, s24, 0x2000
	s_nop 0
	global_load_lds_dwordx4 v152, s[22:23]
	s_mov_b32 m0, s39
	s_nop 0
	global_load_lds_dwordx4 v146, s[100:101]
	s_mov_b32 m0, s42
	s_nop 0
	global_load_lds_dwordx4 v150, s[100:101]
	ds_read_b128 v[196:199], v163 offset:49152
	ds_read_b128 v[200:203], v163 offset:50176
	ds_read_b128 v[216:219], v163 offset:51200
	ds_read_b128 v[220:223], v163 offset:52224
	ds_read_b128 v[224:227], v163 offset:53248
	ds_read_b128 v[228:231], v163 offset:54272
	ds_read_b128 v[232:235], v163 offset:55296
	ds_read_b128 v[236:239], v163 offset:56320
	s_waitcnt vmcnt(8) lgkmcnt(0)
	s_barrier
	s_setprio 1
	v_mfma_f32_16x16x32_bf16 v[78:81], v[164:167], v[196:199], v[78:81]
	v_mfma_f32_16x16x32_bf16 v[74:77], v[172:175], v[196:199], v[74:77]
	v_mfma_f32_16x16x32_bf16 v[62:65], v[164:167], v[216:219], v[62:65]
	v_mfma_f32_16x16x32_bf16 v[58:61], v[172:175], v[216:219], v[58:61]
	v_mfma_f32_16x16x32_bf16 v[46:49], v[164:167], v[224:227], v[46:49]
	v_mfma_f32_16x16x32_bf16 v[42:45], v[172:175], v[224:227], v[42:45]
	v_mfma_f32_16x16x32_bf16 v[30:33], v[164:167], v[232:235], v[30:33]
	v_mfma_f32_16x16x32_bf16 v[26:29], v[172:175], v[232:235], v[26:29]
	v_mfma_f32_16x16x32_bf16 v[78:81], v[168:171], v[200:203], v[78:81]
	v_mfma_f32_16x16x32_bf16 v[74:77], v[176:179], v[200:203], v[74:77]
	v_mfma_f32_16x16x32_bf16 v[62:65], v[168:171], v[220:223], v[62:65]
	v_mfma_f32_16x16x32_bf16 v[58:61], v[176:179], v[220:223], v[58:61]
	v_mfma_f32_16x16x32_bf16 v[46:49], v[168:171], v[228:231], v[46:49]
	v_mfma_f32_16x16x32_bf16 v[42:45], v[176:179], v[228:231], v[42:45]
	v_mfma_f32_16x16x32_bf16 v[30:33], v[168:171], v[236:239], v[30:33]
	v_mfma_f32_16x16x32_bf16 v[26:29], v[176:179], v[236:239], v[26:29]
	v_mfma_f32_16x16x32_bf16 v[70:73], v[180:183], v[196:199], v[70:73]
	v_mfma_f32_16x16x32_bf16 v[66:69], v[188:191], v[196:199], v[66:69]
	v_mfma_f32_16x16x32_bf16 v[54:57], v[180:183], v[216:219], v[54:57]
	v_mfma_f32_16x16x32_bf16 v[50:53], v[188:191], v[216:219], v[50:53]
	v_mfma_f32_16x16x32_bf16 v[38:41], v[180:183], v[224:227], v[38:41]
	v_mfma_f32_16x16x32_bf16 v[34:37], v[188:191], v[224:227], v[34:37]
	v_mfma_f32_16x16x32_bf16 v[22:25], v[180:183], v[232:235], v[22:25]
	v_mfma_f32_16x16x32_bf16 v[18:21], v[188:191], v[232:235], v[18:21]
	v_mfma_f32_16x16x32_bf16 v[70:73], v[184:187], v[200:203], v[70:73]
	v_mfma_f32_16x16x32_bf16 v[66:69], v[192:195], v[200:203], v[66:69]
	v_mfma_f32_16x16x32_bf16 v[54:57], v[184:187], v[220:223], v[54:57]
	v_mfma_f32_16x16x32_bf16 v[50:53], v[192:195], v[220:223], v[50:53]
	v_mfma_f32_16x16x32_bf16 v[38:41], v[184:187], v[228:231], v[38:41]
	v_mfma_f32_16x16x32_bf16 v[34:37], v[192:195], v[228:231], v[34:37]
	v_mfma_f32_16x16x32_bf16 v[22:25], v[184:187], v[236:239], v[22:25]
	v_mfma_f32_16x16x32_bf16 v[18:21], v[192:195], v[236:239], v[18:21]
	s_setprio 0
	s_barrier
	s_add_i32 s64, s64, 2
	s_add_u32 s20, s20, 0x100
	s_addc_u32 s21, s21, 0
	s_add_u32 s62, s62, 0x100
	s_addc_u32 s63, s63, 0
.LBB0_121:
	s_add_u32 s22, s20, 0xfffc0080
	s_addc_u32 s23, s21, -1
	s_add_i32 s90, 0, 0x10000
	s_cmp_eq_u32 s64, 12
	s_cselect_b32 s25, s13, s23
	s_cselect_b32 s24, s52, s22
	s_cselect_b32 s23, s15, s63
	s_cselect_b32 s22, s53, s62
	s_add_u32 s98, s22, s46
	s_addc_u32 s99, s23, s47
	s_add_u32 s100, s24, s46
	s_addc_u32 s101, s25, s47
	s_add_i32 s81, 0, 0x14000
	s_add_i32 m0, s35, 0xc000
	s_nop 0
	global_load_lds_dwordx4 v154, s[20:21]
	s_add_i32 m0, s35, 0xe000
	s_nop 0
	global_load_lds_dwordx4 v156, s[20:21]
	v_add_u32_e32 v158, s90, v160
	ds_read_b128 v[164:167], v158
	ds_read_b128 v[168:171], v158 offset:1024
	ds_read_b128 v[172:175], v158 offset:2048
	ds_read_b128 v[176:179], v158 offset:3072
	v_add_u32_e32 v158, s81, v160
	ds_read_b128 v[180:183], v158
	ds_read_b128 v[184:187], v158 offset:1024
	ds_read_b128 v[188:191], v158 offset:2048
	ds_read_b128 v[192:195], v158 offset:3072
	ds_read_b128 v[196:199], v163
	ds_read_b128 v[200:203], v163 offset:1024
	ds_read_b128 v[216:219], v163 offset:2048
	ds_read_b128 v[220:223], v163 offset:3072
	ds_read_b128 v[224:227], v163 offset:4096
	ds_read_b128 v[228:231], v163 offset:5120
	ds_read_b128 v[232:235], v163 offset:6144
	ds_read_b128 v[236:239], v163 offset:7168
	s_waitcnt vmcnt(8) lgkmcnt(0)
	s_barrier
; #define PG8_STAGE(bufoff, gbase, voff) do { _Pragma("unroll") for (int _i = 0; _i < 2; ++_i) \
;         __builtin_amdgcn_global_load_lds((const unsigned*)((const char*)(gbase) + (voff)[_i]), (PG8_LAS unsigned*)(lds + (bufoff) + ldsw + _i * 8192), 16, 0, 0); } while (0)
; #define PG8_LDA(dst, b, h) do { _Pragma("unroll") for (int m = 0; m < 4; ++m) _Pragma("unroll") for (int k = 0; k < 2; ++k) dst[m][k] = *(const PG8_LAS bf16x8*)(lds + PG8_SA(b, h) + aoff + m * 2048 + k * 1024); } while (0)
; #define PG8_LDB(dst, b, h) do { _Pragma("unroll") for (int n = 0; n < 2; ++n) _Pragma("unroll") for (int k = 0; k < 2; ++k) dst[n][k] = *(const PG8_LAS bf16x8*)(lds + PG8_SB(b, h) + boff + n * 2048 + k * 1024); } while (0)
; #define PG8_MMA(ai, bj, At, Bt) do { __builtin_amdgcn_s_setprio(1); _Pragma("unroll") for (int m = 0; m < 4; ++m) _Pragma("unroll") for (int n = 0; n < 2; ++n) _Pragma("unroll") for (int k = 0; k < 2; ++k) \
;         acc[ai][bj][m][n] = __builtin_amdgcn_mfma_f32_16x16x32_bf16(Bt[n][k], At[m][k], acc[ai][bj][m][n], 0, 0, 0); __builtin_amdgcn_s_setprio(0); } while (0)
; #define PG8_BAR __builtin_amdgcn_s_barrier()
; template <class Epi, class Sched, bool ALIGN_EPI = false, bool SP2 = false>
; __device__ __forceinline__ void gemm_phase(PG8_LAS unsigned char* lds, const Gemm g, const Sched& S, const Epi& E) {
;     ...
;             if constexpr (SP2) {
;             PG8_LDB(B0, 0, 0); PG8_LDB(B1, 0, 1); PG8_SCHED; PG8_LDA(At, 0, 0); PG8_STAGE(PG8_SA(1, 1), a1 + hstep, voffA);
;             PG8_WAIT_V(8); PG8_WAIT_L(0); PG8_BAR; PG8_MMA(0, 0, At, B0); PG8_MMA(0, 1, At, B1); PG8_BAR; PG8_SCHED;
;             PG8_LDA(At, 0, 1); PG8_STAGE(PG8_SB(0, 0), b2, voffB); PG8_STAGE(PG8_SB(0, 1), b2 + hstep, voffB); PG8_STAGE(PG8_SA(0, 0), a2, voffA);
;             PG8_WAIT_V(8); PG8_WAIT_L(0); PG8_BAR; PG8_MMA(1, 0, At, B0); PG8_MMA(1, 1, At, B1); PG8_BAR; PG8_SCHED;
;             PG8_LDB(B0, 1, 0); PG8_LDB(B1, 1, 1); PG8_SCHED; PG8_LDA(At, 1, 0); PG8_STAGE(PG8_SA(0, 1), a2 + hstep, voffA);
;             PG8_WAIT_V(8); PG8_WAIT_L(0); PG8_BAR; PG8_MMA(0, 0, At, B0); PG8_MMA(0, 1, At, B1); PG8_BAR; PG8_SCHED;
;             PG8_LDA(At, 1, 1); PG8_STAGE(PG8_SB(1, 0), b3, voffB); PG8_STAGE(PG8_SB(1, 1), b3 + hstep, voffB); PG8_STAGE(PG8_SA(1, 0), a3, voffA);
;             PG8_WAIT_V(8); PG8_WAIT_L(0); PG8_BAR; PG8_MMA(1, 0, At, B0); PG8_MMA(1, 1, At, B1); PG8_BAR; PG8_SCHED;
	s_setprio 1
	v_mfma_f32_16x16x32_bf16 v[142:145], v[164:167], v[196:199], v[142:145]
	v_mfma_f32_16x16x32_bf16 v[138:141], v[172:175], v[196:199], v[138:141]
	v_mfma_f32_16x16x32_bf16 v[126:129], v[164:167], v[216:219], v[126:129]
	v_mfma_f32_16x16x32_bf16 v[122:125], v[172:175], v[216:219], v[122:125]
	v_mfma_f32_16x16x32_bf16 v[110:113], v[164:167], v[224:227], v[110:113]
	v_mfma_f32_16x16x32_bf16 v[106:109], v[172:175], v[224:227], v[106:109]
	v_mfma_f32_16x16x32_bf16 v[94:97], v[164:167], v[232:235], v[94:97]
	v_mfma_f32_16x16x32_bf16 v[90:93], v[172:175], v[232:235], v[90:93]
	v_mfma_f32_16x16x32_bf16 v[142:145], v[168:171], v[200:203], v[142:145]
	v_mfma_f32_16x16x32_bf16 v[138:141], v[176:179], v[200:203], v[138:141]
	v_mfma_f32_16x16x32_bf16 v[126:129], v[168:171], v[220:223], v[126:129]
	v_mfma_f32_16x16x32_bf16 v[122:125], v[176:179], v[220:223], v[122:125]
	v_mfma_f32_16x16x32_bf16 v[110:113], v[168:171], v[228:231], v[110:113]
	v_mfma_f32_16x16x32_bf16 v[106:109], v[176:179], v[228:231], v[106:109]
	v_mfma_f32_16x16x32_bf16 v[94:97], v[168:171], v[236:239], v[94:97]
	v_mfma_f32_16x16x32_bf16 v[90:93], v[176:179], v[236:239], v[90:93]
	v_mfma_f32_16x16x32_bf16 v[134:137], v[180:183], v[196:199], v[134:137]
	v_mfma_f32_16x16x32_bf16 v[130:133], v[188:191], v[196:199], v[130:133]
	v_mfma_f32_16x16x32_bf16 v[118:121], v[180:183], v[216:219], v[118:121]
	v_mfma_f32_16x16x32_bf16 v[114:117], v[188:191], v[216:219], v[114:117]
	v_mfma_f32_16x16x32_bf16 v[102:105], v[180:183], v[224:227], v[102:105]
	v_mfma_f32_16x16x32_bf16 v[98:101], v[188:191], v[224:227], v[98:101]
	v_mfma_f32_16x16x32_bf16 v[86:89], v[180:183], v[232:235], v[86:89]
	v_mfma_f32_16x16x32_bf16 v[82:85], v[188:191], v[232:235], v[82:85]
	v_mfma_f32_16x16x32_bf16 v[134:137], v[184:187], v[200:203], v[134:137]
	v_mfma_f32_16x16x32_bf16 v[130:133], v[192:195], v[200:203], v[130:133]
	v_mfma_f32_16x16x32_bf16 v[118:121], v[184:187], v[220:223], v[118:121]
	v_mfma_f32_16x16x32_bf16 v[114:117], v[192:195], v[220:223], v[114:117]
	v_mfma_f32_16x16x32_bf16 v[102:105], v[184:187], v[228:231], v[102:105]
	v_mfma_f32_16x16x32_bf16 v[98:101], v[192:195], v[228:231], v[98:101]
	v_mfma_f32_16x16x32_bf16 v[86:89], v[184:187], v[236:239], v[86:89]
	v_mfma_f32_16x16x32_bf16 v[82:85], v[192:195], v[236:239], v[82:85]
	s_setprio 0
	s_barrier
	s_add_i32 s65, s90, s34
	s_mov_b32 m0, s65
	s_nop 0
	global_load_lds_dwordx4 v148, s[22:23]
	s_add_i32 m0, s65, 0x2000
	s_add_u32 s66, s22, 0x40000
	s_addc_u32 s67, s23, 0
	s_add_i32 s65, s81, s34
	global_load_lds_dwordx4 v152, s[22:23]
	s_mov_b32 m0, s65
	s_nop 0
	global_load_lds_dwordx4 v148, s[66:67]
	s_add_i32 m0, s65, 0x2000
	s_nop 0
	global_load_lds_dwordx4 v152, s[66:67]
	s_mov_b32 m0, s35
	s_nop 0
	global_load_lds_dwordx4 v146, s[24:25]
	s_mov_b32 m0, s36
	s_nop 0
	global_load_lds_dwordx4 v150, s[24:25]
	ds_read_b128 v[196:199], v163 offset:16384
	ds_read_b128 v[200:203], v163 offset:17408
	ds_read_b128 v[216:219], v163 offset:18432
	ds_read_b128 v[220:223], v163 offset:19456
	ds_read_b128 v[224:227], v163 offset:20480
	ds_read_b128 v[228:231], v163 offset:21504
	ds_read_b128 v[232:235], v163 offset:22528
	ds_read_b128 v[236:239], v163 offset:23552
	s_waitcnt vmcnt(8) lgkmcnt(0)
	s_barrier
	s_setprio 1
	v_mfma_f32_16x16x32_bf16 v[78:81], v[164:167], v[196:199], v[78:81]
	v_mfma_f32_16x16x32_bf16 v[74:77], v[172:175], v[196:199], v[74:77]
	v_mfma_f32_16x16x32_bf16 v[62:65], v[164:167], v[216:219], v[62:65]
	v_mfma_f32_16x16x32_bf16 v[58:61], v[172:175], v[216:219], v[58:61]
	v_mfma_f32_16x16x32_bf16 v[46:49], v[164:167], v[224:227], v[46:49]
	v_mfma_f32_16x16x32_bf16 v[42:45], v[172:175], v[224:227], v[42:45]
	v_mfma_f32_16x16x32_bf16 v[30:33], v[164:167], v[232:235], v[30:33]
	v_mfma_f32_16x16x32_bf16 v[26:29], v[172:175], v[232:235], v[26:29]
	v_mfma_f32_16x16x32_bf16 v[78:81], v[168:171], v[200:203], v[78:81]
	v_mfma_f32_16x16x32_bf16 v[74:77], v[176:179], v[200:203], v[74:77]
	v_mfma_f32_16x16x32_bf16 v[62:65], v[168:171], v[220:223], v[62:65]
	v_mfma_f32_16x16x32_bf16 v[58:61], v[176:179], v[220:223], v[58:61]
	v_mfma_f32_16x16x32_bf16 v[46:49], v[168:171], v[228:231], v[46:49]
	v_mfma_f32_16x16x32_bf16 v[42:45], v[176:179], v[228:231], v[42:45]
	v_mfma_f32_16x16x32_bf16 v[30:33], v[168:171], v[236:239], v[30:33]
	v_mfma_f32_16x16x32_bf16 v[26:29], v[176:179], v[236:239], v[26:29]
	v_mfma_f32_16x16x32_bf16 v[70:73], v[180:183], v[196:199], v[70:73]
	v_mfma_f32_16x16x32_bf16 v[66:69], v[188:191], v[196:199], v[66:69]
	v_mfma_f32_16x16x32_bf16 v[54:57], v[180:183], v[216:219], v[54:57]
	v_mfma_f32_16x16x32_bf16 v[50:53], v[188:191], v[216:219], v[50:53]
	v_mfma_f32_16x16x32_bf16 v[38:41], v[180:183], v[224:227], v[38:41]
	v_mfma_f32_16x16x32_bf16 v[34:37], v[188:191], v[224:227], v[34:37]
	v_mfma_f32_16x16x32_bf16 v[22:25], v[180:183], v[232:235], v[22:25]
	v_mfma_f32_16x16x32_bf16 v[18:21], v[188:191], v[232:235], v[18:21]
	v_mfma_f32_16x16x32_bf16 v[70:73], v[184:187], v[200:203], v[70:73]
	v_mfma_f32_16x16x32_bf16 v[66:69], v[192:195], v[200:203], v[66:69]
	v_mfma_f32_16x16x32_bf16 v[54:57], v[184:187], v[220:223], v[54:57]
	v_mfma_f32_16x16x32_bf16 v[50:53], v[192:195], v[220:223], v[50:53]
	v_mfma_f32_16x16x32_bf16 v[38:41], v[184:187], v[228:231], v[38:41]
	v_mfma_f32_16x16x32_bf16 v[34:37], v[192:195], v[228:231], v[34:37]
	v_mfma_f32_16x16x32_bf16 v[22:25], v[184:187], v[236:239], v[22:25]
	v_mfma_f32_16x16x32_bf16 v[18:21], v[192:195], v[236:239], v[18:21]
	s_setprio 0
	s_barrier
; #define PG8_STAGE(bufoff, gbase, voff) do { _Pragma("unroll") for (int _i = 0; _i < 2; ++_i) \
;         __builtin_amdgcn_global_load_lds((const unsigned*)((const char*)(gbase) + (voff)[_i]), (PG8_LAS unsigned*)(lds + (bufoff) + ldsw + _i * 8192), 16, 0, 0); } while (0)
; #define PG8_LDA(dst, b, h) do { _Pragma("unroll") for (int m = 0; m < 4; ++m) _Pragma("unroll") for (int k = 0; k < 2; ++k) dst[m][k] = *(const PG8_LAS bf16x8*)(lds + PG8_SA(b, h) + aoff + m * 2048 + k * 1024); } while (0)
; #define PG8_LDB(dst, b, h) do { _Pragma("unroll") for (int n = 0; n < 2; ++n) _Pragma("unroll") for (int k = 0; k < 2; ++k) dst[n][k] = *(const PG8_LAS bf16x8*)(lds + PG8_SB(b, h) + boff + n * 2048 + k * 1024); } while (0)
; #define PG8_MMA(ai, bj, At, Bt) do { __builtin_amdgcn_s_setprio(1); _Pragma("unroll") for (int m = 0; m < 4; ++m) _Pragma("unroll") for (int n = 0; n < 2; ++n) _Pragma("unroll") for (int k = 0; k < 2; ++k) \
;         acc[ai][bj][m][n] = __builtin_amdgcn_mfma_f32_16x16x32_bf16(Bt[n][k], At[m][k], acc[ai][bj][m][n], 0, 0, 0); __builtin_amdgcn_s_setprio(0); } while (0)
; #define PG8_BAR __builtin_amdgcn_s_barrier()
; template <class Epi, class Sched, bool ALIGN_EPI = false, bool SP2 = false>
; __device__ __forceinline__ void gemm_phase(PG8_LAS unsigned char* lds, const Gemm g, const Sched& S, const Epi& E) {
;     ...
;             if constexpr (SP2) {
;             PG8_LDB(B0, 0, 0); PG8_LDB(B1, 0, 1); PG8_SCHED; PG8_LDA(At, 0, 0); PG8_STAGE(PG8_SA(1, 1), a1 + hstep, voffA);
;             PG8_WAIT_V(8); PG8_WAIT_L(0); PG8_BAR; PG8_MMA(0, 0, At, B0); PG8_MMA(0, 1, At, B1); PG8_BAR; PG8_SCHED;
;             PG8_LDA(At, 0, 1); PG8_STAGE(PG8_SB(0, 0), b2, voffB); PG8_STAGE(PG8_SB(0, 1), b2 + hstep, voffB); PG8_STAGE(PG8_SA(0, 0), a2, voffA);
;             PG8_WAIT_V(8); PG8_WAIT_L(0); PG8_BAR; PG8_MMA(1, 0, At, B0); PG8_MMA(1, 1, At, B1); PG8_BAR; PG8_SCHED;
;             PG8_LDB(B0, 1, 0); PG8_LDB(B1, 1, 1); PG8_SCHED; PG8_LDA(At, 1, 0); PG8_STAGE(PG8_SA(0, 1), a2 + hstep, voffA);
;             PG8_WAIT_V(8); PG8_WAIT_L(0); PG8_BAR; PG8_MMA(0, 0, At, B0); PG8_MMA(0, 1, At, B1); PG8_BAR; PG8_SCHED;
;             PG8_LDA(At, 1, 1); PG8_STAGE(PG8_SB(1, 0), b3, voffB); PG8_STAGE(PG8_SB(1, 1), b3 + hstep, voffB); PG8_STAGE(PG8_SA(1, 0), a3, voffA);
;             PG8_WAIT_V(8); PG8_WAIT_L(0); PG8_BAR; PG8_MMA(1, 0, At, B0); PG8_MMA(1, 1, At, B1); PG8_BAR; PG8_SCHED;
	s_add_i32 s82, 0, 0x18000
	s_add_i32 s83, 0, 0x1c000
	s_add_u32 s24, s24, 0x40000
	s_addc_u32 s25, s25, 0
	s_mov_b32 m0, s37
	s_nop 0
	global_load_lds_dwordx4 v146, s[24:25]
	s_mov_b32 m0, s38
	s_nop 0
	global_load_lds_dwordx4 v150, s[24:25]
	v_add_u32_e32 v176, s82, v160
	v_add_u32_e32 v192, s83, v160
	ds_read_b128 v[164:167], v176
	ds_read_b128 v[168:171], v176 offset:1024
	ds_read_b128 v[172:175], v176 offset:2048
	ds_read_b128 v[176:179], v176 offset:3072
	ds_read_b128 v[180:183], v192
	ds_read_b128 v[184:187], v192 offset:1024
	ds_read_b128 v[188:191], v192 offset:2048
	ds_read_b128 v[192:195], v192 offset:3072
	ds_read_b128 v[196:199], v163 offset:32768
	ds_read_b128 v[200:203], v163 offset:33792
	ds_read_b128 v[216:219], v163 offset:34816
	ds_read_b128 v[220:223], v163 offset:35840
	ds_read_b128 v[224:227], v163 offset:36864
	ds_read_b128 v[228:231], v163 offset:37888
	ds_read_b128 v[232:235], v163 offset:38912
	ds_read_b128 v[236:239], v163 offset:39936
	s_waitcnt vmcnt(8) lgkmcnt(0)
	s_barrier
	s_setprio 1
	v_mfma_f32_16x16x32_bf16 v[142:145], v[164:167], v[196:199], v[142:145]
	v_mfma_f32_16x16x32_bf16 v[138:141], v[172:175], v[196:199], v[138:141]
	v_mfma_f32_16x16x32_bf16 v[126:129], v[164:167], v[216:219], v[126:129]
	v_mfma_f32_16x16x32_bf16 v[122:125], v[172:175], v[216:219], v[122:125]
	v_mfma_f32_16x16x32_bf16 v[110:113], v[164:167], v[224:227], v[110:113]
	v_mfma_f32_16x16x32_bf16 v[106:109], v[172:175], v[224:227], v[106:109]
	v_mfma_f32_16x16x32_bf16 v[94:97], v[164:167], v[232:235], v[94:97]
	v_mfma_f32_16x16x32_bf16 v[90:93], v[172:175], v[232:235], v[90:93]
	v_mfma_f32_16x16x32_bf16 v[142:145], v[168:171], v[200:203], v[142:145]
	v_mfma_f32_16x16x32_bf16 v[138:141], v[176:179], v[200:203], v[138:141]
	v_mfma_f32_16x16x32_bf16 v[126:129], v[168:171], v[220:223], v[126:129]
	v_mfma_f32_16x16x32_bf16 v[122:125], v[176:179], v[220:223], v[122:125]
	v_mfma_f32_16x16x32_bf16 v[110:113], v[168:171], v[228:231], v[110:113]
	v_mfma_f32_16x16x32_bf16 v[106:109], v[176:179], v[228:231], v[106:109]
	v_mfma_f32_16x16x32_bf16 v[94:97], v[168:171], v[236:239], v[94:97]
	v_mfma_f32_16x16x32_bf16 v[90:93], v[176:179], v[236:239], v[90:93]
	v_mfma_f32_16x16x32_bf16 v[134:137], v[180:183], v[196:199], v[134:137]
	v_mfma_f32_16x16x32_bf16 v[130:133], v[188:191], v[196:199], v[130:133]
	v_mfma_f32_16x16x32_bf16 v[118:121], v[180:183], v[216:219], v[118:121]
	v_mfma_f32_16x16x32_bf16 v[114:117], v[188:191], v[216:219], v[114:117]
	v_mfma_f32_16x16x32_bf16 v[102:105], v[180:183], v[224:227], v[102:105]
	v_mfma_f32_16x16x32_bf16 v[98:101], v[188:191], v[224:227], v[98:101]
	v_mfma_f32_16x16x32_bf16 v[86:89], v[180:183], v[232:235], v[86:89]
	v_mfma_f32_16x16x32_bf16 v[82:85], v[188:191], v[232:235], v[82:85]
	v_mfma_f32_16x16x32_bf16 v[134:137], v[184:187], v[200:203], v[134:137]
	v_mfma_f32_16x16x32_bf16 v[130:133], v[192:195], v[200:203], v[130:133]
	v_mfma_f32_16x16x32_bf16 v[118:121], v[184:187], v[220:223], v[118:121]
	v_mfma_f32_16x16x32_bf16 v[114:117], v[192:195], v[220:223], v[114:117]
	v_mfma_f32_16x16x32_bf16 v[102:105], v[184:187], v[228:231], v[102:105]
	v_mfma_f32_16x16x32_bf16 v[98:101], v[192:195], v[228:231], v[98:101]
	v_mfma_f32_16x16x32_bf16 v[86:89], v[184:187], v[236:239], v[86:89]
	v_mfma_f32_16x16x32_bf16 v[82:85], v[192:195], v[236:239], v[82:85]
	s_setprio 0
	s_barrier
	s_add_i32 s24, s82, s34
	s_mov_b32 m0, s24
	s_nop 0
	global_load_lds_dwordx4 v148, s[98:99]
	s_add_i32 m0, s24, 0x2000
	s_add_u32 s22, s22, 0x40080
	s_addc_u32 s23, s23, 0
	s_add_i32 s24, s83, s34
	global_load_lds_dwordx4 v152, s[98:99]
	s_mov_b32 m0, s24
	s_nop 0
	global_load_lds_dwordx4 v148, s[22:23]
	s_add_i32 m0, s24, 0x2000
	s_nop 0
	global_load_lds_dwordx4 v152, s[22:23]
	s_mov_b32 m0, s39
	s_nop 0
	global_load_lds_dwordx4 v146, s[100:101]
	s_mov_b32 m0, s42
	s_nop 0
	global_load_lds_dwordx4 v150, s[100:101]
	ds_read_b128 v[196:199], v163 offset:49152
	ds_read_b128 v[200:203], v163 offset:50176
	ds_read_b128 v[216:219], v163 offset:51200
	ds_read_b128 v[220:223], v163 offset:52224
	ds_read_b128 v[224:227], v163 offset:53248
	ds_read_b128 v[228:231], v163 offset:54272
	ds_read_b128 v[232:235], v163 offset:55296
	ds_read_b128 v[236:239], v163 offset:56320
	s_waitcnt vmcnt(8) lgkmcnt(0)
	s_barrier
	s_setprio 1
	v_mfma_f32_16x16x32_bf16 v[78:81], v[164:167], v[196:199], v[78:81]
	v_mfma_f32_16x16x32_bf16 v[74:77], v[172:175], v[196:199], v[74:77]
	v_mfma_f32_16x16x32_bf16 v[62:65], v[164:167], v[216:219], v[62:65]
	v_mfma_f32_16x16x32_bf16 v[58:61], v[172:175], v[216:219], v[58:61]
	v_mfma_f32_16x16x32_bf16 v[46:49], v[164:167], v[224:227], v[46:49]
	v_mfma_f32_16x16x32_bf16 v[42:45], v[172:175], v[224:227], v[42:45]
	v_mfma_f32_16x16x32_bf16 v[30:33], v[164:167], v[232:235], v[30:33]
	v_mfma_f32_16x16x32_bf16 v[26:29], v[172:175], v[232:235], v[26:29]
	v_mfma_f32_16x16x32_bf16 v[78:81], v[168:171], v[200:203], v[78:81]
	v_mfma_f32_16x16x32_bf16 v[74:77], v[176:179], v[200:203], v[74:77]
	v_mfma_f32_16x16x32_bf16 v[62:65], v[168:171], v[220:223], v[62:65]
	v_mfma_f32_16x16x32_bf16 v[58:61], v[176:179], v[220:223], v[58:61]
	v_mfma_f32_16x16x32_bf16 v[46:49], v[168:171], v[228:231], v[46:49]
	v_mfma_f32_16x16x32_bf16 v[42:45], v[176:179], v[228:231], v[42:45]
	v_mfma_f32_16x16x32_bf16 v[30:33], v[168:171], v[236:239], v[30:33]
	v_mfma_f32_16x16x32_bf16 v[26:29], v[176:179], v[236:239], v[26:29]
	v_mfma_f32_16x16x32_bf16 v[70:73], v[180:183], v[196:199], v[70:73]
	v_mfma_f32_16x16x32_bf16 v[66:69], v[188:191], v[196:199], v[66:69]
	v_mfma_f32_16x16x32_bf16 v[54:57], v[180:183], v[216:219], v[54:57]
	v_mfma_f32_16x16x32_bf16 v[50:53], v[188:191], v[216:219], v[50:53]
	v_mfma_f32_16x16x32_bf16 v[38:41], v[180:183], v[224:227], v[38:41]
	v_mfma_f32_16x16x32_bf16 v[34:37], v[188:191], v[224:227], v[34:37]
	v_mfma_f32_16x16x32_bf16 v[22:25], v[180:183], v[232:235], v[22:25]
	v_mfma_f32_16x16x32_bf16 v[18:21], v[188:191], v[232:235], v[18:21]
	v_mfma_f32_16x16x32_bf16 v[70:73], v[184:187], v[200:203], v[70:73]
	v_mfma_f32_16x16x32_bf16 v[66:69], v[192:195], v[200:203], v[66:69]
	v_mfma_f32_16x16x32_bf16 v[54:57], v[184:187], v[220:223], v[54:57]
	v_mfma_f32_16x16x32_bf16 v[50:53], v[192:195], v[220:223], v[50:53]
	v_mfma_f32_16x16x32_bf16 v[38:41], v[184:187], v[228:231], v[38:41]
	v_mfma_f32_16x16x32_bf16 v[34:37], v[192:195], v[228:231], v[34:37]
	v_mfma_f32_16x16x32_bf16 v[22:25], v[184:187], v[236:239], v[22:25]
	v_mfma_f32_16x16x32_bf16 v[18:21], v[192:195], v[236:239], v[18:21]
	s_setprio 0
	s_barrier
	s_add_i32 s64, s64, 2
	s_add_u32 s20, s20, 0x100
	s_addc_u32 s21, s21, 0
	s_add_u32 s62, s62, 0x100
	s_addc_u32 s63, s63, 0
	s_cmp_gt_u32 s64, 13
	s_cbranch_scc0 .LBB0_121
	s_and_b64 vcc, exec, s[10:11]
	s_cbranch_vccz .LBB0_124
	s_barrier

; #define PG8_STAGE(bufoff, gbase, voff) do { _Pragma("unroll") for (int _i = 0; _i < 2; ++_i) \
;         __builtin_amdgcn_global_load_lds((const unsigned*)((const char*)(gbase) + (voff)[_i]), (PG8_LAS unsigned*)(lds + (bufoff) + ldsw + _i * 8192), 16, 0, 0); } while (0)
; #define PG8_LDA(dst, b, h) do { _Pragma("unroll") for (int m = 0; m < 4; ++m) _Pragma("unroll") for (int k = 0; k < 2; ++k) dst[m][k] = *(const PG8_LAS bf16x8*)(lds + PG8_SA(b, h) + aoff + m * 2048 + k * 1024); } while (0)
; #define PG8_WAIT_V(n) asm volatile("s_waitcnt vmcnt(" #n ")" ::: "memory")
; #define PG8_WAIT_L(n) asm volatile("s_waitcnt lgkmcnt(" #n ")" ::: "memory")
; #define PG8_BAR __builtin_amdgcn_s_barrier()
; template <class Epi, class Sched, bool ALIGN_EPI = false, bool SP2 = false>
; __device__ __forceinline__ void gemm_phase(PG8_LAS unsigned char* lds, const Gemm g, const Sched& S, const Epi& E) {
;     ...
;         for (int t = t_lo; t < t_hi; t += 2) {
;             const bool last = (t == nt - 2);
;             const char* a1 = cA + (size_t)(t + 1) * kstep;
;             const char* a2 = last ? nA : cA + (size_t)(t + 2) * kstep; const char* b2 = last ? nB : cB + (size_t)(t + 2) * kstep;
;             const char* a3 = a2 + kstep; const char* b3 = b2 + kstep;
;             if (last && has_next) S.a_ready_inloop(nxt, ui + 1);
;             if constexpr (SP2) {
;             PG8_LDB(B0, 0, 0); PG8_LDB(B1, 0, 1); PG8_SCHED; PG8_LDA(At, 0, 0); PG8_STAGE(PG8_SA(1, 1), a1 + hstep, voffA);
;             PG8_WAIT_V(8); PG8_WAIT_L(0); PG8_BAR; PG8_MMA(0, 0, At, B0); PG8_MMA(0, 1, At, B1); PG8_BAR; PG8_SCHED;
;             PG8_LDA(At, 0, 1); PG8_STAGE(PG8_SB(0, 0), b2, voffB); PG8_STAGE(PG8_SB(0, 1), b2 + hstep, voffB); PG8_STAGE(PG8_SA(0, 0), a2, voffA);
;             PG8_WAIT_V(8); PG8_WAIT_L(0); PG8_BAR; PG8_MMA(1, 0, At, B0); PG8_MMA(1, 1, At, B1); PG8_BAR; PG8_SCHED;
;             PG8_LDB(B0, 1, 0); PG8_LDB(B1, 1, 1); PG8_SCHED; PG8_LDA(At, 1, 0); PG8_STAGE(PG8_SA(0, 1), a2 + hstep, voffA);
;             PG8_WAIT_V(8); PG8_WAIT_L(0); PG8_BAR; PG8_MMA(0, 0, At, B0); PG8_MMA(0, 1, At, B1); PG8_BAR; PG8_SCHED;
;             PG8_LDA(At, 1, 1); PG8_STAGE(PG8_SB(1, 0), b3, voffB); PG8_STAGE(PG8_SB(1, 1), b3 + hstep, voffB); PG8_STAGE(PG8_SA(1, 0), a3, voffA);
;             PG8_WAIT_V(8); PG8_WAIT_L(0); PG8_BAR; PG8_MMA(1, 0, At, B0); PG8_MMA(1, 1, At, B1); PG8_BAR; PG8_SCHED;
.LBB0_211:
	s_mov_b64 s[18:19], s[6:7]
	s_mov_b64 s[20:21], s[14:15]
	s_and_b64 s[6:7], s[16:17], exec
	s_cselect_b32 s7, s37, s19
	s_cselect_b32 s6, s36, s18
	s_cselect_b32 s15, s3, s21
	s_cselect_b32 s14, s2, s20
	s_add_u32 s39, s20, 0x100
	s_addc_u32 s42, s21, 0
	s_mov_b32 s44, -2
	s_add_u32 s20, s18, 0x100
	s_addc_u32 s21, s19, 0
	s_cmp_eq_u32 s44, 40
	s_cselect_b32 s25, s7, s21
	s_cselect_b32 s24, s6, s20
	s_cselect_b32 s23, s15, s42
	s_cselect_b32 s22, s14, s39
	s_add_u32 s98, s22, s46
	s_addc_u32 s99, s23, s47
	s_add_u32 s100, s24, s46
	s_addc_u32 s101, s25, s47
	s_add_i32 m0, s27, 0xc000
	s_nop 0
	global_load_lds_dwordx4 v168, s[18:19]
	s_add_i32 m0, s27, 0xe000
	s_nop 0
	global_load_lds_dwordx4 v170, s[18:19]
	v_add_u32_e32 v142, s90, v188
	v_add_u32_e32 v172, s81, v188
	ds_read_b128 v[130:133], v142
	ds_read_b128 v[134:137], v142 offset:1024
	ds_read_b128 v[138:141], v142 offset:2048
	ds_read_b128 v[142:145], v142 offset:3072
	ds_read_b128 v[146:149], v172
	ds_read_b128 v[150:153], v172 offset:1024
	ds_read_b128 v[154:157], v172 offset:2048
	ds_read_b128 v[172:175], v172 offset:3072
	ds_read_b128 v[176:179], v189
	ds_read_b128 v[180:183], v189 offset:1024
	ds_read_b128 v[184:187], v189 offset:2048
	ds_read_b128 v[190:193], v189 offset:3072
	ds_read_b128 v[194:197], v189 offset:4096
	ds_read_b128 v[198:201], v189 offset:5120
	ds_read_b128 v[216:219], v189 offset:6144
	ds_read_b128 v[220:223], v189 offset:7168
	s_waitcnt vmcnt(8) lgkmcnt(0)
	s_barrier
	s_setprio 1
	v_mfma_f32_16x16x32_bf16 v[126:129], v[130:133], v[176:179], 0
	v_mfma_f32_16x16x32_bf16 v[122:125], v[138:141], v[176:179], 0
	v_mfma_f32_16x16x32_bf16 v[110:113], v[130:133], v[184:187], 0
	v_mfma_f32_16x16x32_bf16 v[106:109], v[138:141], v[184:187], 0
	v_mfma_f32_16x16x32_bf16 v[94:97], v[130:133], v[194:197], 0
	v_mfma_f32_16x16x32_bf16 v[90:93], v[138:141], v[194:197], 0
	v_mfma_f32_16x16x32_bf16 v[78:81], v[130:133], v[216:219], 0
	v_mfma_f32_16x16x32_bf16 v[74:77], v[138:141], v[216:219], 0
	v_mfma_f32_16x16x32_bf16 v[126:129], v[134:137], v[180:183], v[126:129]
	v_mfma_f32_16x16x32_bf16 v[122:125], v[142:145], v[180:183], v[122:125]
	v_mfma_f32_16x16x32_bf16 v[110:113], v[134:137], v[190:193], v[110:113]
	v_mfma_f32_16x16x32_bf16 v[106:109], v[142:145], v[190:193], v[106:109]
	v_mfma_f32_16x16x32_bf16 v[94:97], v[134:137], v[198:201], v[94:97]
	v_mfma_f32_16x16x32_bf16 v[90:93], v[142:145], v[198:201], v[90:93]
	v_mfma_f32_16x16x32_bf16 v[78:81], v[134:137], v[220:223], v[78:81]
	v_mfma_f32_16x16x32_bf16 v[74:77], v[142:145], v[220:223], v[74:77]
	v_mfma_f32_16x16x32_bf16 v[118:121], v[146:149], v[176:179], 0
	v_mfma_f32_16x16x32_bf16 v[114:117], v[154:157], v[176:179], 0
	v_mfma_f32_16x16x32_bf16 v[102:105], v[146:149], v[184:187], 0
	v_mfma_f32_16x16x32_bf16 v[98:101], v[154:157], v[184:187], 0
	v_mfma_f32_16x16x32_bf16 v[86:89], v[146:149], v[194:197], 0
	v_mfma_f32_16x16x32_bf16 v[82:85], v[154:157], v[194:197], 0
	v_mfma_f32_16x16x32_bf16 v[70:73], v[146:149], v[216:219], 0
	v_mfma_f32_16x16x32_bf16 v[66:69], v[154:157], v[216:219], 0
	v_mfma_f32_16x16x32_bf16 v[118:121], v[150:153], v[180:183], v[118:121]
	v_mfma_f32_16x16x32_bf16 v[114:117], v[172:175], v[180:183], v[114:117]
	v_mfma_f32_16x16x32_bf16 v[102:105], v[150:153], v[190:193], v[102:105]
	v_mfma_f32_16x16x32_bf16 v[98:101], v[172:175], v[190:193], v[98:101]
	v_mfma_f32_16x16x32_bf16 v[86:89], v[150:153], v[198:201], v[86:89]
	v_mfma_f32_16x16x32_bf16 v[82:85], v[172:175], v[198:201], v[82:85]
	v_mfma_f32_16x16x32_bf16 v[70:73], v[150:153], v[220:223], v[70:73]
	v_mfma_f32_16x16x32_bf16 v[66:69], v[172:175], v[220:223], v[66:69]
	s_setprio 0
	s_barrier
	s_add_i32 s18, s90, s26
	s_mov_b32 m0, s18
	s_nop 0
	global_load_lds_dwordx4 v160, s[22:23]
	s_add_i32 m0, s18, 0x2000
	s_add_u32 s18, s22, 0xb0000
	s_addc_u32 s19, s23, 0
	s_add_i32 s45, s81, s26
	global_load_lds_dwordx4 v164, s[22:23]
	s_mov_b32 m0, s45
	s_nop 0
	global_load_lds_dwordx4 v160, s[18:19]
	s_add_i32 m0, s45, 0x2000
	s_nop 0
	global_load_lds_dwordx4 v164, s[18:19]
	s_mov_b32 m0, s27
	s_nop 0
	global_load_lds_dwordx4 v158, s[24:25]
	s_mov_b32 m0, s28
	s_nop 0
	global_load_lds_dwordx4 v162, s[24:25]
	ds_read_b128 v[176:179], v189 offset:16384
	ds_read_b128 v[180:183], v189 offset:17408
	ds_read_b128 v[184:187], v189 offset:18432
	ds_read_b128 v[190:193], v189 offset:19456
	ds_read_b128 v[194:197], v189 offset:20480
	ds_read_b128 v[198:201], v189 offset:21504
	ds_read_b128 v[216:219], v189 offset:22528
	ds_read_b128 v[220:223], v189 offset:23552
	s_waitcnt vmcnt(8) lgkmcnt(0)
	s_barrier
	s_setprio 1
	v_mfma_f32_16x16x32_bf16 v[62:65], v[130:133], v[176:179], 0
	v_mfma_f32_16x16x32_bf16 v[58:61], v[138:141], v[176:179], 0
	v_mfma_f32_16x16x32_bf16 v[46:49], v[130:133], v[184:187], 0
	v_mfma_f32_16x16x32_bf16 v[42:45], v[138:141], v[184:187], 0
	v_mfma_f32_16x16x32_bf16 v[30:33], v[130:133], v[194:197], 0
	v_mfma_f32_16x16x32_bf16 v[26:29], v[138:141], v[194:197], 0
	v_mfma_f32_16x16x32_bf16 v[14:17], v[130:133], v[216:219], 0
	v_mfma_f32_16x16x32_bf16 v[10:13], v[138:141], v[216:219], 0
	v_mfma_f32_16x16x32_bf16 v[62:65], v[134:137], v[180:183], v[62:65]
	v_mfma_f32_16x16x32_bf16 v[58:61], v[142:145], v[180:183], v[58:61]
	v_mfma_f32_16x16x32_bf16 v[46:49], v[134:137], v[190:193], v[46:49]
	v_mfma_f32_16x16x32_bf16 v[42:45], v[142:145], v[190:193], v[42:45]
	v_mfma_f32_16x16x32_bf16 v[30:33], v[134:137], v[198:201], v[30:33]
	v_mfma_f32_16x16x32_bf16 v[26:29], v[142:145], v[198:201], v[26:29]
	v_mfma_f32_16x16x32_bf16 v[14:17], v[134:137], v[220:223], v[14:17]
	v_mfma_f32_16x16x32_bf16 v[10:13], v[142:145], v[220:223], v[10:13]
	v_mfma_f32_16x16x32_bf16 v[54:57], v[146:149], v[176:179], 0
	v_mfma_f32_16x16x32_bf16 v[50:53], v[154:157], v[176:179], 0
	v_mfma_f32_16x16x32_bf16 v[38:41], v[146:149], v[184:187], 0
	v_mfma_f32_16x16x32_bf16 v[34:37], v[154:157], v[184:187], 0
	v_mfma_f32_16x16x32_bf16 v[22:25], v[146:149], v[194:197], 0
	v_mfma_f32_16x16x32_bf16 v[18:21], v[154:157], v[194:197], 0
	v_mfma_f32_16x16x32_bf16 v[6:9], v[146:149], v[216:219], 0
	v_mfma_f32_16x16x32_bf16 v[2:5], v[154:157], v[216:219], 0
	v_mfma_f32_16x16x32_bf16 v[54:57], v[150:153], v[180:183], v[54:57]
	v_mfma_f32_16x16x32_bf16 v[50:53], v[172:175], v[180:183], v[50:53]
	v_mfma_f32_16x16x32_bf16 v[38:41], v[150:153], v[190:193], v[38:41]
	v_mfma_f32_16x16x32_bf16 v[34:37], v[172:175], v[190:193], v[34:37]
	v_mfma_f32_16x16x32_bf16 v[22:25], v[150:153], v[198:201], v[22:25]
	v_mfma_f32_16x16x32_bf16 v[18:21], v[172:175], v[198:201], v[18:21]
	v_mfma_f32_16x16x32_bf16 v[6:9], v[150:153], v[220:223], v[6:9]
	v_mfma_f32_16x16x32_bf16 v[2:5], v[172:175], v[220:223], v[2:5]
	s_setprio 0
	s_barrier
; #define PG8_STAGE(bufoff, gbase, voff) do { _Pragma("unroll") for (int _i = 0; _i < 2; ++_i) \
;         __builtin_amdgcn_global_load_lds((const unsigned*)((const char*)(gbase) + (voff)[_i]), (PG8_LAS unsigned*)(lds + (bufoff) + ldsw + _i * 8192), 16, 0, 0); } while (0)
; #define PG8_LDA(dst, b, h) do { _Pragma("unroll") for (int m = 0; m < 4; ++m) _Pragma("unroll") for (int k = 0; k < 2; ++k) dst[m][k] = *(const PG8_LAS bf16x8*)(lds + PG8_SA(b, h) + aoff + m * 2048 + k * 1024); } while (0)
; #define PG8_LDB(dst, b, h) do { _Pragma("unroll") for (int n = 0; n < 2; ++n) _Pragma("unroll") for (int k = 0; k < 2; ++k) dst[n][k] = *(const PG8_LAS bf16x8*)(lds + PG8_SB(b, h) + boff + n * 2048 + k * 1024); } while (0)
; #define PG8_MMA(ai, bj, At, Bt) do { __builtin_amdgcn_s_setprio(1); _Pragma("unroll") for (int m = 0; m < 4; ++m) _Pragma("unroll") for (int n = 0; n < 2; ++n) _Pragma("unroll") for (int k = 0; k < 2; ++k) \
;         acc[ai][bj][m][n] = __builtin_amdgcn_mfma_f32_16x16x32_bf16(Bt[n][k], At[m][k], acc[ai][bj][m][n], 0, 0, 0); __builtin_amdgcn_s_setprio(0); } while (0)
; #define PG8_BAR __builtin_amdgcn_s_barrier()
; template <class Epi, class Sched, bool ALIGN_EPI = false, bool SP2 = false>
; __device__ __forceinline__ void gemm_phase(PG8_LAS unsigned char* lds, const Gemm g, const Sched& S, const Epi& E) {
;     ...
;             if constexpr (SP2) {
;             PG8_LDB(B0, 0, 0); PG8_LDB(B1, 0, 1); PG8_SCHED; PG8_LDA(At, 0, 0); PG8_STAGE(PG8_SA(1, 1), a1 + hstep, voffA);
;             PG8_WAIT_V(8); PG8_WAIT_L(0); PG8_BAR; PG8_MMA(0, 0, At, B0); PG8_MMA(0, 1, At, B1); PG8_BAR; PG8_SCHED;
;             PG8_LDA(At, 0, 1); PG8_STAGE(PG8_SB(0, 0), b2, voffB); PG8_STAGE(PG8_SB(0, 1), b2 + hstep, voffB); PG8_STAGE(PG8_SA(0, 0), a2, voffA);
;             PG8_WAIT_V(8); PG8_WAIT_L(0); PG8_BAR; PG8_MMA(1, 0, At, B0); PG8_MMA(1, 1, At, B1); PG8_BAR; PG8_SCHED;
;             PG8_LDB(B0, 1, 0); PG8_LDB(B1, 1, 1); PG8_SCHED; PG8_LDA(At, 1, 0); PG8_STAGE(PG8_SA(0, 1), a2 + hstep, voffA);
;             PG8_WAIT_V(8); PG8_WAIT_L(0); PG8_BAR; PG8_MMA(0, 0, At, B0); PG8_MMA(0, 1, At, B1); PG8_BAR; PG8_SCHED;
;             PG8_LDA(At, 1, 1); PG8_STAGE(PG8_SB(1, 0), b3, voffB); PG8_STAGE(PG8_SB(1, 1), b3 + hstep, voffB); PG8_STAGE(PG8_SA(1, 0), a3, voffA);
;             PG8_WAIT_V(8); PG8_WAIT_L(0); PG8_BAR; PG8_MMA(1, 0, At, B0); PG8_MMA(1, 1, At, B1); PG8_BAR; PG8_SCHED;
	s_add_u32 s18, s24, 0xb0000
	s_addc_u32 s19, s25, 0
	s_mov_b32 m0, s29
	s_nop 0
	global_load_lds_dwordx4 v158, s[18:19]
	s_mov_b32 m0, s30
	s_nop 0
	global_load_lds_dwordx4 v162, s[18:19]
	v_add_u32_e32 v142, s82, v188
	v_add_u32_e32 v172, s83, v188
	ds_read_b128 v[130:133], v142
	ds_read_b128 v[134:137], v142 offset:1024
	ds_read_b128 v[138:141], v142 offset:2048
	ds_read_b128 v[142:145], v142 offset:3072
	ds_read_b128 v[146:149], v172
	ds_read_b128 v[150:153], v172 offset:1024
	ds_read_b128 v[154:157], v172 offset:2048
	ds_read_b128 v[172:175], v172 offset:3072
	ds_read_b128 v[176:179], v189 offset:32768
	ds_read_b128 v[180:183], v189 offset:33792
	ds_read_b128 v[184:187], v189 offset:34816
	ds_read_b128 v[190:193], v189 offset:35840
	ds_read_b128 v[194:197], v189 offset:36864
	ds_read_b128 v[198:201], v189 offset:37888
	ds_read_b128 v[216:219], v189 offset:38912
	ds_read_b128 v[220:223], v189 offset:39936
	s_waitcnt vmcnt(8) lgkmcnt(0)
	s_barrier
	s_setprio 1
	v_mfma_f32_16x16x32_bf16 v[126:129], v[130:133], v[176:179], v[126:129]
	v_mfma_f32_16x16x32_bf16 v[122:125], v[138:141], v[176:179], v[122:125]
	v_mfma_f32_16x16x32_bf16 v[110:113], v[130:133], v[184:187], v[110:113]
	v_mfma_f32_16x16x32_bf16 v[106:109], v[138:141], v[184:187], v[106:109]
	v_mfma_f32_16x16x32_bf16 v[94:97], v[130:133], v[194:197], v[94:97]
	v_mfma_f32_16x16x32_bf16 v[90:93], v[138:141], v[194:197], v[90:93]
	v_mfma_f32_16x16x32_bf16 v[78:81], v[130:133], v[216:219], v[78:81]
	v_mfma_f32_16x16x32_bf16 v[74:77], v[138:141], v[216:219], v[74:77]
	v_mfma_f32_16x16x32_bf16 v[126:129], v[134:137], v[180:183], v[126:129]
	v_mfma_f32_16x16x32_bf16 v[122:125], v[142:145], v[180:183], v[122:125]
	v_mfma_f32_16x16x32_bf16 v[110:113], v[134:137], v[190:193], v[110:113]
	v_mfma_f32_16x16x32_bf16 v[106:109], v[142:145], v[190:193], v[106:109]
	v_mfma_f32_16x16x32_bf16 v[94:97], v[134:137], v[198:201], v[94:97]
	v_mfma_f32_16x16x32_bf16 v[90:93], v[142:145], v[198:201], v[90:93]
	v_mfma_f32_16x16x32_bf16 v[78:81], v[134:137], v[220:223], v[78:81]
	v_mfma_f32_16x16x32_bf16 v[74:77], v[142:145], v[220:223], v[74:77]
	v_mfma_f32_16x16x32_bf16 v[118:121], v[146:149], v[176:179], v[118:121]
	v_mfma_f32_16x16x32_bf16 v[114:117], v[154:157], v[176:179], v[114:117]
	v_mfma_f32_16x16x32_bf16 v[102:105], v[146:149], v[184:187], v[102:105]
	v_mfma_f32_16x16x32_bf16 v[98:101], v[154:157], v[184:187], v[98:101]
	v_mfma_f32_16x16x32_bf16 v[86:89], v[146:149], v[194:197], v[86:89]
	v_mfma_f32_16x16x32_bf16 v[82:85], v[154:157], v[194:197], v[82:85]
	v_mfma_f32_16x16x32_bf16 v[70:73], v[146:149], v[216:219], v[70:73]
	v_mfma_f32_16x16x32_bf16 v[66:69], v[154:157], v[216:219], v[66:69]
	v_mfma_f32_16x16x32_bf16 v[118:121], v[150:153], v[180:183], v[118:121]
	v_mfma_f32_16x16x32_bf16 v[114:117], v[172:175], v[180:183], v[114:117]
	v_mfma_f32_16x16x32_bf16 v[102:105], v[150:153], v[190:193], v[102:105]
	v_mfma_f32_16x16x32_bf16 v[98:101], v[172:175], v[190:193], v[98:101]
	v_mfma_f32_16x16x32_bf16 v[86:89], v[150:153], v[198:201], v[86:89]
	v_mfma_f32_16x16x32_bf16 v[82:85], v[172:175], v[198:201], v[82:85]
	v_mfma_f32_16x16x32_bf16 v[70:73], v[150:153], v[220:223], v[70:73]
	v_mfma_f32_16x16x32_bf16 v[66:69], v[172:175], v[220:223], v[66:69]
	s_setprio 0
	s_barrier
	s_add_i32 s18, s82, s26
	s_mov_b32 m0, s18
	s_nop 0
	global_load_lds_dwordx4 v160, s[98:99]
	s_add_i32 m0, s18, 0x2000
	s_add_u32 s18, s22, 0xb0080
	s_addc_u32 s19, s23, 0
	s_add_i32 s22, s83, s26
	global_load_lds_dwordx4 v164, s[98:99]
	s_mov_b32 m0, s22
	s_nop 0
	global_load_lds_dwordx4 v160, s[18:19]
	s_add_i32 m0, s22, 0x2000
	s_nop 0
	global_load_lds_dwordx4 v164, s[18:19]
	s_mov_b32 m0, s31
	s_nop 0
	global_load_lds_dwordx4 v158, s[100:101]
	s_mov_b32 m0, s34
	s_nop 0
	global_load_lds_dwordx4 v162, s[100:101]
	ds_read_b128 v[176:179], v189 offset:49152
	ds_read_b128 v[180:183], v189 offset:50176
	ds_read_b128 v[184:187], v189 offset:51200
	ds_read_b128 v[190:193], v189 offset:52224
	ds_read_b128 v[194:197], v189 offset:53248
	ds_read_b128 v[198:201], v189 offset:54272
	ds_read_b128 v[216:219], v189 offset:55296
	ds_read_b128 v[220:223], v189 offset:56320
	s_waitcnt vmcnt(8) lgkmcnt(0)
	s_barrier
	s_setprio 1
	v_mfma_f32_16x16x32_bf16 v[62:65], v[130:133], v[176:179], v[62:65]
	v_mfma_f32_16x16x32_bf16 v[58:61], v[138:141], v[176:179], v[58:61]
	v_mfma_f32_16x16x32_bf16 v[46:49], v[130:133], v[184:187], v[46:49]
	v_mfma_f32_16x16x32_bf16 v[42:45], v[138:141], v[184:187], v[42:45]
	v_mfma_f32_16x16x32_bf16 v[30:33], v[130:133], v[194:197], v[30:33]
	v_mfma_f32_16x16x32_bf16 v[26:29], v[138:141], v[194:197], v[26:29]
	v_mfma_f32_16x16x32_bf16 v[14:17], v[130:133], v[216:219], v[14:17]
	v_mfma_f32_16x16x32_bf16 v[10:13], v[138:141], v[216:219], v[10:13]
	v_mfma_f32_16x16x32_bf16 v[62:65], v[134:137], v[180:183], v[62:65]
	v_mfma_f32_16x16x32_bf16 v[58:61], v[142:145], v[180:183], v[58:61]
	v_mfma_f32_16x16x32_bf16 v[46:49], v[134:137], v[190:193], v[46:49]
	v_mfma_f32_16x16x32_bf16 v[42:45], v[142:145], v[190:193], v[42:45]
	v_mfma_f32_16x16x32_bf16 v[30:33], v[134:137], v[198:201], v[30:33]
	v_mfma_f32_16x16x32_bf16 v[26:29], v[142:145], v[198:201], v[26:29]
	v_mfma_f32_16x16x32_bf16 v[14:17], v[134:137], v[220:223], v[14:17]
	v_mfma_f32_16x16x32_bf16 v[10:13], v[142:145], v[220:223], v[10:13]
	v_mfma_f32_16x16x32_bf16 v[54:57], v[146:149], v[176:179], v[54:57]
	v_mfma_f32_16x16x32_bf16 v[50:53], v[154:157], v[176:179], v[50:53]
	v_mfma_f32_16x16x32_bf16 v[38:41], v[146:149], v[184:187], v[38:41]
	v_mfma_f32_16x16x32_bf16 v[34:37], v[154:157], v[184:187], v[34:37]
	v_mfma_f32_16x16x32_bf16 v[22:25], v[146:149], v[194:197], v[22:25]
	v_mfma_f32_16x16x32_bf16 v[18:21], v[154:157], v[194:197], v[18:21]
	v_mfma_f32_16x16x32_bf16 v[6:9], v[146:149], v[216:219], v[6:9]
	v_mfma_f32_16x16x32_bf16 v[2:5], v[154:157], v[216:219], v[2:5]
	v_mfma_f32_16x16x32_bf16 v[54:57], v[150:153], v[180:183], v[54:57]
	v_mfma_f32_16x16x32_bf16 v[50:53], v[172:175], v[180:183], v[50:53]
	v_mfma_f32_16x16x32_bf16 v[38:41], v[150:153], v[190:193], v[38:41]
	v_mfma_f32_16x16x32_bf16 v[34:37], v[172:175], v[190:193], v[34:37]
	v_mfma_f32_16x16x32_bf16 v[22:25], v[150:153], v[198:201], v[22:25]
	v_mfma_f32_16x16x32_bf16 v[18:21], v[172:175], v[198:201], v[18:21]
	v_mfma_f32_16x16x32_bf16 v[6:9], v[150:153], v[220:223], v[6:9]
	v_mfma_f32_16x16x32_bf16 v[2:5], v[172:175], v[220:223], v[2:5]
	s_setprio 0
	s_barrier
	s_add_i32 s44, s44, 2
	s_add_u32 s39, s39, 0x100
	s_addc_u32 s42, s42, 0
	s_mov_b64 s[18:19], s[20:21]
; #define PG8_STAGE(bufoff, gbase, voff) do { _Pragma("unroll") for (int _i = 0; _i < 2; ++_i) \
;         __builtin_amdgcn_global_load_lds((const unsigned*)((const char*)(gbase) + (voff)[_i]), (PG8_LAS unsigned*)(lds + (bufoff) + ldsw + _i * 8192), 16, 0, 0); } while (0)
; #define PG8_LDA(dst, b, h) do { _Pragma("unroll") for (int m = 0; m < 4; ++m) _Pragma("unroll") for (int k = 0; k < 2; ++k) dst[m][k] = *(const PG8_LAS bf16x8*)(lds + PG8_SA(b, h) + aoff + m * 2048 + k * 1024); } while (0)
; #define PG8_LDB(dst, b, h) do { _Pragma("unroll") for (int n = 0; n < 2; ++n) _Pragma("unroll") for (int k = 0; k < 2; ++k) dst[n][k] = *(const PG8_LAS bf16x8*)(lds + PG8_SB(b, h) + boff + n * 2048 + k * 1024); } while (0)
; #define PG8_MMA(ai, bj, At, Bt) do { __builtin_amdgcn_s_setprio(1); _Pragma("unroll") for (int m = 0; m < 4; ++m) _Pragma("unroll") for (int n = 0; n < 2; ++n) _Pragma("unroll") for (int k = 0; k < 2; ++k) \
;         acc[ai][bj][m][n] = __builtin_amdgcn_mfma_f32_16x16x32_bf16(Bt[n][k], At[m][k], acc[ai][bj][m][n], 0, 0, 0); __builtin_amdgcn_s_setprio(0); } while (0)
; #define PG8_BAR __builtin_amdgcn_s_barrier()
; template <class Epi, class Sched, bool ALIGN_EPI = false, bool SP2 = false>
; __device__ __forceinline__ void gemm_phase(PG8_LAS unsigned char* lds, const Gemm g, const Sched& S, const Epi& E) {
;     ...
;             if constexpr (SP2) {
;             PG8_LDB(B0, 0, 0); PG8_LDB(B1, 0, 1); PG8_SCHED; PG8_LDA(At, 0, 0); PG8_STAGE(PG8_SA(1, 1), a1 + hstep, voffA);
;             PG8_WAIT_V(8); PG8_WAIT_L(0); PG8_BAR; PG8_MMA(0, 0, At, B0); PG8_MMA(0, 1, At, B1); PG8_BAR; PG8_SCHED;
;             PG8_LDA(At, 0, 1); PG8_STAGE(PG8_SB(0, 0), b2, voffB); PG8_STAGE(PG8_SB(0, 1), b2 + hstep, voffB); PG8_STAGE(PG8_SA(0, 0), a2, voffA);
;             PG8_WAIT_V(8); PG8_WAIT_L(0); PG8_BAR; PG8_MMA(1, 0, At, B0); PG8_MMA(1, 1, At, B1); PG8_BAR; PG8_SCHED;
;             PG8_LDB(B0, 1, 0); PG8_LDB(B1, 1, 1); PG8_SCHED; PG8_LDA(At, 1, 0); PG8_STAGE(PG8_SA(0, 1), a2 + hstep, voffA);
;             PG8_WAIT_V(8); PG8_WAIT_L(0); PG8_BAR; PG8_MMA(0, 0, At, B0); PG8_MMA(0, 1, At, B1); PG8_BAR; PG8_SCHED;
;             PG8_LDA(At, 1, 1); PG8_STAGE(PG8_SB(1, 0), b3, voffB); PG8_STAGE(PG8_SB(1, 1), b3 + hstep, voffB); PG8_STAGE(PG8_SA(1, 0), a3, voffA);
;             PG8_WAIT_V(8); PG8_WAIT_L(0); PG8_BAR; PG8_MMA(1, 0, At, B0); PG8_MMA(1, 1, At, B1); PG8_BAR; PG8_SCHED;
.LBB0_212:
	s_add_u32 s20, s18, 0x100
	s_addc_u32 s21, s19, 0
	s_cmp_eq_u32 s44, 40
	s_cselect_b32 s25, s7, s21
	s_cselect_b32 s24, s6, s20
	s_cselect_b32 s23, s15, s42
	s_cselect_b32 s22, s14, s39
	s_add_u32 s98, s22, s46
	s_addc_u32 s99, s23, s47
	s_add_u32 s100, s24, s46
	s_addc_u32 s101, s25, s47
	s_add_i32 m0, s27, 0xc000
	s_nop 0
	global_load_lds_dwordx4 v168, s[18:19]
	s_add_i32 m0, s27, 0xe000
	s_nop 0
	global_load_lds_dwordx4 v170, s[18:19]
	v_add_u32_e32 v142, s90, v188
	v_add_u32_e32 v172, s81, v188
	ds_read_b128 v[130:133], v142
	ds_read_b128 v[134:137], v142 offset:1024
	ds_read_b128 v[138:141], v142 offset:2048
	ds_read_b128 v[142:145], v142 offset:3072
	ds_read_b128 v[146:149], v172
	ds_read_b128 v[150:153], v172 offset:1024
	ds_read_b128 v[154:157], v172 offset:2048
	ds_read_b128 v[172:175], v172 offset:3072
	ds_read_b128 v[176:179], v189
	ds_read_b128 v[180:183], v189 offset:1024
	ds_read_b128 v[184:187], v189 offset:2048
	ds_read_b128 v[190:193], v189 offset:3072
	ds_read_b128 v[194:197], v189 offset:4096
	ds_read_b128 v[198:201], v189 offset:5120
	ds_read_b128 v[216:219], v189 offset:6144
	ds_read_b128 v[220:223], v189 offset:7168
	s_waitcnt vmcnt(8) lgkmcnt(0)
	s_barrier
	s_setprio 1
	v_mfma_f32_16x16x32_bf16 v[126:129], v[130:133], v[176:179], v[126:129]
	v_mfma_f32_16x16x32_bf16 v[122:125], v[138:141], v[176:179], v[122:125]
	v_mfma_f32_16x16x32_bf16 v[110:113], v[130:133], v[184:187], v[110:113]
	v_mfma_f32_16x16x32_bf16 v[106:109], v[138:141], v[184:187], v[106:109]
	v_mfma_f32_16x16x32_bf16 v[94:97], v[130:133], v[194:197], v[94:97]
	v_mfma_f32_16x16x32_bf16 v[90:93], v[138:141], v[194:197], v[90:93]
	v_mfma_f32_16x16x32_bf16 v[78:81], v[130:133], v[216:219], v[78:81]
	v_mfma_f32_16x16x32_bf16 v[74:77], v[138:141], v[216:219], v[74:77]
	v_mfma_f32_16x16x32_bf16 v[126:129], v[134:137], v[180:183], v[126:129]
	v_mfma_f32_16x16x32_bf16 v[122:125], v[142:145], v[180:183], v[122:125]
	v_mfma_f32_16x16x32_bf16 v[110:113], v[134:137], v[190:193], v[110:113]
	v_mfma_f32_16x16x32_bf16 v[106:109], v[142:145], v[190:193], v[106:109]
	v_mfma_f32_16x16x32_bf16 v[94:97], v[134:137], v[198:201], v[94:97]
	v_mfma_f32_16x16x32_bf16 v[90:93], v[142:145], v[198:201], v[90:93]
	v_mfma_f32_16x16x32_bf16 v[78:81], v[134:137], v[220:223], v[78:81]
	v_mfma_f32_16x16x32_bf16 v[74:77], v[142:145], v[220:223], v[74:77]
	v_mfma_f32_16x16x32_bf16 v[118:121], v[146:149], v[176:179], v[118:121]
	v_mfma_f32_16x16x32_bf16 v[114:117], v[154:157], v[176:179], v[114:117]
	v_mfma_f32_16x16x32_bf16 v[102:105], v[146:149], v[184:187], v[102:105]
	v_mfma_f32_16x16x32_bf16 v[98:101], v[154:157], v[184:187], v[98:101]
	v_mfma_f32_16x16x32_bf16 v[86:89], v[146:149], v[194:197], v[86:89]
	v_mfma_f32_16x16x32_bf16 v[82:85], v[154:157], v[194:197], v[82:85]
	v_mfma_f32_16x16x32_bf16 v[70:73], v[146:149], v[216:219], v[70:73]
	v_mfma_f32_16x16x32_bf16 v[66:69], v[154:157], v[216:219], v[66:69]
	v_mfma_f32_16x16x32_bf16 v[118:121], v[150:153], v[180:183], v[118:121]
	v_mfma_f32_16x16x32_bf16 v[114:117], v[172:175], v[180:183], v[114:117]
	v_mfma_f32_16x16x32_bf16 v[102:105], v[150:153], v[190:193], v[102:105]
	v_mfma_f32_16x16x32_bf16 v[98:101], v[172:175], v[190:193], v[98:101]
	v_mfma_f32_16x16x32_bf16 v[86:89], v[150:153], v[198:201], v[86:89]
	v_mfma_f32_16x16x32_bf16 v[82:85], v[172:175], v[198:201], v[82:85]
	v_mfma_f32_16x16x32_bf16 v[70:73], v[150:153], v[220:223], v[70:73]
	v_mfma_f32_16x16x32_bf16 v[66:69], v[172:175], v[220:223], v[66:69]
	s_setprio 0
	s_barrier
	s_add_i32 s18, s90, s26
	s_mov_b32 m0, s18
	s_nop 0
	global_load_lds_dwordx4 v160, s[22:23]
	s_add_i32 m0, s18, 0x2000
	s_add_u32 s18, s22, 0xb0000
	s_addc_u32 s19, s23, 0
	s_add_i32 s45, s81, s26
	global_load_lds_dwordx4 v164, s[22:23]
	s_mov_b32 m0, s45
	s_nop 0
	global_load_lds_dwordx4 v160, s[18:19]
	s_add_i32 m0, s45, 0x2000
	s_nop 0
	global_load_lds_dwordx4 v164, s[18:19]
	s_mov_b32 m0, s27
	s_nop 0
	global_load_lds_dwordx4 v158, s[24:25]
	s_mov_b32 m0, s28
	s_nop 0
	global_load_lds_dwordx4 v162, s[24:25]
	ds_read_b128 v[176:179], v189 offset:16384
	ds_read_b128 v[180:183], v189 offset:17408
	ds_read_b128 v[184:187], v189 offset:18432
	ds_read_b128 v[190:193], v189 offset:19456
	ds_read_b128 v[194:197], v189 offset:20480
	ds_read_b128 v[198:201], v189 offset:21504
	ds_read_b128 v[216:219], v189 offset:22528
	ds_read_b128 v[220:223], v189 offset:23552
	s_waitcnt vmcnt(8) lgkmcnt(0)
	s_barrier
	s_setprio 1
	v_mfma_f32_16x16x32_bf16 v[62:65], v[130:133], v[176:179], v[62:65]
	v_mfma_f32_16x16x32_bf16 v[58:61], v[138:141], v[176:179], v[58:61]
	v_mfma_f32_16x16x32_bf16 v[46:49], v[130:133], v[184:187], v[46:49]
	v_mfma_f32_16x16x32_bf16 v[42:45], v[138:141], v[184:187], v[42:45]
	v_mfma_f32_16x16x32_bf16 v[30:33], v[130:133], v[194:197], v[30:33]
	v_mfma_f32_16x16x32_bf16 v[26:29], v[138:141], v[194:197], v[26:29]
	v_mfma_f32_16x16x32_bf16 v[14:17], v[130:133], v[216:219], v[14:17]
	v_mfma_f32_16x16x32_bf16 v[10:13], v[138:141], v[216:219], v[10:13]
	v_mfma_f32_16x16x32_bf16 v[62:65], v[134:137], v[180:183], v[62:65]
	v_mfma_f32_16x16x32_bf16 v[58:61], v[142:145], v[180:183], v[58:61]
	v_mfma_f32_16x16x32_bf16 v[46:49], v[134:137], v[190:193], v[46:49]
	v_mfma_f32_16x16x32_bf16 v[42:45], v[142:145], v[190:193], v[42:45]
	v_mfma_f32_16x16x32_bf16 v[30:33], v[134:137], v[198:201], v[30:33]
	v_mfma_f32_16x16x32_bf16 v[26:29], v[142:145], v[198:201], v[26:29]
	v_mfma_f32_16x16x32_bf16 v[14:17], v[134:137], v[220:223], v[14:17]
	v_mfma_f32_16x16x32_bf16 v[10:13], v[142:145], v[220:223], v[10:13]
	v_mfma_f32_16x16x32_bf16 v[54:57], v[146:149], v[176:179], v[54:57]
	v_mfma_f32_16x16x32_bf16 v[50:53], v[154:157], v[176:179], v[50:53]
	v_mfma_f32_16x16x32_bf16 v[38:41], v[146:149], v[184:187], v[38:41]
	v_mfma_f32_16x16x32_bf16 v[34:37], v[154:157], v[184:187], v[34:37]
	v_mfma_f32_16x16x32_bf16 v[22:25], v[146:149], v[194:197], v[22:25]
	v_mfma_f32_16x16x32_bf16 v[18:21], v[154:157], v[194:197], v[18:21]
	v_mfma_f32_16x16x32_bf16 v[6:9], v[146:149], v[216:219], v[6:9]
	v_mfma_f32_16x16x32_bf16 v[2:5], v[154:157], v[216:219], v[2:5]
	v_mfma_f32_16x16x32_bf16 v[54:57], v[150:153], v[180:183], v[54:57]
	v_mfma_f32_16x16x32_bf16 v[50:53], v[172:175], v[180:183], v[50:53]
	v_mfma_f32_16x16x32_bf16 v[38:41], v[150:153], v[190:193], v[38:41]
	v_mfma_f32_16x16x32_bf16 v[34:37], v[172:175], v[190:193], v[34:37]
	v_mfma_f32_16x16x32_bf16 v[22:25], v[150:153], v[198:201], v[22:25]
	v_mfma_f32_16x16x32_bf16 v[18:21], v[172:175], v[198:201], v[18:21]
	v_mfma_f32_16x16x32_bf16 v[6:9], v[150:153], v[220:223], v[6:9]
	v_mfma_f32_16x16x32_bf16 v[2:5], v[172:175], v[220:223], v[2:5]
	s_setprio 0
	s_barrier
; #define PG8_STAGE(bufoff, gbase, voff) do { _Pragma("unroll") for (int _i = 0; _i < 2; ++_i) \
;         __builtin_amdgcn_global_load_lds((const unsigned*)((const char*)(gbase) + (voff)[_i]), (PG8_LAS unsigned*)(lds + (bufoff) + ldsw + _i * 8192), 16, 0, 0); } while (0)
; #define PG8_LDA(dst, b, h) do { _Pragma("unroll") for (int m = 0; m < 4; ++m) _Pragma("unroll") for (int k = 0; k < 2; ++k) dst[m][k] = *(const PG8_LAS bf16x8*)(lds + PG8_SA(b, h) + aoff + m * 2048 + k * 1024); } while (0)
; #define PG8_LDB(dst, b, h) do { _Pragma("unroll") for (int n = 0; n < 2; ++n) _Pragma("unroll") for (int k = 0; k < 2; ++k) dst[n][k] = *(const PG8_LAS bf16x8*)(lds + PG8_SB(b, h) + boff + n * 2048 + k * 1024); } while (0)
; #define PG8_MMA(ai, bj, At, Bt) do { __builtin_amdgcn_s_setprio(1); _Pragma("unroll") for (int m = 0; m < 4; ++m) _Pragma("unroll") for (int n = 0; n < 2; ++n) _Pragma("unroll") for (int k = 0; k < 2; ++k) \
;         acc[ai][bj][m][n] = __builtin_amdgcn_mfma_f32_16x16x32_bf16(Bt[n][k], At[m][k], acc[ai][bj][m][n], 0, 0, 0); __builtin_amdgcn_s_setprio(0); } while (0)
; #define PG8_BAR __builtin_amdgcn_s_barrier()
; template <class Epi, class Sched, bool ALIGN_EPI = false, bool SP2 = false>
; __device__ __forceinline__ void gemm_phase(PG8_LAS unsigned char* lds, const Gemm g, const Sched& S, const Epi& E) {
;     ...
;             if constexpr (SP2) {
;             PG8_LDB(B0, 0, 0); PG8_LDB(B1, 0, 1); PG8_SCHED; PG8_LDA(At, 0, 0); PG8_STAGE(PG8_SA(1, 1), a1 + hstep, voffA);
;             PG8_WAIT_V(8); PG8_WAIT_L(0); PG8_BAR; PG8_MMA(0, 0, At, B0); PG8_MMA(0, 1, At, B1); PG8_BAR; PG8_SCHED;
;             PG8_LDA(At, 0, 1); PG8_STAGE(PG8_SB(0, 0), b2, voffB); PG8_STAGE(PG8_SB(0, 1), b2 + hstep, voffB); PG8_STAGE(PG8_SA(0, 0), a2, voffA);
;             PG8_WAIT_V(8); PG8_WAIT_L(0); PG8_BAR; PG8_MMA(1, 0, At, B0); PG8_MMA(1, 1, At, B1); PG8_BAR; PG8_SCHED;
;             PG8_LDB(B0, 1, 0); PG8_LDB(B1, 1, 1); PG8_SCHED; PG8_LDA(At, 1, 0); PG8_STAGE(PG8_SA(0, 1), a2 + hstep, voffA);
;             PG8_WAIT_V(8); PG8_WAIT_L(0); PG8_BAR; PG8_MMA(0, 0, At, B0); PG8_MMA(0, 1, At, B1); PG8_BAR; PG8_SCHED;
;             PG8_LDA(At, 1, 1); PG8_STAGE(PG8_SB(1, 0), b3, voffB); PG8_STAGE(PG8_SB(1, 1), b3 + hstep, voffB); PG8_STAGE(PG8_SA(1, 0), a3, voffA);
;             PG8_WAIT_V(8); PG8_WAIT_L(0); PG8_BAR; PG8_MMA(1, 0, At, B0); PG8_MMA(1, 1, At, B1); PG8_BAR; PG8_SCHED;
	s_add_u32 s18, s24, 0xb0000
	s_addc_u32 s19, s25, 0
	s_mov_b32 m0, s29
	s_nop 0
	global_load_lds_dwordx4 v158, s[18:19]
	s_mov_b32 m0, s30
	s_nop 0
	global_load_lds_dwordx4 v162, s[18:19]
	v_add_u32_e32 v142, s82, v188
	v_add_u32_e32 v172, s83, v188
	ds_read_b128 v[130:133], v142
	ds_read_b128 v[134:137], v142 offset:1024
	ds_read_b128 v[138:141], v142 offset:2048
	ds_read_b128 v[142:145], v142 offset:3072
	ds_read_b128 v[146:149], v172
	ds_read_b128 v[150:153], v172 offset:1024
	ds_read_b128 v[154:157], v172 offset:2048
	ds_read_b128 v[172:175], v172 offset:3072
	ds_read_b128 v[176:179], v189 offset:32768
	ds_read_b128 v[180:183], v189 offset:33792
	ds_read_b128 v[184:187], v189 offset:34816
	ds_read_b128 v[190:193], v189 offset:35840
	ds_read_b128 v[194:197], v189 offset:36864
	ds_read_b128 v[198:201], v189 offset:37888
	ds_read_b128 v[216:219], v189 offset:38912
	ds_read_b128 v[220:223], v189 offset:39936
	s_waitcnt vmcnt(8) lgkmcnt(0)
	s_barrier
	s_setprio 1
	v_mfma_f32_16x16x32_bf16 v[126:129], v[130:133], v[176:179], v[126:129]
	v_mfma_f32_16x16x32_bf16 v[122:125], v[138:141], v[176:179], v[122:125]
	v_mfma_f32_16x16x32_bf16 v[110:113], v[130:133], v[184:187], v[110:113]
	v_mfma_f32_16x16x32_bf16 v[106:109], v[138:141], v[184:187], v[106:109]
	v_mfma_f32_16x16x32_bf16 v[94:97], v[130:133], v[194:197], v[94:97]
	v_mfma_f32_16x16x32_bf16 v[90:93], v[138:141], v[194:197], v[90:93]
	v_mfma_f32_16x16x32_bf16 v[78:81], v[130:133], v[216:219], v[78:81]
	v_mfma_f32_16x16x32_bf16 v[74:77], v[138:141], v[216:219], v[74:77]
	v_mfma_f32_16x16x32_bf16 v[126:129], v[134:137], v[180:183], v[126:129]
	v_mfma_f32_16x16x32_bf16 v[122:125], v[142:145], v[180:183], v[122:125]
	v_mfma_f32_16x16x32_bf16 v[110:113], v[134:137], v[190:193], v[110:113]
	v_mfma_f32_16x16x32_bf16 v[106:109], v[142:145], v[190:193], v[106:109]
	v_mfma_f32_16x16x32_bf16 v[94:97], v[134:137], v[198:201], v[94:97]
	v_mfma_f32_16x16x32_bf16 v[90:93], v[142:145], v[198:201], v[90:93]
	v_mfma_f32_16x16x32_bf16 v[78:81], v[134:137], v[220:223], v[78:81]
	v_mfma_f32_16x16x32_bf16 v[74:77], v[142:145], v[220:223], v[74:77]
	v_mfma_f32_16x16x32_bf16 v[118:121], v[146:149], v[176:179], v[118:121]
	v_mfma_f32_16x16x32_bf16 v[114:117], v[154:157], v[176:179], v[114:117]
	v_mfma_f32_16x16x32_bf16 v[102:105], v[146:149], v[184:187], v[102:105]
	v_mfma_f32_16x16x32_bf16 v[98:101], v[154:157], v[184:187], v[98:101]
	v_mfma_f32_16x16x32_bf16 v[86:89], v[146:149], v[194:197], v[86:89]
	v_mfma_f32_16x16x32_bf16 v[82:85], v[154:157], v[194:197], v[82:85]
	v_mfma_f32_16x16x32_bf16 v[70:73], v[146:149], v[216:219], v[70:73]
	v_mfma_f32_16x16x32_bf16 v[66:69], v[154:157], v[216:219], v[66:69]
	v_mfma_f32_16x16x32_bf16 v[118:121], v[150:153], v[180:183], v[118:121]
	v_mfma_f32_16x16x32_bf16 v[114:117], v[172:175], v[180:183], v[114:117]
	v_mfma_f32_16x16x32_bf16 v[102:105], v[150:153], v[190:193], v[102:105]
	v_mfma_f32_16x16x32_bf16 v[98:101], v[172:175], v[190:193], v[98:101]
	v_mfma_f32_16x16x32_bf16 v[86:89], v[150:153], v[198:201], v[86:89]
	v_mfma_f32_16x16x32_bf16 v[82:85], v[172:175], v[198:201], v[82:85]
	v_mfma_f32_16x16x32_bf16 v[70:73], v[150:153], v[220:223], v[70:73]
	v_mfma_f32_16x16x32_bf16 v[66:69], v[172:175], v[220:223], v[66:69]
	s_setprio 0
	s_barrier
	s_add_i32 s18, s82, s26
	s_mov_b32 m0, s18
	s_nop 0
	global_load_lds_dwordx4 v160, s[98:99]
	s_add_i32 m0, s18, 0x2000
	s_add_u32 s18, s22, 0xb0080
	s_addc_u32 s19, s23, 0
	s_add_i32 s22, s83, s26
	global_load_lds_dwordx4 v164, s[98:99]
	s_mov_b32 m0, s22
	s_nop 0
	global_load_lds_dwordx4 v160, s[18:19]
	s_add_i32 m0, s22, 0x2000
	s_nop 0
	global_load_lds_dwordx4 v164, s[18:19]
	s_mov_b32 m0, s31
	s_nop 0
	global_load_lds_dwordx4 v158, s[100:101]
	s_mov_b32 m0, s34
	s_nop 0
	global_load_lds_dwordx4 v162, s[100:101]
	ds_read_b128 v[176:179], v189 offset:49152
	ds_read_b128 v[180:183], v189 offset:50176
	ds_read_b128 v[184:187], v189 offset:51200
	ds_read_b128 v[190:193], v189 offset:52224
	ds_read_b128 v[194:197], v189 offset:53248
	ds_read_b128 v[198:201], v189 offset:54272
	ds_read_b128 v[216:219], v189 offset:55296
	ds_read_b128 v[220:223], v189 offset:56320
	s_waitcnt vmcnt(8) lgkmcnt(0)
	s_barrier
	s_setprio 1
	v_mfma_f32_16x16x32_bf16 v[62:65], v[130:133], v[176:179], v[62:65]
	v_mfma_f32_16x16x32_bf16 v[58:61], v[138:141], v[176:179], v[58:61]
	v_mfma_f32_16x16x32_bf16 v[46:49], v[130:133], v[184:187], v[46:49]
	v_mfma_f32_16x16x32_bf16 v[42:45], v[138:141], v[184:187], v[42:45]
	v_mfma_f32_16x16x32_bf16 v[30:33], v[130:133], v[194:197], v[30:33]
	v_mfma_f32_16x16x32_bf16 v[26:29], v[138:141], v[194:197], v[26:29]
	v_mfma_f32_16x16x32_bf16 v[14:17], v[130:133], v[216:219], v[14:17]
	v_mfma_f32_16x16x32_bf16 v[10:13], v[138:141], v[216:219], v[10:13]
	v_mfma_f32_16x16x32_bf16 v[62:65], v[134:137], v[180:183], v[62:65]
	v_mfma_f32_16x16x32_bf16 v[58:61], v[142:145], v[180:183], v[58:61]
	v_mfma_f32_16x16x32_bf16 v[46:49], v[134:137], v[190:193], v[46:49]
	v_mfma_f32_16x16x32_bf16 v[42:45], v[142:145], v[190:193], v[42:45]
	v_mfma_f32_16x16x32_bf16 v[30:33], v[134:137], v[198:201], v[30:33]
	v_mfma_f32_16x16x32_bf16 v[26:29], v[142:145], v[198:201], v[26:29]
	v_mfma_f32_16x16x32_bf16 v[14:17], v[134:137], v[220:223], v[14:17]
	v_mfma_f32_16x16x32_bf16 v[10:13], v[142:145], v[220:223], v[10:13]
	v_mfma_f32_16x16x32_bf16 v[54:57], v[146:149], v[176:179], v[54:57]
	v_mfma_f32_16x16x32_bf16 v[50:53], v[154:157], v[176:179], v[50:53]
	v_mfma_f32_16x16x32_bf16 v[38:41], v[146:149], v[184:187], v[38:41]
	v_mfma_f32_16x16x32_bf16 v[34:37], v[154:157], v[184:187], v[34:37]
	v_mfma_f32_16x16x32_bf16 v[22:25], v[146:149], v[194:197], v[22:25]
	v_mfma_f32_16x16x32_bf16 v[18:21], v[154:157], v[194:197], v[18:21]
	v_mfma_f32_16x16x32_bf16 v[6:9], v[146:149], v[216:219], v[6:9]
	v_mfma_f32_16x16x32_bf16 v[2:5], v[154:157], v[216:219], v[2:5]
	v_mfma_f32_16x16x32_bf16 v[54:57], v[150:153], v[180:183], v[54:57]
	v_mfma_f32_16x16x32_bf16 v[50:53], v[172:175], v[180:183], v[50:53]
	v_mfma_f32_16x16x32_bf16 v[38:41], v[150:153], v[190:193], v[38:41]
	v_mfma_f32_16x16x32_bf16 v[34:37], v[172:175], v[190:193], v[34:37]
	v_mfma_f32_16x16x32_bf16 v[22:25], v[150:153], v[198:201], v[22:25]
	v_mfma_f32_16x16x32_bf16 v[18:21], v[172:175], v[198:201], v[18:21]
	v_mfma_f32_16x16x32_bf16 v[6:9], v[150:153], v[220:223], v[6:9]
	v_mfma_f32_16x16x32_bf16 v[2:5], v[172:175], v[220:223], v[2:5]
	s_setprio 0
	s_barrier
	s_add_i32 s44, s44, 2
	s_add_u32 s39, s39, 0x100
	s_addc_u32 s42, s42, 0
	s_cmp_gt_u32 s44, 41
	s_mov_b64 s[18:19], s[20:21]
	s_cbranch_scc0 .LBB0_212
	s_and_b64 vcc, exec, s[10:11]
	s_cbranch_vccz .LBB0_215
	s_barrier

; #define PG8_STAGE(bufoff, gbase, voff) do { _Pragma("unroll") for (int _i = 0; _i < 2; ++_i) \
;         __builtin_amdgcn_global_load_lds((const unsigned*)((const char*)(gbase) + (voff)[_i]), (PG8_LAS unsigned*)(lds + (bufoff) + ldsw + _i * 8192), 16, 0, 0); } while (0)
; #define PG8_LDA(dst, b, h) do { _Pragma("unroll") for (int m = 0; m < 4; ++m) _Pragma("unroll") for (int k = 0; k < 2; ++k) dst[m][k] = *(const PG8_LAS bf16x8*)(lds + PG8_SA(b, h) + aoff + m * 2048 + k * 1024); } while (0)
; #define PG8_WAIT_V(n) asm volatile("s_waitcnt vmcnt(" #n ")" ::: "memory")
; #define PG8_WAIT_L(n) asm volatile("s_waitcnt lgkmcnt(" #n ")" ::: "memory")
; #define PG8_BAR __builtin_amdgcn_s_barrier()
; template <class Epi, class Sched, bool ALIGN_EPI = false, bool SP2 = false>
; __device__ __forceinline__ void gemm_phase(PG8_LAS unsigned char* lds, const Gemm g, const Sched& S, const Epi& E) {
;     ...
;         for (int t = t_lo; t < t_hi; t += 2) {
;             const bool last = (t == nt - 2);
;             const char* a1 = cA + (size_t)(t + 1) * kstep;
;             const char* a2 = last ? nA : cA + (size_t)(t + 2) * kstep; const char* b2 = last ? nB : cB + (size_t)(t + 2) * kstep;
;             const char* a3 = a2 + kstep; const char* b3 = b2 + kstep;
;             if (last && has_next) S.a_ready_inloop(nxt, ui + 1);
;             if constexpr (SP2) {
;             PG8_LDB(B0, 0, 0); PG8_LDB(B1, 0, 1); PG8_SCHED; PG8_LDA(At, 0, 0); PG8_STAGE(PG8_SA(1, 1), a1 + hstep, voffA);
;             PG8_WAIT_V(8); PG8_WAIT_L(0); PG8_BAR; PG8_MMA(0, 0, At, B0); PG8_MMA(0, 1, At, B1); PG8_BAR; PG8_SCHED;
;             PG8_LDA(At, 0, 1); PG8_STAGE(PG8_SB(0, 0), b2, voffB); PG8_STAGE(PG8_SB(0, 1), b2 + hstep, voffB); PG8_STAGE(PG8_SA(0, 0), a2, voffA);
;             PG8_WAIT_V(8); PG8_WAIT_L(0); PG8_BAR; PG8_MMA(1, 0, At, B0); PG8_MMA(1, 1, At, B1); PG8_BAR; PG8_SCHED;
;             PG8_LDB(B0, 1, 0); PG8_LDB(B1, 1, 1); PG8_SCHED; PG8_LDA(At, 1, 0); PG8_STAGE(PG8_SA(0, 1), a2 + hstep, voffA);
;             PG8_WAIT_V(8); PG8_WAIT_L(0); PG8_BAR; PG8_MMA(0, 0, At, B0); PG8_MMA(0, 1, At, B1); PG8_BAR; PG8_SCHED;
;             PG8_LDA(At, 1, 1); PG8_STAGE(PG8_SB(1, 0), b3, voffB); PG8_STAGE(PG8_SB(1, 1), b3 + hstep, voffB); PG8_STAGE(PG8_SA(1, 0), a3, voffA);
;             PG8_WAIT_V(8); PG8_WAIT_L(0); PG8_BAR; PG8_MMA(1, 0, At, B0); PG8_MMA(1, 1, At, B1); PG8_BAR; PG8_SCHED;
.LBB0_318:
	s_ashr_i32 s17, s16, 31
	s_lshl_b64 s[20:21], s[16:17], 19
	s_add_u32 s20, s34, s20
	s_addc_u32 s21, s35, s21
	s_and_b64 s[22:23], s[2:3], exec
	s_cselect_b32 s13, s21, s25
	s_cselect_b32 s17, s20, s24
	s_ashr_i32 s19, s18, 31
	s_lshl_b64 s[22:23], s[18:19], 19
	s_add_u32 s22, s36, s22
	s_addc_u32 s23, s37, s23
	s_and_b64 s[28:29], s[2:3], exec
	s_cselect_b32 s19, s23, s27
	s_cselect_b32 s42, s22, s26
	s_add_u32 s24, s24, 0x40080
	s_addc_u32 s25, s25, 0
	s_add_u32 s44, s26, 0x100
	s_addc_u32 s45, s27, 0
	s_mov_b32 s52, -2
	s_add_u32 s26, s24, 0xfffc0080
	s_addc_u32 s27, s25, -1
	s_cmp_eq_u32 s52, 12
	s_cselect_b32 s29, s13, s27
	s_cselect_b32 s28, s17, s26
	s_cselect_b32 s27, s19, s45
	s_cselect_b32 s26, s42, s44
	s_add_u32 s98, s26, s46
	s_addc_u32 s99, s27, s47
	s_add_u32 s100, s28, s46
	s_addc_u32 s101, s29, s47
	s_add_i32 m0, s39, 0xc000
	s_nop 0
	global_load_lds_dwordx4 v190, s[24:25]
	s_add_i32 m0, s39, 0xe000
	s_nop 0
	global_load_lds_dwordx4 v192, s[24:25]
	v_add_u32_e32 v158, s90, v200
	v_add_u32_e32 v174, s81, v200
	ds_read_b128 v[146:149], v158
	ds_read_b128 v[150:153], v158 offset:1024
	ds_read_b128 v[154:157], v158 offset:2048
	ds_read_b128 v[158:161], v158 offset:3072
	ds_read_b128 v[162:165], v174
	ds_read_b128 v[166:169], v174 offset:1024
	ds_read_b128 v[170:173], v174 offset:2048
	ds_read_b128 v[174:177], v174 offset:3072
	ds_read_b128 v[216:219], v202
	ds_read_b128 v[220:223], v202 offset:1024
	ds_read_b128 v[224:227], v202 offset:2048
	ds_read_b128 v[228:231], v202 offset:3072
	ds_read_b128 v[232:235], v202 offset:4096
	ds_read_b128 v[236:239], v202 offset:5120
	ds_read_b128 v[240:243], v202 offset:6144
	ds_read_b128 v[244:247], v202 offset:7168
	s_waitcnt vmcnt(8) lgkmcnt(0)
	s_barrier
	s_setprio 1
	v_mfma_f32_16x16x32_bf16 v[142:145], v[146:149], v[216:219], 0
	v_mfma_f32_16x16x32_bf16 v[138:141], v[154:157], v[216:219], 0
	v_mfma_f32_16x16x32_bf16 v[126:129], v[146:149], v[224:227], 0
	v_mfma_f32_16x16x32_bf16 v[122:125], v[154:157], v[224:227], 0
	v_mfma_f32_16x16x32_bf16 v[110:113], v[146:149], v[232:235], 0
	v_mfma_f32_16x16x32_bf16 v[106:109], v[154:157], v[232:235], 0
	v_mfma_f32_16x16x32_bf16 v[94:97], v[146:149], v[240:243], 0
	v_mfma_f32_16x16x32_bf16 v[90:93], v[154:157], v[240:243], 0
	v_mfma_f32_16x16x32_bf16 v[142:145], v[150:153], v[220:223], v[142:145]
	v_mfma_f32_16x16x32_bf16 v[138:141], v[158:161], v[220:223], v[138:141]
	v_mfma_f32_16x16x32_bf16 v[126:129], v[150:153], v[228:231], v[126:129]
	v_mfma_f32_16x16x32_bf16 v[122:125], v[158:161], v[228:231], v[122:125]
	v_mfma_f32_16x16x32_bf16 v[110:113], v[150:153], v[236:239], v[110:113]
	v_mfma_f32_16x16x32_bf16 v[106:109], v[158:161], v[236:239], v[106:109]
	v_mfma_f32_16x16x32_bf16 v[94:97], v[150:153], v[244:247], v[94:97]
	v_mfma_f32_16x16x32_bf16 v[90:93], v[158:161], v[244:247], v[90:93]
	v_mfma_f32_16x16x32_bf16 v[134:137], v[162:165], v[216:219], 0
	v_mfma_f32_16x16x32_bf16 v[130:133], v[170:173], v[216:219], 0
	v_mfma_f32_16x16x32_bf16 v[118:121], v[162:165], v[224:227], 0
	v_mfma_f32_16x16x32_bf16 v[114:117], v[170:173], v[224:227], 0
	v_mfma_f32_16x16x32_bf16 v[102:105], v[162:165], v[232:235], 0
	v_mfma_f32_16x16x32_bf16 v[98:101], v[170:173], v[232:235], 0
	v_mfma_f32_16x16x32_bf16 v[86:89], v[162:165], v[240:243], 0
	v_mfma_f32_16x16x32_bf16 v[82:85], v[170:173], v[240:243], 0
	v_mfma_f32_16x16x32_bf16 v[134:137], v[166:169], v[220:223], v[134:137]
	v_mfma_f32_16x16x32_bf16 v[130:133], v[174:177], v[220:223], v[130:133]
	v_mfma_f32_16x16x32_bf16 v[118:121], v[166:169], v[228:231], v[118:121]
	v_mfma_f32_16x16x32_bf16 v[114:117], v[174:177], v[228:231], v[114:117]
	v_mfma_f32_16x16x32_bf16 v[102:105], v[166:169], v[236:239], v[102:105]
	v_mfma_f32_16x16x32_bf16 v[98:101], v[174:177], v[236:239], v[98:101]
	v_mfma_f32_16x16x32_bf16 v[86:89], v[166:169], v[244:247], v[86:89]
	v_mfma_f32_16x16x32_bf16 v[82:85], v[174:177], v[244:247], v[82:85]
	s_setprio 0
	s_barrier
	s_add_i32 s53, s90, s38
	s_mov_b32 m0, s53
	s_nop 0
	global_load_lds_dwordx4 v180, s[26:27]
	s_add_i32 m0, s53, 0x2000
	s_add_u32 vcc_lo, s26, 0x40000
	s_addc_u32 vcc_hi, s27, 0
	s_add_i32 s53, s81, s38
	global_load_lds_dwordx4 v184, s[26:27]
	s_mov_b32 m0, s53
	s_nop 0
	global_load_lds_dwordx4 v180, vcc
	s_add_i32 m0, s53, 0x2000
	s_nop 0
	global_load_lds_dwordx4 v184, vcc
	s_mov_b32 m0, s39
	s_nop 0
	global_load_lds_dwordx4 v178, s[28:29]
	s_mov_b32 m0, s60
	s_nop 0
	global_load_lds_dwordx4 v182, s[28:29]
	ds_read_b128 v[216:219], v202 offset:16384
	ds_read_b128 v[220:223], v202 offset:17408
	ds_read_b128 v[224:227], v202 offset:18432
	ds_read_b128 v[228:231], v202 offset:19456
	ds_read_b128 v[232:235], v202 offset:20480
	ds_read_b128 v[236:239], v202 offset:21504
	ds_read_b128 v[240:243], v202 offset:22528
	ds_read_b128 v[244:247], v202 offset:23552
	s_waitcnt vmcnt(8) lgkmcnt(0)
	s_barrier
; #define PG8_STAGE(bufoff, gbase, voff) do { _Pragma("unroll") for (int _i = 0; _i < 2; ++_i) \
;         __builtin_amdgcn_global_load_lds((const unsigned*)((const char*)(gbase) + (voff)[_i]), (PG8_LAS unsigned*)(lds + (bufoff) + ldsw + _i * 8192), 16, 0, 0); } while (0)
; #define PG8_LDA(dst, b, h) do { _Pragma("unroll") for (int m = 0; m < 4; ++m) _Pragma("unroll") for (int k = 0; k < 2; ++k) dst[m][k] = *(const PG8_LAS bf16x8*)(lds + PG8_SA(b, h) + aoff + m * 2048 + k * 1024); } while (0)
; #define PG8_LDB(dst, b, h) do { _Pragma("unroll") for (int n = 0; n < 2; ++n) _Pragma("unroll") for (int k = 0; k < 2; ++k) dst[n][k] = *(const PG8_LAS bf16x8*)(lds + PG8_SB(b, h) + boff + n * 2048 + k * 1024); } while (0)
; #define PG8_MMA(ai, bj, At, Bt) do { __builtin_amdgcn_s_setprio(1); _Pragma("unroll") for (int m = 0; m < 4; ++m) _Pragma("unroll") for (int n = 0; n < 2; ++n) _Pragma("unroll") for (int k = 0; k < 2; ++k) \
;         acc[ai][bj][m][n] = __builtin_amdgcn_mfma_f32_16x16x32_bf16(Bt[n][k], At[m][k], acc[ai][bj][m][n], 0, 0, 0); __builtin_amdgcn_s_setprio(0); } while (0)
; #define PG8_BAR __builtin_amdgcn_s_barrier()
; template <class Epi, class Sched, bool ALIGN_EPI = false, bool SP2 = false>
; __device__ __forceinline__ void gemm_phase(PG8_LAS unsigned char* lds, const Gemm g, const Sched& S, const Epi& E) {
;     ...
;             if constexpr (SP2) {
;             PG8_LDB(B0, 0, 0); PG8_LDB(B1, 0, 1); PG8_SCHED; PG8_LDA(At, 0, 0); PG8_STAGE(PG8_SA(1, 1), a1 + hstep, voffA);
;             PG8_WAIT_V(8); PG8_WAIT_L(0); PG8_BAR; PG8_MMA(0, 0, At, B0); PG8_MMA(0, 1, At, B1); PG8_BAR; PG8_SCHED;
;             PG8_LDA(At, 0, 1); PG8_STAGE(PG8_SB(0, 0), b2, voffB); PG8_STAGE(PG8_SB(0, 1), b2 + hstep, voffB); PG8_STAGE(PG8_SA(0, 0), a2, voffA);
;             PG8_WAIT_V(8); PG8_WAIT_L(0); PG8_BAR; PG8_MMA(1, 0, At, B0); PG8_MMA(1, 1, At, B1); PG8_BAR; PG8_SCHED;
;             PG8_LDB(B0, 1, 0); PG8_LDB(B1, 1, 1); PG8_SCHED; PG8_LDA(At, 1, 0); PG8_STAGE(PG8_SA(0, 1), a2 + hstep, voffA);
;             PG8_WAIT_V(8); PG8_WAIT_L(0); PG8_BAR; PG8_MMA(0, 0, At, B0); PG8_MMA(0, 1, At, B1); PG8_BAR; PG8_SCHED;
;             PG8_LDA(At, 1, 1); PG8_STAGE(PG8_SB(1, 0), b3, voffB); PG8_STAGE(PG8_SB(1, 1), b3 + hstep, voffB); PG8_STAGE(PG8_SA(1, 0), a3, voffA);
;             PG8_WAIT_V(8); PG8_WAIT_L(0); PG8_BAR; PG8_MMA(1, 0, At, B0); PG8_MMA(1, 1, At, B1); PG8_BAR; PG8_SCHED;
	s_setprio 1
	v_mfma_f32_16x16x32_bf16 v[78:81], v[146:149], v[216:219], 0
	v_mfma_f32_16x16x32_bf16 v[74:77], v[154:157], v[216:219], 0
	v_mfma_f32_16x16x32_bf16 v[62:65], v[146:149], v[224:227], 0
	v_mfma_f32_16x16x32_bf16 v[58:61], v[154:157], v[224:227], 0
	v_mfma_f32_16x16x32_bf16 v[46:49], v[146:149], v[232:235], 0
	v_mfma_f32_16x16x32_bf16 v[42:45], v[154:157], v[232:235], 0
	v_mfma_f32_16x16x32_bf16 v[30:33], v[146:149], v[240:243], 0
	v_mfma_f32_16x16x32_bf16 v[26:29], v[154:157], v[240:243], 0
	v_mfma_f32_16x16x32_bf16 v[78:81], v[150:153], v[220:223], v[78:81]
	v_mfma_f32_16x16x32_bf16 v[74:77], v[158:161], v[220:223], v[74:77]
	v_mfma_f32_16x16x32_bf16 v[62:65], v[150:153], v[228:231], v[62:65]
	v_mfma_f32_16x16x32_bf16 v[58:61], v[158:161], v[228:231], v[58:61]
	v_mfma_f32_16x16x32_bf16 v[46:49], v[150:153], v[236:239], v[46:49]
	v_mfma_f32_16x16x32_bf16 v[42:45], v[158:161], v[236:239], v[42:45]
	v_mfma_f32_16x16x32_bf16 v[30:33], v[150:153], v[244:247], v[30:33]
	v_mfma_f32_16x16x32_bf16 v[26:29], v[158:161], v[244:247], v[26:29]
	v_mfma_f32_16x16x32_bf16 v[70:73], v[162:165], v[216:219], 0
	v_mfma_f32_16x16x32_bf16 v[66:69], v[170:173], v[216:219], 0
	v_mfma_f32_16x16x32_bf16 v[54:57], v[162:165], v[224:227], 0
	v_mfma_f32_16x16x32_bf16 v[50:53], v[170:173], v[224:227], 0
	v_mfma_f32_16x16x32_bf16 v[38:41], v[162:165], v[232:235], 0
	v_mfma_f32_16x16x32_bf16 v[34:37], v[170:173], v[232:235], 0
	v_mfma_f32_16x16x32_bf16 v[22:25], v[162:165], v[240:243], 0
	v_mfma_f32_16x16x32_bf16 v[18:21], v[170:173], v[240:243], 0
	v_mfma_f32_16x16x32_bf16 v[70:73], v[166:169], v[220:223], v[70:73]
	v_mfma_f32_16x16x32_bf16 v[66:69], v[174:177], v[220:223], v[66:69]
	v_mfma_f32_16x16x32_bf16 v[54:57], v[166:169], v[228:231], v[54:57]
	v_mfma_f32_16x16x32_bf16 v[50:53], v[174:177], v[228:231], v[50:53]
	v_mfma_f32_16x16x32_bf16 v[38:41], v[166:169], v[236:239], v[38:41]
	v_mfma_f32_16x16x32_bf16 v[34:37], v[174:177], v[236:239], v[34:37]
	v_mfma_f32_16x16x32_bf16 v[22:25], v[166:169], v[244:247], v[22:25]
	v_mfma_f32_16x16x32_bf16 v[18:21], v[174:177], v[244:247], v[18:21]
	s_setprio 0
	s_barrier
	s_add_u32 s28, s28, 0x40000
	s_addc_u32 s29, s29, 0
	s_mov_b32 m0, s61
	s_nop 0
	global_load_lds_dwordx4 v178, s[28:29]
	s_mov_b32 m0, s62
	s_nop 0
	global_load_lds_dwordx4 v182, s[28:29]
	v_add_u32_e32 v158, s82, v200
	v_add_u32_e32 v174, s83, v200
	ds_read_b128 v[146:149], v158
	ds_read_b128 v[150:153], v158 offset:1024
	ds_read_b128 v[154:157], v158 offset:2048
	ds_read_b128 v[158:161], v158 offset:3072
	ds_read_b128 v[162:165], v174
	ds_read_b128 v[166:169], v174 offset:1024
	ds_read_b128 v[170:173], v174 offset:2048
	ds_read_b128 v[174:177], v174 offset:3072
	ds_read_b128 v[216:219], v202 offset:32768
	ds_read_b128 v[220:223], v202 offset:33792
	ds_read_b128 v[224:227], v202 offset:34816
	ds_read_b128 v[228:231], v202 offset:35840
	ds_read_b128 v[232:235], v202 offset:36864
	ds_read_b128 v[236:239], v202 offset:37888
	ds_read_b128 v[240:243], v202 offset:38912
	ds_read_b128 v[244:247], v202 offset:39936
	s_waitcnt vmcnt(8) lgkmcnt(0)
	s_barrier
	s_setprio 1
	v_mfma_f32_16x16x32_bf16 v[142:145], v[146:149], v[216:219], v[142:145]
	v_mfma_f32_16x16x32_bf16 v[138:141], v[154:157], v[216:219], v[138:141]
	v_mfma_f32_16x16x32_bf16 v[126:129], v[146:149], v[224:227], v[126:129]
	v_mfma_f32_16x16x32_bf16 v[122:125], v[154:157], v[224:227], v[122:125]
	v_mfma_f32_16x16x32_bf16 v[110:113], v[146:149], v[232:235], v[110:113]
	v_mfma_f32_16x16x32_bf16 v[106:109], v[154:157], v[232:235], v[106:109]
	v_mfma_f32_16x16x32_bf16 v[94:97], v[146:149], v[240:243], v[94:97]
	v_mfma_f32_16x16x32_bf16 v[90:93], v[154:157], v[240:243], v[90:93]
	v_mfma_f32_16x16x32_bf16 v[142:145], v[150:153], v[220:223], v[142:145]
	v_mfma_f32_16x16x32_bf16 v[138:141], v[158:161], v[220:223], v[138:141]
	v_mfma_f32_16x16x32_bf16 v[126:129], v[150:153], v[228:231], v[126:129]
	v_mfma_f32_16x16x32_bf16 v[122:125], v[158:161], v[228:231], v[122:125]
	v_mfma_f32_16x16x32_bf16 v[110:113], v[150:153], v[236:239], v[110:113]
	v_mfma_f32_16x16x32_bf16 v[106:109], v[158:161], v[236:239], v[106:109]
	v_mfma_f32_16x16x32_bf16 v[94:97], v[150:153], v[244:247], v[94:97]
	v_mfma_f32_16x16x32_bf16 v[90:93], v[158:161], v[244:247], v[90:93]
	v_mfma_f32_16x16x32_bf16 v[134:137], v[162:165], v[216:219], v[134:137]
	v_mfma_f32_16x16x32_bf16 v[130:133], v[170:173], v[216:219], v[130:133]
	v_mfma_f32_16x16x32_bf16 v[118:121], v[162:165], v[224:227], v[118:121]
	v_mfma_f32_16x16x32_bf16 v[114:117], v[170:173], v[224:227], v[114:117]
	v_mfma_f32_16x16x32_bf16 v[102:105], v[162:165], v[232:235], v[102:105]
	v_mfma_f32_16x16x32_bf16 v[98:101], v[170:173], v[232:235], v[98:101]
	v_mfma_f32_16x16x32_bf16 v[86:89], v[162:165], v[240:243], v[86:89]
	v_mfma_f32_16x16x32_bf16 v[82:85], v[170:173], v[240:243], v[82:85]
	v_mfma_f32_16x16x32_bf16 v[134:137], v[166:169], v[220:223], v[134:137]
	v_mfma_f32_16x16x32_bf16 v[130:133], v[174:177], v[220:223], v[130:133]
	v_mfma_f32_16x16x32_bf16 v[118:121], v[166:169], v[228:231], v[118:121]
	v_mfma_f32_16x16x32_bf16 v[114:117], v[174:177], v[228:231], v[114:117]
	v_mfma_f32_16x16x32_bf16 v[102:105], v[166:169], v[236:239], v[102:105]
	v_mfma_f32_16x16x32_bf16 v[98:101], v[174:177], v[236:239], v[98:101]
	v_mfma_f32_16x16x32_bf16 v[86:89], v[166:169], v[244:247], v[86:89]
	v_mfma_f32_16x16x32_bf16 v[82:85], v[174:177], v[244:247], v[82:85]
	s_setprio 0
	s_barrier
; #define PG8_STAGE(bufoff, gbase, voff) do { _Pragma("unroll") for (int _i = 0; _i < 2; ++_i) \
;         __builtin_amdgcn_global_load_lds((const unsigned*)((const char*)(gbase) + (voff)[_i]), (PG8_LAS unsigned*)(lds + (bufoff) + ldsw + _i * 8192), 16, 0, 0); } while (0)
; #define PG8_LDA(dst, b, h) do { _Pragma("unroll") for (int m = 0; m < 4; ++m) _Pragma("unroll") for (int k = 0; k < 2; ++k) dst[m][k] = *(const PG8_LAS bf16x8*)(lds + PG8_SA(b, h) + aoff + m * 2048 + k * 1024); } while (0)
; #define PG8_WAIT_V(n) asm volatile("s_waitcnt vmcnt(" #n ")" ::: "memory")
; #define PG8_WAIT_L(n) asm volatile("s_waitcnt lgkmcnt(" #n ")" ::: "memory")
; #define PG8_BAR __builtin_amdgcn_s_barrier()
; template <class Epi, class Sched, bool ALIGN_EPI = false, bool SP2 = false>
; __device__ __forceinline__ void gemm_phase(PG8_LAS unsigned char* lds, const Gemm g, const Sched& S, const Epi& E) {
;     ...
;         for (int t = t_lo; t < t_hi; t += 2) {
;             const bool last = (t == nt - 2);
;             const char* a1 = cA + (size_t)(t + 1) * kstep;
;             const char* a2 = last ? nA : cA + (size_t)(t + 2) * kstep; const char* b2 = last ? nB : cB + (size_t)(t + 2) * kstep;
;             const char* a3 = a2 + kstep; const char* b3 = b2 + kstep;
;             if (last && has_next) S.a_ready_inloop(nxt, ui + 1);
;             if constexpr (SP2) {
;             PG8_LDB(B0, 0, 0); PG8_LDB(B1, 0, 1); PG8_SCHED; PG8_LDA(At, 0, 0); PG8_STAGE(PG8_SA(1, 1), a1 + hstep, voffA);
;             PG8_WAIT_V(8); PG8_WAIT_L(0); PG8_BAR; PG8_MMA(0, 0, At, B0); PG8_MMA(0, 1, At, B1); PG8_BAR; PG8_SCHED;
;             PG8_LDA(At, 0, 1); PG8_STAGE(PG8_SB(0, 0), b2, voffB); PG8_STAGE(PG8_SB(0, 1), b2 + hstep, voffB); PG8_STAGE(PG8_SA(0, 0), a2, voffA);
;             PG8_WAIT_V(8); PG8_WAIT_L(0); PG8_BAR; PG8_MMA(1, 0, At, B0); PG8_MMA(1, 1, At, B1); PG8_BAR; PG8_SCHED;
;             PG8_LDB(B0, 1, 0); PG8_LDB(B1, 1, 1); PG8_SCHED; PG8_LDA(At, 1, 0); PG8_STAGE(PG8_SA(0, 1), a2 + hstep, voffA);
;             PG8_WAIT_V(8); PG8_WAIT_L(0); PG8_BAR; PG8_MMA(0, 0, At, B0); PG8_MMA(0, 1, At, B1); PG8_BAR; PG8_SCHED;
;             PG8_LDA(At, 1, 1); PG8_STAGE(PG8_SB(1, 0), b3, voffB); PG8_STAGE(PG8_SB(1, 1), b3 + hstep, voffB); PG8_STAGE(PG8_SA(1, 0), a3, voffA);
;             PG8_WAIT_V(8); PG8_WAIT_L(0); PG8_BAR; PG8_MMA(1, 0, At, B0); PG8_MMA(1, 1, At, B1); PG8_BAR; PG8_SCHED;
	s_add_i32 s28, s82, s38
	s_mov_b32 m0, s28
	s_nop 0
	global_load_lds_dwordx4 v180, s[98:99]
	s_add_i32 m0, s28, 0x2000
	s_add_u32 s26, s26, 0x40080
	s_addc_u32 s27, s27, 0
	s_add_i32 s28, s83, s38
	global_load_lds_dwordx4 v184, s[98:99]
	s_mov_b32 m0, s28
	s_nop 0
	global_load_lds_dwordx4 v180, s[26:27]
	s_add_i32 m0, s28, 0x2000
	s_nop 0
	global_load_lds_dwordx4 v184, s[26:27]
	s_mov_b32 m0, s63
	s_nop 0
	global_load_lds_dwordx4 v178, s[100:101]
	s_mov_b32 m0, s64
	s_nop 0
	global_load_lds_dwordx4 v182, s[100:101]
	ds_read_b128 v[216:219], v202 offset:49152
	ds_read_b128 v[220:223], v202 offset:50176
	ds_read_b128 v[224:227], v202 offset:51200
	ds_read_b128 v[228:231], v202 offset:52224
	ds_read_b128 v[232:235], v202 offset:53248
	ds_read_b128 v[236:239], v202 offset:54272
	ds_read_b128 v[240:243], v202 offset:55296
	ds_read_b128 v[244:247], v202 offset:56320
	s_waitcnt vmcnt(8) lgkmcnt(0)
	s_barrier
	s_setprio 1
	v_mfma_f32_16x16x32_bf16 v[78:81], v[146:149], v[216:219], v[78:81]
	v_mfma_f32_16x16x32_bf16 v[74:77], v[154:157], v[216:219], v[74:77]
	v_mfma_f32_16x16x32_bf16 v[62:65], v[146:149], v[224:227], v[62:65]
	v_mfma_f32_16x16x32_bf16 v[58:61], v[154:157], v[224:227], v[58:61]
	v_mfma_f32_16x16x32_bf16 v[46:49], v[146:149], v[232:235], v[46:49]
	v_mfma_f32_16x16x32_bf16 v[42:45], v[154:157], v[232:235], v[42:45]
	v_mfma_f32_16x16x32_bf16 v[30:33], v[146:149], v[240:243], v[30:33]
	v_mfma_f32_16x16x32_bf16 v[26:29], v[154:157], v[240:243], v[26:29]
	v_mfma_f32_16x16x32_bf16 v[78:81], v[150:153], v[220:223], v[78:81]
	v_mfma_f32_16x16x32_bf16 v[74:77], v[158:161], v[220:223], v[74:77]
	v_mfma_f32_16x16x32_bf16 v[62:65], v[150:153], v[228:231], v[62:65]
	v_mfma_f32_16x16x32_bf16 v[58:61], v[158:161], v[228:231], v[58:61]
	v_mfma_f32_16x16x32_bf16 v[46:49], v[150:153], v[236:239], v[46:49]
	v_mfma_f32_16x16x32_bf16 v[42:45], v[158:161], v[236:239], v[42:45]
	v_mfma_f32_16x16x32_bf16 v[30:33], v[150:153], v[244:247], v[30:33]
	v_mfma_f32_16x16x32_bf16 v[26:29], v[158:161], v[244:247], v[26:29]
	v_mfma_f32_16x16x32_bf16 v[70:73], v[162:165], v[216:219], v[70:73]
	v_mfma_f32_16x16x32_bf16 v[66:69], v[170:173], v[216:219], v[66:69]
	v_mfma_f32_16x16x32_bf16 v[54:57], v[162:165], v[224:227], v[54:57]
	v_mfma_f32_16x16x32_bf16 v[50:53], v[170:173], v[224:227], v[50:53]
	v_mfma_f32_16x16x32_bf16 v[38:41], v[162:165], v[232:235], v[38:41]
	v_mfma_f32_16x16x32_bf16 v[34:37], v[170:173], v[232:235], v[34:37]
	v_mfma_f32_16x16x32_bf16 v[22:25], v[162:165], v[240:243], v[22:25]
	v_mfma_f32_16x16x32_bf16 v[18:21], v[170:173], v[240:243], v[18:21]
	v_mfma_f32_16x16x32_bf16 v[70:73], v[166:169], v[220:223], v[70:73]
	v_mfma_f32_16x16x32_bf16 v[66:69], v[174:177], v[220:223], v[66:69]
	v_mfma_f32_16x16x32_bf16 v[54:57], v[166:169], v[228:231], v[54:57]
	v_mfma_f32_16x16x32_bf16 v[50:53], v[174:177], v[228:231], v[50:53]
	v_mfma_f32_16x16x32_bf16 v[38:41], v[166:169], v[236:239], v[38:41]
	v_mfma_f32_16x16x32_bf16 v[34:37], v[174:177], v[236:239], v[34:37]
	v_mfma_f32_16x16x32_bf16 v[22:25], v[166:169], v[244:247], v[22:25]
	v_mfma_f32_16x16x32_bf16 v[18:21], v[174:177], v[244:247], v[18:21]
	s_setprio 0
	s_barrier
	s_add_i32 s52, s52, 2
	s_add_u32 s24, s24, 0x100
	s_addc_u32 s25, s25, 0
	s_add_u32 s44, s44, 0x100
	s_addc_u32 s45, s45, 0
.LBB0_319:
	s_add_u32 s26, s24, 0xfffc0080
	s_addc_u32 s27, s25, -1
	s_cmp_eq_u32 s52, 12
	s_cselect_b32 s29, s13, s27
	s_cselect_b32 s28, s17, s26
	s_cselect_b32 s27, s19, s45
	s_cselect_b32 s26, s42, s44
	s_add_u32 s98, s26, s46
	s_addc_u32 s99, s27, s47
	s_add_u32 s100, s28, s46
	s_addc_u32 s101, s29, s47
	s_add_i32 m0, s39, 0xc000
	s_nop 0
	global_load_lds_dwordx4 v190, s[24:25]
	s_add_i32 m0, s39, 0xe000
	s_nop 0
	global_load_lds_dwordx4 v192, s[24:25]
	v_add_u32_e32 v158, s90, v200
	v_add_u32_e32 v174, s81, v200
	ds_read_b128 v[146:149], v158
	ds_read_b128 v[150:153], v158 offset:1024
	ds_read_b128 v[154:157], v158 offset:2048
	ds_read_b128 v[158:161], v158 offset:3072
	ds_read_b128 v[162:165], v174
	ds_read_b128 v[166:169], v174 offset:1024
	ds_read_b128 v[170:173], v174 offset:2048
	ds_read_b128 v[174:177], v174 offset:3072
	ds_read_b128 v[216:219], v202
	ds_read_b128 v[220:223], v202 offset:1024
	ds_read_b128 v[224:227], v202 offset:2048
	ds_read_b128 v[228:231], v202 offset:3072
	ds_read_b128 v[232:235], v202 offset:4096
	ds_read_b128 v[236:239], v202 offset:5120
	ds_read_b128 v[240:243], v202 offset:6144
	ds_read_b128 v[244:247], v202 offset:7168
	s_waitcnt vmcnt(8) lgkmcnt(0)
	s_barrier
; #define PG8_STAGE(bufoff, gbase, voff) do { _Pragma("unroll") for (int _i = 0; _i < 2; ++_i) \
;         __builtin_amdgcn_global_load_lds((const unsigned*)((const char*)(gbase) + (voff)[_i]), (PG8_LAS unsigned*)(lds + (bufoff) + ldsw + _i * 8192), 16, 0, 0); } while (0)
; #define PG8_LDA(dst, b, h) do { _Pragma("unroll") for (int m = 0; m < 4; ++m) _Pragma("unroll") for (int k = 0; k < 2; ++k) dst[m][k] = *(const PG8_LAS bf16x8*)(lds + PG8_SA(b, h) + aoff + m * 2048 + k * 1024); } while (0)
; #define PG8_LDB(dst, b, h) do { _Pragma("unroll") for (int n = 0; n < 2; ++n) _Pragma("unroll") for (int k = 0; k < 2; ++k) dst[n][k] = *(const PG8_LAS bf16x8*)(lds + PG8_SB(b, h) + boff + n * 2048 + k * 1024); } while (0)
; #define PG8_MMA(ai, bj, At, Bt) do { __builtin_amdgcn_s_setprio(1); _Pragma("unroll") for (int m = 0; m < 4; ++m) _Pragma("unroll") for (int n = 0; n < 2; ++n) _Pragma("unroll") for (int k = 0; k < 2; ++k) \
;         acc[ai][bj][m][n] = __builtin_amdgcn_mfma_f32_16x16x32_bf16(Bt[n][k], At[m][k], acc[ai][bj][m][n], 0, 0, 0); __builtin_amdgcn_s_setprio(0); } while (0)
; #define PG8_BAR __builtin_amdgcn_s_barrier()
; template <class Epi, class Sched, bool ALIGN_EPI = false, bool SP2 = false>
; __device__ __forceinline__ void gemm_phase(PG8_LAS unsigned char* lds, const Gemm g, const Sched& S, const Epi& E) {
;     ...
;             if constexpr (SP2) {
;             PG8_LDB(B0, 0, 0); PG8_LDB(B1, 0, 1); PG8_SCHED; PG8_LDA(At, 0, 0); PG8_STAGE(PG8_SA(1, 1), a1 + hstep, voffA);
;             PG8_WAIT_V(8); PG8_WAIT_L(0); PG8_BAR; PG8_MMA(0, 0, At, B0); PG8_MMA(0, 1, At, B1); PG8_BAR; PG8_SCHED;
;             PG8_LDA(At, 0, 1); PG8_STAGE(PG8_SB(0, 0), b2, voffB); PG8_STAGE(PG8_SB(0, 1), b2 + hstep, voffB); PG8_STAGE(PG8_SA(0, 0), a2, voffA);
;             PG8_WAIT_V(8); PG8_WAIT_L(0); PG8_BAR; PG8_MMA(1, 0, At, B0); PG8_MMA(1, 1, At, B1); PG8_BAR; PG8_SCHED;
;             PG8_LDB(B0, 1, 0); PG8_LDB(B1, 1, 1); PG8_SCHED; PG8_LDA(At, 1, 0); PG8_STAGE(PG8_SA(0, 1), a2 + hstep, voffA);
;             PG8_WAIT_V(8); PG8_WAIT_L(0); PG8_BAR; PG8_MMA(0, 0, At, B0); PG8_MMA(0, 1, At, B1); PG8_BAR; PG8_SCHED;
;             PG8_LDA(At, 1, 1); PG8_STAGE(PG8_SB(1, 0), b3, voffB); PG8_STAGE(PG8_SB(1, 1), b3 + hstep, voffB); PG8_STAGE(PG8_SA(1, 0), a3, voffA);
;             PG8_WAIT_V(8); PG8_WAIT_L(0); PG8_BAR; PG8_MMA(1, 0, At, B0); PG8_MMA(1, 1, At, B1); PG8_BAR; PG8_SCHED;
	s_setprio 1
	v_mfma_f32_16x16x32_bf16 v[142:145], v[146:149], v[216:219], v[142:145]
	v_mfma_f32_16x16x32_bf16 v[138:141], v[154:157], v[216:219], v[138:141]
	v_mfma_f32_16x16x32_bf16 v[126:129], v[146:149], v[224:227], v[126:129]
	v_mfma_f32_16x16x32_bf16 v[122:125], v[154:157], v[224:227], v[122:125]
	v_mfma_f32_16x16x32_bf16 v[110:113], v[146:149], v[232:235], v[110:113]
	v_mfma_f32_16x16x32_bf16 v[106:109], v[154:157], v[232:235], v[106:109]
	v_mfma_f32_16x16x32_bf16 v[94:97], v[146:149], v[240:243], v[94:97]
	v_mfma_f32_16x16x32_bf16 v[90:93], v[154:157], v[240:243], v[90:93]
	v_mfma_f32_16x16x32_bf16 v[142:145], v[150:153], v[220:223], v[142:145]
	v_mfma_f32_16x16x32_bf16 v[138:141], v[158:161], v[220:223], v[138:141]
	v_mfma_f32_16x16x32_bf16 v[126:129], v[150:153], v[228:231], v[126:129]
	v_mfma_f32_16x16x32_bf16 v[122:125], v[158:161], v[228:231], v[122:125]
	v_mfma_f32_16x16x32_bf16 v[110:113], v[150:153], v[236:239], v[110:113]
	v_mfma_f32_16x16x32_bf16 v[106:109], v[158:161], v[236:239], v[106:109]
	v_mfma_f32_16x16x32_bf16 v[94:97], v[150:153], v[244:247], v[94:97]
	v_mfma_f32_16x16x32_bf16 v[90:93], v[158:161], v[244:247], v[90:93]
	v_mfma_f32_16x16x32_bf16 v[134:137], v[162:165], v[216:219], v[134:137]
	v_mfma_f32_16x16x32_bf16 v[130:133], v[170:173], v[216:219], v[130:133]
	v_mfma_f32_16x16x32_bf16 v[118:121], v[162:165], v[224:227], v[118:121]
	v_mfma_f32_16x16x32_bf16 v[114:117], v[170:173], v[224:227], v[114:117]
	v_mfma_f32_16x16x32_bf16 v[102:105], v[162:165], v[232:235], v[102:105]
	v_mfma_f32_16x16x32_bf16 v[98:101], v[170:173], v[232:235], v[98:101]
	v_mfma_f32_16x16x32_bf16 v[86:89], v[162:165], v[240:243], v[86:89]
	v_mfma_f32_16x16x32_bf16 v[82:85], v[170:173], v[240:243], v[82:85]
	v_mfma_f32_16x16x32_bf16 v[134:137], v[166:169], v[220:223], v[134:137]
	v_mfma_f32_16x16x32_bf16 v[130:133], v[174:177], v[220:223], v[130:133]
	v_mfma_f32_16x16x32_bf16 v[118:121], v[166:169], v[228:231], v[118:121]
	v_mfma_f32_16x16x32_bf16 v[114:117], v[174:177], v[228:231], v[114:117]
	v_mfma_f32_16x16x32_bf16 v[102:105], v[166:169], v[236:239], v[102:105]
	v_mfma_f32_16x16x32_bf16 v[98:101], v[174:177], v[236:239], v[98:101]
	v_mfma_f32_16x16x32_bf16 v[86:89], v[166:169], v[244:247], v[86:89]
	v_mfma_f32_16x16x32_bf16 v[82:85], v[174:177], v[244:247], v[82:85]
	s_setprio 0
	s_barrier
	s_add_i32 s53, s90, s38
	s_mov_b32 m0, s53
	s_nop 0
	global_load_lds_dwordx4 v180, s[26:27]
	s_add_i32 m0, s53, 0x2000
	s_add_u32 vcc_lo, s26, 0x40000
	s_addc_u32 vcc_hi, s27, 0
	s_add_i32 s53, s81, s38
	global_load_lds_dwordx4 v184, s[26:27]
	s_mov_b32 m0, s53
	s_nop 0
	global_load_lds_dwordx4 v180, vcc
	s_add_i32 m0, s53, 0x2000
	s_nop 0
	global_load_lds_dwordx4 v184, vcc
	s_mov_b32 m0, s39
	s_nop 0
	global_load_lds_dwordx4 v178, s[28:29]
	s_mov_b32 m0, s60
	s_nop 0
	global_load_lds_dwordx4 v182, s[28:29]
	ds_read_b128 v[216:219], v202 offset:16384
	ds_read_b128 v[220:223], v202 offset:17408
	ds_read_b128 v[224:227], v202 offset:18432
	ds_read_b128 v[228:231], v202 offset:19456
	ds_read_b128 v[232:235], v202 offset:20480
	ds_read_b128 v[236:239], v202 offset:21504
	ds_read_b128 v[240:243], v202 offset:22528
	ds_read_b128 v[244:247], v202 offset:23552
	s_waitcnt vmcnt(8) lgkmcnt(0)
	s_barrier
	s_setprio 1
	v_mfma_f32_16x16x32_bf16 v[78:81], v[146:149], v[216:219], v[78:81]
	v_mfma_f32_16x16x32_bf16 v[74:77], v[154:157], v[216:219], v[74:77]
	v_mfma_f32_16x16x32_bf16 v[62:65], v[146:149], v[224:227], v[62:65]
	v_mfma_f32_16x16x32_bf16 v[58:61], v[154:157], v[224:227], v[58:61]
	v_mfma_f32_16x16x32_bf16 v[46:49], v[146:149], v[232:235], v[46:49]
	v_mfma_f32_16x16x32_bf16 v[42:45], v[154:157], v[232:235], v[42:45]
	v_mfma_f32_16x16x32_bf16 v[30:33], v[146:149], v[240:243], v[30:33]
	v_mfma_f32_16x16x32_bf16 v[26:29], v[154:157], v[240:243], v[26:29]
	v_mfma_f32_16x16x32_bf16 v[78:81], v[150:153], v[220:223], v[78:81]
	v_mfma_f32_16x16x32_bf16 v[74:77], v[158:161], v[220:223], v[74:77]
	v_mfma_f32_16x16x32_bf16 v[62:65], v[150:153], v[228:231], v[62:65]
	v_mfma_f32_16x16x32_bf16 v[58:61], v[158:161], v[228:231], v[58:61]
	v_mfma_f32_16x16x32_bf16 v[46:49], v[150:153], v[236:239], v[46:49]
	v_mfma_f32_16x16x32_bf16 v[42:45], v[158:161], v[236:239], v[42:45]
	v_mfma_f32_16x16x32_bf16 v[30:33], v[150:153], v[244:247], v[30:33]
	v_mfma_f32_16x16x32_bf16 v[26:29], v[158:161], v[244:247], v[26:29]
	v_mfma_f32_16x16x32_bf16 v[70:73], v[162:165], v[216:219], v[70:73]
	v_mfma_f32_16x16x32_bf16 v[66:69], v[170:173], v[216:219], v[66:69]
	v_mfma_f32_16x16x32_bf16 v[54:57], v[162:165], v[224:227], v[54:57]
	v_mfma_f32_16x16x32_bf16 v[50:53], v[170:173], v[224:227], v[50:53]
	v_mfma_f32_16x16x32_bf16 v[38:41], v[162:165], v[232:235], v[38:41]
	v_mfma_f32_16x16x32_bf16 v[34:37], v[170:173], v[232:235], v[34:37]
	v_mfma_f32_16x16x32_bf16 v[22:25], v[162:165], v[240:243], v[22:25]
	v_mfma_f32_16x16x32_bf16 v[18:21], v[170:173], v[240:243], v[18:21]
	v_mfma_f32_16x16x32_bf16 v[70:73], v[166:169], v[220:223], v[70:73]
	v_mfma_f32_16x16x32_bf16 v[66:69], v[174:177], v[220:223], v[66:69]
	v_mfma_f32_16x16x32_bf16 v[54:57], v[166:169], v[228:231], v[54:57]
	v_mfma_f32_16x16x32_bf16 v[50:53], v[174:177], v[228:231], v[50:53]
	v_mfma_f32_16x16x32_bf16 v[38:41], v[166:169], v[236:239], v[38:41]
	v_mfma_f32_16x16x32_bf16 v[34:37], v[174:177], v[236:239], v[34:37]
	v_mfma_f32_16x16x32_bf16 v[22:25], v[166:169], v[244:247], v[22:25]
	v_mfma_f32_16x16x32_bf16 v[18:21], v[174:177], v[244:247], v[18:21]
	s_setprio 0
	s_barrier
; #define PG8_STAGE(bufoff, gbase, voff) do { _Pragma("unroll") for (int _i = 0; _i < 2; ++_i) \
;         __builtin_amdgcn_global_load_lds((const unsigned*)((const char*)(gbase) + (voff)[_i]), (PG8_LAS unsigned*)(lds + (bufoff) + ldsw + _i * 8192), 16, 0, 0); } while (0)
; #define PG8_LDA(dst, b, h) do { _Pragma("unroll") for (int m = 0; m < 4; ++m) _Pragma("unroll") for (int k = 0; k < 2; ++k) dst[m][k] = *(const PG8_LAS bf16x8*)(lds + PG8_SA(b, h) + aoff + m * 2048 + k * 1024); } while (0)
; #define PG8_LDB(dst, b, h) do { _Pragma("unroll") for (int n = 0; n < 2; ++n) _Pragma("unroll") for (int k = 0; k < 2; ++k) dst[n][k] = *(const PG8_LAS bf16x8*)(lds + PG8_SB(b, h) + boff + n * 2048 + k * 1024); } while (0)
; #define PG8_MMA(ai, bj, At, Bt) do { __builtin_amdgcn_s_setprio(1); _Pragma("unroll") for (int m = 0; m < 4; ++m) _Pragma("unroll") for (int n = 0; n < 2; ++n) _Pragma("unroll") for (int k = 0; k < 2; ++k) \
;         acc[ai][bj][m][n] = __builtin_amdgcn_mfma_f32_16x16x32_bf16(Bt[n][k], At[m][k], acc[ai][bj][m][n], 0, 0, 0); __builtin_amdgcn_s_setprio(0); } while (0)
; #define PG8_BAR __builtin_amdgcn_s_barrier()
; template <class Epi, class Sched, bool ALIGN_EPI = false, bool SP2 = false>
; __device__ __forceinline__ void gemm_phase(PG8_LAS unsigned char* lds, const Gemm g, const Sched& S, const Epi& E) {
;     ...
;             if constexpr (SP2) {
;             PG8_LDB(B0, 0, 0); PG8_LDB(B1, 0, 1); PG8_SCHED; PG8_LDA(At, 0, 0); PG8_STAGE(PG8_SA(1, 1), a1 + hstep, voffA);
;             PG8_WAIT_V(8); PG8_WAIT_L(0); PG8_BAR; PG8_MMA(0, 0, At, B0); PG8_MMA(0, 1, At, B1); PG8_BAR; PG8_SCHED;
;             PG8_LDA(At, 0, 1); PG8_STAGE(PG8_SB(0, 0), b2, voffB); PG8_STAGE(PG8_SB(0, 1), b2 + hstep, voffB); PG8_STAGE(PG8_SA(0, 0), a2, voffA);
;             PG8_WAIT_V(8); PG8_WAIT_L(0); PG8_BAR; PG8_MMA(1, 0, At, B0); PG8_MMA(1, 1, At, B1); PG8_BAR; PG8_SCHED;
;             PG8_LDB(B0, 1, 0); PG8_LDB(B1, 1, 1); PG8_SCHED; PG8_LDA(At, 1, 0); PG8_STAGE(PG8_SA(0, 1), a2 + hstep, voffA);
;             PG8_WAIT_V(8); PG8_WAIT_L(0); PG8_BAR; PG8_MMA(0, 0, At, B0); PG8_MMA(0, 1, At, B1); PG8_BAR; PG8_SCHED;
;             PG8_LDA(At, 1, 1); PG8_STAGE(PG8_SB(1, 0), b3, voffB); PG8_STAGE(PG8_SB(1, 1), b3 + hstep, voffB); PG8_STAGE(PG8_SA(1, 0), a3, voffA);
;             PG8_WAIT_V(8); PG8_WAIT_L(0); PG8_BAR; PG8_MMA(1, 0, At, B0); PG8_MMA(1, 1, At, B1); PG8_BAR; PG8_SCHED;
	s_add_u32 s28, s28, 0x40000
	s_addc_u32 s29, s29, 0
	s_mov_b32 m0, s61
	s_nop 0
	global_load_lds_dwordx4 v178, s[28:29]
	s_mov_b32 m0, s62
	s_nop 0
	global_load_lds_dwordx4 v182, s[28:29]
	v_add_u32_e32 v158, s82, v200
	v_add_u32_e32 v174, s83, v200
	ds_read_b128 v[146:149], v158
	ds_read_b128 v[150:153], v158 offset:1024
	ds_read_b128 v[154:157], v158 offset:2048
	ds_read_b128 v[158:161], v158 offset:3072
	ds_read_b128 v[162:165], v174
	ds_read_b128 v[166:169], v174 offset:1024
	ds_read_b128 v[170:173], v174 offset:2048
	ds_read_b128 v[174:177], v174 offset:3072
	ds_read_b128 v[216:219], v202 offset:32768
	ds_read_b128 v[220:223], v202 offset:33792
	ds_read_b128 v[224:227], v202 offset:34816
	ds_read_b128 v[228:231], v202 offset:35840
	ds_read_b128 v[232:235], v202 offset:36864
	ds_read_b128 v[236:239], v202 offset:37888
	ds_read_b128 v[240:243], v202 offset:38912
	ds_read_b128 v[244:247], v202 offset:39936
	s_waitcnt vmcnt(8) lgkmcnt(0)
	s_barrier
	s_setprio 1
	v_mfma_f32_16x16x32_bf16 v[142:145], v[146:149], v[216:219], v[142:145]
	v_mfma_f32_16x16x32_bf16 v[138:141], v[154:157], v[216:219], v[138:141]
	v_mfma_f32_16x16x32_bf16 v[126:129], v[146:149], v[224:227], v[126:129]
	v_mfma_f32_16x16x32_bf16 v[122:125], v[154:157], v[224:227], v[122:125]
	v_mfma_f32_16x16x32_bf16 v[110:113], v[146:149], v[232:235], v[110:113]
	v_mfma_f32_16x16x32_bf16 v[106:109], v[154:157], v[232:235], v[106:109]
	v_mfma_f32_16x16x32_bf16 v[94:97], v[146:149], v[240:243], v[94:97]
	v_mfma_f32_16x16x32_bf16 v[90:93], v[154:157], v[240:243], v[90:93]
	v_mfma_f32_16x16x32_bf16 v[142:145], v[150:153], v[220:223], v[142:145]
	v_mfma_f32_16x16x32_bf16 v[138:141], v[158:161], v[220:223], v[138:141]
	v_mfma_f32_16x16x32_bf16 v[126:129], v[150:153], v[228:231], v[126:129]
	v_mfma_f32_16x16x32_bf16 v[122:125], v[158:161], v[228:231], v[122:125]
	v_mfma_f32_16x16x32_bf16 v[110:113], v[150:153], v[236:239], v[110:113]
	v_mfma_f32_16x16x32_bf16 v[106:109], v[158:161], v[236:239], v[106:109]
	v_mfma_f32_16x16x32_bf16 v[94:97], v[150:153], v[244:247], v[94:97]
	v_mfma_f32_16x16x32_bf16 v[90:93], v[158:161], v[244:247], v[90:93]
	v_mfma_f32_16x16x32_bf16 v[134:137], v[162:165], v[216:219], v[134:137]
	v_mfma_f32_16x16x32_bf16 v[130:133], v[170:173], v[216:219], v[130:133]
	v_mfma_f32_16x16x32_bf16 v[118:121], v[162:165], v[224:227], v[118:121]
	v_mfma_f32_16x16x32_bf16 v[114:117], v[170:173], v[224:227], v[114:117]
	v_mfma_f32_16x16x32_bf16 v[102:105], v[162:165], v[232:235], v[102:105]
	v_mfma_f32_16x16x32_bf16 v[98:101], v[170:173], v[232:235], v[98:101]
	v_mfma_f32_16x16x32_bf16 v[86:89], v[162:165], v[240:243], v[86:89]
	v_mfma_f32_16x16x32_bf16 v[82:85], v[170:173], v[240:243], v[82:85]
	v_mfma_f32_16x16x32_bf16 v[134:137], v[166:169], v[220:223], v[134:137]
	v_mfma_f32_16x16x32_bf16 v[130:133], v[174:177], v[220:223], v[130:133]
	v_mfma_f32_16x16x32_bf16 v[118:121], v[166:169], v[228:231], v[118:121]
	v_mfma_f32_16x16x32_bf16 v[114:117], v[174:177], v[228:231], v[114:117]
	v_mfma_f32_16x16x32_bf16 v[102:105], v[166:169], v[236:239], v[102:105]
	v_mfma_f32_16x16x32_bf16 v[98:101], v[174:177], v[236:239], v[98:101]
	v_mfma_f32_16x16x32_bf16 v[86:89], v[166:169], v[244:247], v[86:89]
	v_mfma_f32_16x16x32_bf16 v[82:85], v[174:177], v[244:247], v[82:85]
	s_setprio 0
	s_barrier
	s_add_i32 s28, s82, s38
	s_mov_b32 m0, s28
	s_nop 0
	global_load_lds_dwordx4 v180, s[98:99]
	s_add_i32 m0, s28, 0x2000
	s_add_u32 s26, s26, 0x40080
	s_addc_u32 s27, s27, 0
	s_add_i32 s28, s83, s38
	global_load_lds_dwordx4 v184, s[98:99]
	s_mov_b32 m0, s28
	s_nop 0
	global_load_lds_dwordx4 v180, s[26:27]
	s_add_i32 m0, s28, 0x2000
	s_nop 0
	global_load_lds_dwordx4 v184, s[26:27]
	s_mov_b32 m0, s63
	s_nop 0
	global_load_lds_dwordx4 v178, s[100:101]
	s_mov_b32 m0, s64
	s_nop 0
	global_load_lds_dwordx4 v182, s[100:101]
	ds_read_b128 v[216:219], v202 offset:49152
	ds_read_b128 v[220:223], v202 offset:50176
	ds_read_b128 v[224:227], v202 offset:51200
	ds_read_b128 v[228:231], v202 offset:52224
	ds_read_b128 v[232:235], v202 offset:53248
	ds_read_b128 v[236:239], v202 offset:54272
	ds_read_b128 v[240:243], v202 offset:55296
	ds_read_b128 v[244:247], v202 offset:56320
	s_waitcnt vmcnt(8) lgkmcnt(0)
	s_barrier
	s_setprio 1
	v_mfma_f32_16x16x32_bf16 v[78:81], v[146:149], v[216:219], v[78:81]
	v_mfma_f32_16x16x32_bf16 v[74:77], v[154:157], v[216:219], v[74:77]
	v_mfma_f32_16x16x32_bf16 v[62:65], v[146:149], v[224:227], v[62:65]
	v_mfma_f32_16x16x32_bf16 v[58:61], v[154:157], v[224:227], v[58:61]
	v_mfma_f32_16x16x32_bf16 v[46:49], v[146:149], v[232:235], v[46:49]
	v_mfma_f32_16x16x32_bf16 v[42:45], v[154:157], v[232:235], v[42:45]
	v_mfma_f32_16x16x32_bf16 v[30:33], v[146:149], v[240:243], v[30:33]
	v_mfma_f32_16x16x32_bf16 v[26:29], v[154:157], v[240:243], v[26:29]
	v_mfma_f32_16x16x32_bf16 v[78:81], v[150:153], v[220:223], v[78:81]
	v_mfma_f32_16x16x32_bf16 v[74:77], v[158:161], v[220:223], v[74:77]
	v_mfma_f32_16x16x32_bf16 v[62:65], v[150:153], v[228:231], v[62:65]
	v_mfma_f32_16x16x32_bf16 v[58:61], v[158:161], v[228:231], v[58:61]
	v_mfma_f32_16x16x32_bf16 v[46:49], v[150:153], v[236:239], v[46:49]
	v_mfma_f32_16x16x32_bf16 v[42:45], v[158:161], v[236:239], v[42:45]
	v_mfma_f32_16x16x32_bf16 v[30:33], v[150:153], v[244:247], v[30:33]
	v_mfma_f32_16x16x32_bf16 v[26:29], v[158:161], v[244:247], v[26:29]
	v_mfma_f32_16x16x32_bf16 v[70:73], v[162:165], v[216:219], v[70:73]
	v_mfma_f32_16x16x32_bf16 v[66:69], v[170:173], v[216:219], v[66:69]
	v_mfma_f32_16x16x32_bf16 v[54:57], v[162:165], v[224:227], v[54:57]
	v_mfma_f32_16x16x32_bf16 v[50:53], v[170:173], v[224:227], v[50:53]
	v_mfma_f32_16x16x32_bf16 v[38:41], v[162:165], v[232:235], v[38:41]
	v_mfma_f32_16x16x32_bf16 v[34:37], v[170:173], v[232:235], v[34:37]
	v_mfma_f32_16x16x32_bf16 v[22:25], v[162:165], v[240:243], v[22:25]
	v_mfma_f32_16x16x32_bf16 v[18:21], v[170:173], v[240:243], v[18:21]
	v_mfma_f32_16x16x32_bf16 v[70:73], v[166:169], v[220:223], v[70:73]
	v_mfma_f32_16x16x32_bf16 v[66:69], v[174:177], v[220:223], v[66:69]
	v_mfma_f32_16x16x32_bf16 v[54:57], v[166:169], v[228:231], v[54:57]
	v_mfma_f32_16x16x32_bf16 v[50:53], v[174:177], v[228:231], v[50:53]
	v_mfma_f32_16x16x32_bf16 v[38:41], v[166:169], v[236:239], v[38:41]
	v_mfma_f32_16x16x32_bf16 v[34:37], v[174:177], v[236:239], v[34:37]
	v_mfma_f32_16x16x32_bf16 v[22:25], v[166:169], v[244:247], v[22:25]
	v_mfma_f32_16x16x32_bf16 v[18:21], v[174:177], v[244:247], v[18:21]
	s_setprio 0
	s_barrier
	s_add_i32 s52, s52, 2
	s_add_u32 s24, s24, 0x100
	s_addc_u32 s25, s25, 0
	s_add_u32 s44, s44, 0x100
	s_addc_u32 s45, s45, 0
	s_cmp_gt_u32 s52, 13
	s_cbranch_scc0 .LBB0_319
	s_and_b64 vcc, exec, s[10:11]
	s_cbranch_vccz .LBB0_322
	s_barrier

; #define PG8_STAGE(bufoff, gbase, voff) do { _Pragma("unroll") for (int _i = 0; _i < 2; ++_i) \
;         __builtin_amdgcn_global_load_lds((const unsigned*)((const char*)(gbase) + (voff)[_i]), (PG8_LAS unsigned*)(lds + (bufoff) + ldsw + _i * 8192), 16, 0, 0); } while (0)
; #define PG8_LDA(dst, b, h) do { _Pragma("unroll") for (int m = 0; m < 4; ++m) _Pragma("unroll") for (int k = 0; k < 2; ++k) dst[m][k] = *(const PG8_LAS bf16x8*)(lds + PG8_SA(b, h) + aoff + m * 2048 + k * 1024); } while (0)
; #define PG8_WAIT_V(n) asm volatile("s_waitcnt vmcnt(" #n ")" ::: "memory")
; #define PG8_WAIT_L(n) asm volatile("s_waitcnt lgkmcnt(" #n ")" ::: "memory")
; #define PG8_BAR __builtin_amdgcn_s_barrier()
; template <class Epi, class Sched, bool ALIGN_EPI = false, bool SP2 = false>
; __device__ __forceinline__ void gemm_phase(PG8_LAS unsigned char* lds, const Gemm g, const Sched& S, const Epi& E) {
;     ...
;         for (int t = t_lo; t < t_hi; t += 2) {
;             const bool last = (t == nt - 2);
;             const char* a1 = cA + (size_t)(t + 1) * kstep;
;             const char* a2 = last ? nA : cA + (size_t)(t + 2) * kstep; const char* b2 = last ? nB : cB + (size_t)(t + 2) * kstep;
;             const char* a3 = a2 + kstep; const char* b3 = b2 + kstep;
;             if (last && has_next) S.a_ready_inloop(nxt, ui + 1);
;             if constexpr (SP2) {
;             PG8_LDB(B0, 0, 0); PG8_LDB(B1, 0, 1); PG8_SCHED; PG8_LDA(At, 0, 0); PG8_STAGE(PG8_SA(1, 1), a1 + hstep, voffA);
;             PG8_WAIT_V(8); PG8_WAIT_L(0); PG8_BAR; PG8_MMA(0, 0, At, B0); PG8_MMA(0, 1, At, B1); PG8_BAR; PG8_SCHED;
;             PG8_LDA(At, 0, 1); PG8_STAGE(PG8_SB(0, 0), b2, voffB); PG8_STAGE(PG8_SB(0, 1), b2 + hstep, voffB); PG8_STAGE(PG8_SA(0, 0), a2, voffA);
;             PG8_WAIT_V(8); PG8_WAIT_L(0); PG8_BAR; PG8_MMA(1, 0, At, B0); PG8_MMA(1, 1, At, B1); PG8_BAR; PG8_SCHED;
;             PG8_LDB(B0, 1, 0); PG8_LDB(B1, 1, 1); PG8_SCHED; PG8_LDA(At, 1, 0); PG8_STAGE(PG8_SA(0, 1), a2 + hstep, voffA);
;             PG8_WAIT_V(8); PG8_WAIT_L(0); PG8_BAR; PG8_MMA(0, 0, At, B0); PG8_MMA(0, 1, At, B1); PG8_BAR; PG8_SCHED;
;             PG8_LDA(At, 1, 1); PG8_STAGE(PG8_SB(1, 0), b3, voffB); PG8_STAGE(PG8_SB(1, 1), b3 + hstep, voffB); PG8_STAGE(PG8_SA(1, 0), a3, voffA);
;             PG8_WAIT_V(8); PG8_WAIT_L(0); PG8_BAR; PG8_MMA(1, 0, At, B0); PG8_MMA(1, 1, At, B1); PG8_BAR; PG8_SCHED;
.LBB0_648:
	s_add_i32 s53, s53, 2
	s_add_u32 s34, s30, s42
	s_addc_u32 s35, s31, 0
	s_add_u32 s74, s28, s42
	s_addc_u32 s75, s29, 0
	s_cmp_eq_u32 s42, s24
	s_cselect_b32 s37, s77, s35
	s_cselect_b32 s36, s52, s34
	s_cselect_b32 s35, s13, s75
	s_cselect_b32 s34, s12, s74
	v_lshl_add_u64 v[202:203], v[152:153], 0, s[42:43]
	s_add_i32 m0, s61, 0xc000
	s_nop 0
	global_load_lds_dwordx4 v[202:203], off
	v_lshl_add_u64 v[202:203], v[2:3], 0, s[42:43]
	s_add_i32 m0, s61, 0xe000
	s_nop 0
	global_load_lds_dwordx4 v[202:203], off
	v_add_u32_e32 v1, s90, v216
	ds_read_b128 v[156:159], v1
	ds_read_b128 v[160:163], v1 offset:1024
	ds_read_b128 v[164:167], v1 offset:2048
	ds_read_b128 v[168:171], v1 offset:3072
	v_add_u32_e32 v1, s81, v216
	ds_read_b128 v[172:175], v1
	ds_read_b128 v[190:193], v1 offset:1024
	ds_read_b128 v[194:197], v1 offset:2048
	ds_read_b128 v[198:201], v1 offset:3072
	ds_read_b128 v[218:221], v217
	ds_read_b128 v[222:225], v217 offset:1024
	ds_read_b128 v[226:229], v217 offset:2048
	ds_read_b128 v[230:233], v217 offset:3072
	ds_read_b128 v[234:237], v217 offset:4096
	ds_read_b128 v[238:241], v217 offset:5120
	ds_read_b128 v[242:245], v217 offset:6144
	ds_read_b128 v[246:249], v217 offset:7168
	s_waitcnt vmcnt(8) lgkmcnt(0)
	s_barrier
	s_setprio 1
	v_mfma_f32_16x16x32_bf16 v[144:147], v[156:159], v[218:221], v[144:147]
	v_mfma_f32_16x16x32_bf16 v[140:143], v[164:167], v[218:221], v[140:143]
	v_mfma_f32_16x16x32_bf16 v[128:131], v[156:159], v[226:229], v[128:131]
	v_mfma_f32_16x16x32_bf16 v[124:127], v[164:167], v[226:229], v[124:127]
	v_mfma_f32_16x16x32_bf16 v[112:115], v[156:159], v[234:237], v[112:115]
	v_mfma_f32_16x16x32_bf16 v[108:111], v[164:167], v[234:237], v[108:111]
	v_mfma_f32_16x16x32_bf16 v[96:99], v[156:159], v[242:245], v[96:99]
	v_mfma_f32_16x16x32_bf16 v[92:95], v[164:167], v[242:245], v[92:95]
	v_mfma_f32_16x16x32_bf16 v[144:147], v[160:163], v[222:225], v[144:147]
	v_mfma_f32_16x16x32_bf16 v[140:143], v[168:171], v[222:225], v[140:143]
	v_mfma_f32_16x16x32_bf16 v[128:131], v[160:163], v[230:233], v[128:131]
	v_mfma_f32_16x16x32_bf16 v[124:127], v[168:171], v[230:233], v[124:127]
	v_mfma_f32_16x16x32_bf16 v[112:115], v[160:163], v[238:241], v[112:115]
	v_mfma_f32_16x16x32_bf16 v[108:111], v[168:171], v[238:241], v[108:111]
	v_mfma_f32_16x16x32_bf16 v[96:99], v[160:163], v[246:249], v[96:99]
	v_mfma_f32_16x16x32_bf16 v[92:95], v[168:171], v[246:249], v[92:95]
	v_mfma_f32_16x16x32_bf16 v[136:139], v[172:175], v[218:221], v[136:139]
	v_mfma_f32_16x16x32_bf16 v[132:135], v[194:197], v[218:221], v[132:135]
	v_mfma_f32_16x16x32_bf16 v[120:123], v[172:175], v[226:229], v[120:123]
	v_mfma_f32_16x16x32_bf16 v[116:119], v[194:197], v[226:229], v[116:119]
	v_mfma_f32_16x16x32_bf16 v[104:107], v[172:175], v[234:237], v[104:107]
	v_mfma_f32_16x16x32_bf16 v[100:103], v[194:197], v[234:237], v[100:103]
	v_mfma_f32_16x16x32_bf16 v[88:91], v[172:175], v[242:245], v[88:91]
	v_mfma_f32_16x16x32_bf16 v[84:87], v[194:197], v[242:245], v[84:87]
	v_mfma_f32_16x16x32_bf16 v[136:139], v[190:193], v[222:225], v[136:139]
	v_mfma_f32_16x16x32_bf16 v[132:135], v[198:201], v[222:225], v[132:135]
	v_mfma_f32_16x16x32_bf16 v[120:123], v[190:193], v[230:233], v[120:123]
	v_mfma_f32_16x16x32_bf16 v[116:119], v[198:201], v[230:233], v[116:119]
	v_mfma_f32_16x16x32_bf16 v[104:107], v[190:193], v[238:241], v[104:107]
	v_mfma_f32_16x16x32_bf16 v[100:103], v[198:201], v[238:241], v[100:103]
	v_mfma_f32_16x16x32_bf16 v[88:91], v[190:193], v[246:249], v[88:91]
	v_mfma_f32_16x16x32_bf16 v[84:87], v[198:201], v[246:249], v[84:87]
	s_setprio 0
	s_barrier
	s_add_i32 s74, s90, s60
	v_lshl_add_u64 v[202:203], s[34:35], 0, v[178:179]
	s_mov_b32 m0, s74
	s_nop 0
	global_load_lds_dwordx4 v[202:203], off
	s_add_i32 m0, s74, 0x2000
	s_add_u32 s74, s34, 0x40000
	v_lshl_add_u64 v[208:209], s[34:35], 0, v[182:183]
	s_addc_u32 s75, s35, 0
	s_add_i32 vcc_hi, s81, s60
	global_load_lds_dwordx4 v[208:209], off
	v_lshl_add_u64 v[250:251], s[74:75], 0, v[178:179]
	s_mov_b32 m0, vcc_hi
	v_lshl_add_u64 v[252:253], s[36:37], 0, v[180:181]
	global_load_lds_dwordx4 v[250:251], off
	v_lshl_add_u64 v[250:251], s[74:75], 0, v[182:183]
	s_add_i32 m0, vcc_hi, 0x2000
	s_nop 0
	global_load_lds_dwordx4 v[250:251], off
	v_lshl_add_u64 v[250:251], s[36:37], 0, v[176:177]
	s_mov_b32 m0, s61
	s_nop 0
	global_load_lds_dwordx4 v[250:251], off
	s_mov_b32 m0, s62
	s_nop 0
	global_load_lds_dwordx4 v[252:253], off
	ds_read_b128 v[218:221], v217 offset:16384
	ds_read_b128 v[222:225], v217 offset:17408
	ds_read_b128 v[226:229], v217 offset:18432
	ds_read_b128 v[230:233], v217 offset:19456
	ds_read_b128 v[234:237], v217 offset:20480
	ds_read_b128 v[238:241], v217 offset:21504
	ds_read_b128 v[242:245], v217 offset:22528
	ds_read_b128 v[246:249], v217 offset:23552
	s_waitcnt vmcnt(8) lgkmcnt(0)
	s_barrier
; #define PG8_STAGE(bufoff, gbase, voff) do { _Pragma("unroll") for (int _i = 0; _i < 2; ++_i) \
;         __builtin_amdgcn_global_load_lds((const unsigned*)((const char*)(gbase) + (voff)[_i]), (PG8_LAS unsigned*)(lds + (bufoff) + ldsw + _i * 8192), 16, 0, 0); } while (0)
; #define PG8_LDA(dst, b, h) do { _Pragma("unroll") for (int m = 0; m < 4; ++m) _Pragma("unroll") for (int k = 0; k < 2; ++k) dst[m][k] = *(const PG8_LAS bf16x8*)(lds + PG8_SA(b, h) + aoff + m * 2048 + k * 1024); } while (0)
; #define PG8_LDB(dst, b, h) do { _Pragma("unroll") for (int n = 0; n < 2; ++n) _Pragma("unroll") for (int k = 0; k < 2; ++k) dst[n][k] = *(const PG8_LAS bf16x8*)(lds + PG8_SB(b, h) + boff + n * 2048 + k * 1024); } while (0)
; #define PG8_MMA(ai, bj, At, Bt) do { __builtin_amdgcn_s_setprio(1); _Pragma("unroll") for (int m = 0; m < 4; ++m) _Pragma("unroll") for (int n = 0; n < 2; ++n) _Pragma("unroll") for (int k = 0; k < 2; ++k) \
;         acc[ai][bj][m][n] = __builtin_amdgcn_mfma_f32_16x16x32_bf16(Bt[n][k], At[m][k], acc[ai][bj][m][n], 0, 0, 0); __builtin_amdgcn_s_setprio(0); } while (0)
; #define PG8_BAR __builtin_amdgcn_s_barrier()
; template <class Epi, class Sched, bool ALIGN_EPI = false, bool SP2 = false>
; __device__ __forceinline__ void gemm_phase(PG8_LAS unsigned char* lds, const Gemm g, const Sched& S, const Epi& E) {
;     ...
;             if constexpr (SP2) {
;             PG8_LDB(B0, 0, 0); PG8_LDB(B1, 0, 1); PG8_SCHED; PG8_LDA(At, 0, 0); PG8_STAGE(PG8_SA(1, 1), a1 + hstep, voffA);
;             PG8_WAIT_V(8); PG8_WAIT_L(0); PG8_BAR; PG8_MMA(0, 0, At, B0); PG8_MMA(0, 1, At, B1); PG8_BAR; PG8_SCHED;
;             PG8_LDA(At, 0, 1); PG8_STAGE(PG8_SB(0, 0), b2, voffB); PG8_STAGE(PG8_SB(0, 1), b2 + hstep, voffB); PG8_STAGE(PG8_SA(0, 0), a2, voffA);
;             PG8_WAIT_V(8); PG8_WAIT_L(0); PG8_BAR; PG8_MMA(1, 0, At, B0); PG8_MMA(1, 1, At, B1); PG8_BAR; PG8_SCHED;
;             PG8_LDB(B0, 1, 0); PG8_LDB(B1, 1, 1); PG8_SCHED; PG8_LDA(At, 1, 0); PG8_STAGE(PG8_SA(0, 1), a2 + hstep, voffA);
;             PG8_WAIT_V(8); PG8_WAIT_L(0); PG8_BAR; PG8_MMA(0, 0, At, B0); PG8_MMA(0, 1, At, B1); PG8_BAR; PG8_SCHED;
;             PG8_LDA(At, 1, 1); PG8_STAGE(PG8_SB(1, 0), b3, voffB); PG8_STAGE(PG8_SB(1, 1), b3 + hstep, voffB); PG8_STAGE(PG8_SA(1, 0), a3, voffA);
;             PG8_WAIT_V(8); PG8_WAIT_L(0); PG8_BAR; PG8_MMA(1, 0, At, B0); PG8_MMA(1, 1, At, B1); PG8_BAR; PG8_SCHED;
	s_setprio 1
	v_mfma_f32_16x16x32_bf16 v[80:83], v[156:159], v[218:221], v[80:83]
	v_mfma_f32_16x16x32_bf16 v[76:79], v[164:167], v[218:221], v[76:79]
	v_mfma_f32_16x16x32_bf16 v[64:67], v[156:159], v[226:229], v[64:67]
	v_mfma_f32_16x16x32_bf16 v[60:63], v[164:167], v[226:229], v[60:63]
	v_mfma_f32_16x16x32_bf16 v[48:51], v[156:159], v[234:237], v[48:51]
	v_mfma_f32_16x16x32_bf16 v[44:47], v[164:167], v[234:237], v[44:47]
	v_mfma_f32_16x16x32_bf16 v[32:35], v[156:159], v[242:245], v[32:35]
	v_mfma_f32_16x16x32_bf16 v[28:31], v[164:167], v[242:245], v[28:31]
	v_mfma_f32_16x16x32_bf16 v[80:83], v[160:163], v[222:225], v[80:83]
	v_mfma_f32_16x16x32_bf16 v[76:79], v[168:171], v[222:225], v[76:79]
	v_mfma_f32_16x16x32_bf16 v[64:67], v[160:163], v[230:233], v[64:67]
	v_mfma_f32_16x16x32_bf16 v[60:63], v[168:171], v[230:233], v[60:63]
	v_mfma_f32_16x16x32_bf16 v[48:51], v[160:163], v[238:241], v[48:51]
	v_mfma_f32_16x16x32_bf16 v[44:47], v[168:171], v[238:241], v[44:47]
	v_mfma_f32_16x16x32_bf16 v[32:35], v[160:163], v[246:249], v[32:35]
	v_mfma_f32_16x16x32_bf16 v[28:31], v[168:171], v[246:249], v[28:31]
	v_mfma_f32_16x16x32_bf16 v[72:75], v[172:175], v[218:221], v[72:75]
	v_mfma_f32_16x16x32_bf16 v[68:71], v[194:197], v[218:221], v[68:71]
	v_mfma_f32_16x16x32_bf16 v[56:59], v[172:175], v[226:229], v[56:59]
	v_mfma_f32_16x16x32_bf16 v[52:55], v[194:197], v[226:229], v[52:55]
	v_mfma_f32_16x16x32_bf16 v[40:43], v[172:175], v[234:237], v[40:43]
	v_mfma_f32_16x16x32_bf16 v[36:39], v[194:197], v[234:237], v[36:39]
	v_mfma_f32_16x16x32_bf16 v[24:27], v[172:175], v[242:245], v[24:27]
	v_mfma_f32_16x16x32_bf16 v[20:23], v[194:197], v[242:245], v[20:23]
	v_mfma_f32_16x16x32_bf16 v[72:75], v[190:193], v[222:225], v[72:75]
	v_mfma_f32_16x16x32_bf16 v[68:71], v[198:201], v[222:225], v[68:71]
	v_mfma_f32_16x16x32_bf16 v[56:59], v[190:193], v[230:233], v[56:59]
	v_mfma_f32_16x16x32_bf16 v[52:55], v[198:201], v[230:233], v[52:55]
	v_mfma_f32_16x16x32_bf16 v[40:43], v[190:193], v[238:241], v[40:43]
	v_mfma_f32_16x16x32_bf16 v[36:39], v[198:201], v[238:241], v[36:39]
	v_mfma_f32_16x16x32_bf16 v[24:27], v[190:193], v[246:249], v[24:27]
	v_mfma_f32_16x16x32_bf16 v[20:23], v[198:201], v[246:249], v[20:23]
	s_setprio 0
	s_barrier
	s_add_u32 s36, s36, 0x40000
	s_addc_u32 s37, s37, 0
	s_mov_b32 m0, s63
	v_lshl_add_u64 v[210:211], s[36:37], 0, v[176:177]
	global_load_lds_dwordx4 v[210:211], off
	v_lshl_add_u64 v[210:211], s[36:37], 0, v[180:181]
	s_mov_b32 m0, s64
	s_nop 0
	global_load_lds_dwordx4 v[210:211], off
	v_add_u32_e32 v1, s82, v216
	ds_read_b128 v[156:159], v1
	ds_read_b128 v[160:163], v1 offset:1024
	ds_read_b128 v[164:167], v1 offset:2048
	ds_read_b128 v[168:171], v1 offset:3072
	v_add_u32_e32 v1, s83, v216
	ds_read_b128 v[172:175], v1
	ds_read_b128 v[190:193], v1 offset:1024
	ds_read_b128 v[194:197], v1 offset:2048
	ds_read_b128 v[198:201], v1 offset:3072
	ds_read_b128 v[218:221], v217 offset:32768
	ds_read_b128 v[222:225], v217 offset:33792
	ds_read_b128 v[226:229], v217 offset:34816
	ds_read_b128 v[230:233], v217 offset:35840
	ds_read_b128 v[234:237], v217 offset:36864
	ds_read_b128 v[238:241], v217 offset:37888
	ds_read_b128 v[242:245], v217 offset:38912
	ds_read_b128 v[246:249], v217 offset:39936
	s_waitcnt vmcnt(8) lgkmcnt(0)
	s_barrier
	s_setprio 1
	v_mfma_f32_16x16x32_bf16 v[144:147], v[156:159], v[218:221], v[144:147]
	v_mfma_f32_16x16x32_bf16 v[140:143], v[164:167], v[218:221], v[140:143]
	v_mfma_f32_16x16x32_bf16 v[128:131], v[156:159], v[226:229], v[128:131]
	v_mfma_f32_16x16x32_bf16 v[124:127], v[164:167], v[226:229], v[124:127]
	v_mfma_f32_16x16x32_bf16 v[112:115], v[156:159], v[234:237], v[112:115]
	v_mfma_f32_16x16x32_bf16 v[108:111], v[164:167], v[234:237], v[108:111]
	v_mfma_f32_16x16x32_bf16 v[96:99], v[156:159], v[242:245], v[96:99]
	v_mfma_f32_16x16x32_bf16 v[92:95], v[164:167], v[242:245], v[92:95]
	v_mfma_f32_16x16x32_bf16 v[144:147], v[160:163], v[222:225], v[144:147]
	v_mfma_f32_16x16x32_bf16 v[140:143], v[168:171], v[222:225], v[140:143]
	v_mfma_f32_16x16x32_bf16 v[128:131], v[160:163], v[230:233], v[128:131]
	v_mfma_f32_16x16x32_bf16 v[124:127], v[168:171], v[230:233], v[124:127]
	v_mfma_f32_16x16x32_bf16 v[112:115], v[160:163], v[238:241], v[112:115]
	v_mfma_f32_16x16x32_bf16 v[108:111], v[168:171], v[238:241], v[108:111]
	v_mfma_f32_16x16x32_bf16 v[96:99], v[160:163], v[246:249], v[96:99]
	v_mfma_f32_16x16x32_bf16 v[92:95], v[168:171], v[246:249], v[92:95]
	v_mfma_f32_16x16x32_bf16 v[136:139], v[172:175], v[218:221], v[136:139]
	v_mfma_f32_16x16x32_bf16 v[132:135], v[194:197], v[218:221], v[132:135]
	v_mfma_f32_16x16x32_bf16 v[120:123], v[172:175], v[226:229], v[120:123]
	v_mfma_f32_16x16x32_bf16 v[116:119], v[194:197], v[226:229], v[116:119]
	v_mfma_f32_16x16x32_bf16 v[104:107], v[172:175], v[234:237], v[104:107]
	v_mfma_f32_16x16x32_bf16 v[100:103], v[194:197], v[234:237], v[100:103]
	v_mfma_f32_16x16x32_bf16 v[88:91], v[172:175], v[242:245], v[88:91]
	v_mfma_f32_16x16x32_bf16 v[84:87], v[194:197], v[242:245], v[84:87]
	v_mfma_f32_16x16x32_bf16 v[136:139], v[190:193], v[222:225], v[136:139]
	v_mfma_f32_16x16x32_bf16 v[132:135], v[198:201], v[222:225], v[132:135]
	v_mfma_f32_16x16x32_bf16 v[120:123], v[190:193], v[230:233], v[120:123]
	v_mfma_f32_16x16x32_bf16 v[116:119], v[198:201], v[230:233], v[116:119]
	v_mfma_f32_16x16x32_bf16 v[104:107], v[190:193], v[238:241], v[104:107]
	v_mfma_f32_16x16x32_bf16 v[100:103], v[198:201], v[238:241], v[100:103]
	v_mfma_f32_16x16x32_bf16 v[88:91], v[190:193], v[246:249], v[88:91]
	v_mfma_f32_16x16x32_bf16 v[84:87], v[198:201], v[246:249], v[84:87]
	s_setprio 0
	s_barrier
; #define PG8_STAGE(bufoff, gbase, voff) do { _Pragma("unroll") for (int _i = 0; _i < 2; ++_i) \
;         __builtin_amdgcn_global_load_lds((const unsigned*)((const char*)(gbase) + (voff)[_i]), (PG8_LAS unsigned*)(lds + (bufoff) + ldsw + _i * 8192), 16, 0, 0); } while (0)
; #define PG8_LDA(dst, b, h) do { _Pragma("unroll") for (int m = 0; m < 4; ++m) _Pragma("unroll") for (int k = 0; k < 2; ++k) dst[m][k] = *(const PG8_LAS bf16x8*)(lds + PG8_SA(b, h) + aoff + m * 2048 + k * 1024); } while (0)
; #define PG8_WAIT_V(n) asm volatile("s_waitcnt vmcnt(" #n ")" ::: "memory")
; #define PG8_WAIT_L(n) asm volatile("s_waitcnt lgkmcnt(" #n ")" ::: "memory")
; #define PG8_BAR __builtin_amdgcn_s_barrier()
; template <class Epi, class Sched, bool ALIGN_EPI = false, bool SP2 = false>
; __device__ __forceinline__ void gemm_phase(PG8_LAS unsigned char* lds, const Gemm g, const Sched& S, const Epi& E) {
;     ...
;         for (int t = t_lo; t < t_hi; t += 2) {
;             const bool last = (t == nt - 2);
;             const char* a1 = cA + (size_t)(t + 1) * kstep;
;             const char* a2 = last ? nA : cA + (size_t)(t + 2) * kstep; const char* b2 = last ? nB : cB + (size_t)(t + 2) * kstep;
;             const char* a3 = a2 + kstep; const char* b3 = b2 + kstep;
;             if (last && has_next) S.a_ready_inloop(nxt, ui + 1);
;             if constexpr (SP2) {
;             PG8_LDB(B0, 0, 0); PG8_LDB(B1, 0, 1); PG8_SCHED; PG8_LDA(At, 0, 0); PG8_STAGE(PG8_SA(1, 1), a1 + hstep, voffA);
;             PG8_WAIT_V(8); PG8_WAIT_L(0); PG8_BAR; PG8_MMA(0, 0, At, B0); PG8_MMA(0, 1, At, B1); PG8_BAR; PG8_SCHED;
;             PG8_LDA(At, 0, 1); PG8_STAGE(PG8_SB(0, 0), b2, voffB); PG8_STAGE(PG8_SB(0, 1), b2 + hstep, voffB); PG8_STAGE(PG8_SA(0, 0), a2, voffA);
;             PG8_WAIT_V(8); PG8_WAIT_L(0); PG8_BAR; PG8_MMA(1, 0, At, B0); PG8_MMA(1, 1, At, B1); PG8_BAR; PG8_SCHED;
;             PG8_LDB(B0, 1, 0); PG8_LDB(B1, 1, 1); PG8_SCHED; PG8_LDA(At, 1, 0); PG8_STAGE(PG8_SA(0, 1), a2 + hstep, voffA);
;             PG8_WAIT_V(8); PG8_WAIT_L(0); PG8_BAR; PG8_MMA(0, 0, At, B0); PG8_MMA(0, 1, At, B1); PG8_BAR; PG8_SCHED;
;             PG8_LDA(At, 1, 1); PG8_STAGE(PG8_SB(1, 0), b3, voffB); PG8_STAGE(PG8_SB(1, 1), b3 + hstep, voffB); PG8_STAGE(PG8_SA(1, 0), a3, voffA);
;             PG8_WAIT_V(8); PG8_WAIT_L(0); PG8_BAR; PG8_MMA(1, 0, At, B0); PG8_MMA(1, 1, At, B1); PG8_BAR; PG8_SCHED;
	s_add_i32 s36, s82, s60
	v_lshl_add_u64 v[202:203], v[202:203], 0, s[46:47]
	s_mov_b32 m0, s36
	s_nop 0
	global_load_lds_dwordx4 v[202:203], off
	s_add_i32 m0, s36, 0x2000
	s_add_u32 s34, s34, 0x40080
	v_lshl_add_u64 v[202:203], v[208:209], 0, s[46:47]
	s_addc_u32 s35, s35, 0
	s_add_i32 s36, s83, s60
	global_load_lds_dwordx4 v[202:203], off
	v_lshl_add_u64 v[202:203], s[34:35], 0, v[178:179]
	s_mov_b32 m0, s36
	s_nop 0
	global_load_lds_dwordx4 v[202:203], off
	v_lshl_add_u64 v[202:203], s[34:35], 0, v[182:183]
	s_add_i32 m0, s36, 0x2000
	s_nop 0
	global_load_lds_dwordx4 v[202:203], off
	v_lshl_add_u64 v[202:203], v[250:251], 0, s[46:47]
	s_mov_b32 m0, s66
	s_nop 0
	global_load_lds_dwordx4 v[202:203], off
	v_lshl_add_u64 v[202:203], v[252:253], 0, s[46:47]
	s_mov_b32 m0, s67
	s_nop 0
	global_load_lds_dwordx4 v[202:203], off
	ds_read_b128 v[218:221], v217 offset:49152
	ds_read_b128 v[222:225], v217 offset:50176
	ds_read_b128 v[226:229], v217 offset:51200
	ds_read_b128 v[230:233], v217 offset:52224
	ds_read_b128 v[234:237], v217 offset:53248
	ds_read_b128 v[238:241], v217 offset:54272
	ds_read_b128 v[242:245], v217 offset:55296
	ds_read_b128 v[246:249], v217 offset:56320
	s_waitcnt vmcnt(8) lgkmcnt(0)
	s_barrier
	s_setprio 1
	v_mfma_f32_16x16x32_bf16 v[80:83], v[156:159], v[218:221], v[80:83]
	v_mfma_f32_16x16x32_bf16 v[76:79], v[164:167], v[218:221], v[76:79]
	v_mfma_f32_16x16x32_bf16 v[64:67], v[156:159], v[226:229], v[64:67]
	v_mfma_f32_16x16x32_bf16 v[60:63], v[164:167], v[226:229], v[60:63]
	v_mfma_f32_16x16x32_bf16 v[48:51], v[156:159], v[234:237], v[48:51]
	v_mfma_f32_16x16x32_bf16 v[44:47], v[164:167], v[234:237], v[44:47]
	v_mfma_f32_16x16x32_bf16 v[32:35], v[156:159], v[242:245], v[32:35]
	v_mfma_f32_16x16x32_bf16 v[28:31], v[164:167], v[242:245], v[28:31]
	v_mfma_f32_16x16x32_bf16 v[80:83], v[160:163], v[222:225], v[80:83]
	v_mfma_f32_16x16x32_bf16 v[76:79], v[168:171], v[222:225], v[76:79]
	v_mfma_f32_16x16x32_bf16 v[64:67], v[160:163], v[230:233], v[64:67]
	v_mfma_f32_16x16x32_bf16 v[60:63], v[168:171], v[230:233], v[60:63]
	v_mfma_f32_16x16x32_bf16 v[48:51], v[160:163], v[238:241], v[48:51]
	v_mfma_f32_16x16x32_bf16 v[44:47], v[168:171], v[238:241], v[44:47]
	v_mfma_f32_16x16x32_bf16 v[32:35], v[160:163], v[246:249], v[32:35]
	v_mfma_f32_16x16x32_bf16 v[28:31], v[168:171], v[246:249], v[28:31]
	v_mfma_f32_16x16x32_bf16 v[72:75], v[172:175], v[218:221], v[72:75]
	v_mfma_f32_16x16x32_bf16 v[68:71], v[194:197], v[218:221], v[68:71]
	v_mfma_f32_16x16x32_bf16 v[56:59], v[172:175], v[226:229], v[56:59]
	v_mfma_f32_16x16x32_bf16 v[52:55], v[194:197], v[226:229], v[52:55]
	v_mfma_f32_16x16x32_bf16 v[40:43], v[172:175], v[234:237], v[40:43]
	v_mfma_f32_16x16x32_bf16 v[36:39], v[194:197], v[234:237], v[36:39]
	v_mfma_f32_16x16x32_bf16 v[24:27], v[172:175], v[242:245], v[24:27]
	v_mfma_f32_16x16x32_bf16 v[20:23], v[194:197], v[242:245], v[20:23]
	v_mfma_f32_16x16x32_bf16 v[72:75], v[190:193], v[222:225], v[72:75]
	v_mfma_f32_16x16x32_bf16 v[68:71], v[198:201], v[222:225], v[68:71]
	v_mfma_f32_16x16x32_bf16 v[56:59], v[190:193], v[230:233], v[56:59]
	v_mfma_f32_16x16x32_bf16 v[52:55], v[198:201], v[230:233], v[52:55]
	v_mfma_f32_16x16x32_bf16 v[40:43], v[190:193], v[238:241], v[40:43]
	v_mfma_f32_16x16x32_bf16 v[36:39], v[198:201], v[238:241], v[36:39]
	v_mfma_f32_16x16x32_bf16 v[24:27], v[190:193], v[246:249], v[24:27]
	v_mfma_f32_16x16x32_bf16 v[20:23], v[198:201], v[246:249], v[20:23]
	s_setprio 0
	s_barrier
	s_add_u32 s30, s30, 0x100
	s_addc_u32 s31, s31, 0
	s_add_u32 s28, s28, 0x100
	s_addc_u32 s29, s29, 0
	s_add_u32 s24, s24, 0xffffff00
	s_addc_u32 s25, s25, -1
	v_lshl_add_u64 v[152:153], v[152:153], 0, s[48:49]
	s_cmp_ge_u32 s53, vcc_lo
	v_lshl_add_u64 v[2:3], v[2:3], 0, s[48:49]
	s_cbranch_scc0 .LBB0_648
	s_mov_b64 s[28:29], -1
	s_mov_b64 s[24:25], 0
	s_and_b64 vcc, exec, s[26:27]
	s_cbranch_vccz .LBB0_645
	s_and_b64 vcc, exec, s[18:19]
	s_cbranch_vccz .LBB0_652
	s_barrier

; #define PG8_STAGE(bufoff, gbase, voff) do { _Pragma("unroll") for (int _i = 0; _i < 2; ++_i) \
;         __builtin_amdgcn_global_load_lds((const unsigned*)((const char*)(gbase) + (voff)[_i]), (PG8_LAS unsigned*)(lds + (bufoff) + ldsw + _i * 8192), 16, 0, 0); } while (0)
; #define PG8_LDA(dst, b, h) do { _Pragma("unroll") for (int m = 0; m < 4; ++m) _Pragma("unroll") for (int k = 0; k < 2; ++k) dst[m][k] = *(const PG8_LAS bf16x8*)(lds + PG8_SA(b, h) + aoff + m * 2048 + k * 1024); } while (0)
; #define PG8_WAIT_V(n) asm volatile("s_waitcnt vmcnt(" #n ")" ::: "memory")
; #define PG8_WAIT_L(n) asm volatile("s_waitcnt lgkmcnt(" #n ")" ::: "memory")
; #define PG8_BAR __builtin_amdgcn_s_barrier()
; template <class Epi, class Sched, bool ALIGN_EPI = false, bool SP2 = false>
; __device__ __forceinline__ void gemm_phase(PG8_LAS unsigned char* lds, const Gemm g, const Sched& S, const Epi& E) {
;     ...
;         for (int t = t_lo; t < t_hi; t += 2) {
;             const bool last = (t == nt - 2);
;             const char* a1 = cA + (size_t)(t + 1) * kstep;
;             const char* a2 = last ? nA : cA + (size_t)(t + 2) * kstep; const char* b2 = last ? nB : cB + (size_t)(t + 2) * kstep;
;             const char* a3 = a2 + kstep; const char* b3 = b2 + kstep;
;             if (last && has_next) S.a_ready_inloop(nxt, ui + 1);
;             if constexpr (SP2) {
;             PG8_LDB(B0, 0, 0); PG8_LDB(B1, 0, 1); PG8_SCHED; PG8_LDA(At, 0, 0); PG8_STAGE(PG8_SA(1, 1), a1 + hstep, voffA);
;             PG8_WAIT_V(8); PG8_WAIT_L(0); PG8_BAR; PG8_MMA(0, 0, At, B0); PG8_MMA(0, 1, At, B1); PG8_BAR; PG8_SCHED;
;             PG8_LDA(At, 0, 1); PG8_STAGE(PG8_SB(0, 0), b2, voffB); PG8_STAGE(PG8_SB(0, 1), b2 + hstep, voffB); PG8_STAGE(PG8_SA(0, 0), a2, voffA);
;             PG8_WAIT_V(8); PG8_WAIT_L(0); PG8_BAR; PG8_MMA(1, 0, At, B0); PG8_MMA(1, 1, At, B1); PG8_BAR; PG8_SCHED;
;             PG8_LDB(B0, 1, 0); PG8_LDB(B1, 1, 1); PG8_SCHED; PG8_LDA(At, 1, 0); PG8_STAGE(PG8_SA(0, 1), a2 + hstep, voffA);
;             PG8_WAIT_V(8); PG8_WAIT_L(0); PG8_BAR; PG8_MMA(0, 0, At, B0); PG8_MMA(0, 1, At, B1); PG8_BAR; PG8_SCHED;
;             PG8_LDA(At, 1, 1); PG8_STAGE(PG8_SB(1, 0), b3, voffB); PG8_STAGE(PG8_SB(1, 1), b3 + hstep, voffB); PG8_STAGE(PG8_SA(1, 0), a3, voffA);
;             PG8_WAIT_V(8); PG8_WAIT_L(0); PG8_BAR; PG8_MMA(1, 0, At, B0); PG8_MMA(1, 1, At, B1); PG8_BAR; PG8_SCHED;
.LBB0_761:
	s_ashr_i32 s13, s12, 31
	s_lshl_b64 s[16:17], s[12:13], 19
	s_add_u32 s16, s28, s16
	s_addc_u32 s17, s29, s17
	s_and_b64 s[18:19], s[2:3], exec
	s_cselect_b32 s13, s17, s21
	s_cselect_b32 s52, s16, s20
	s_ashr_i32 s15, s14, 31
	s_lshl_b64 s[18:19], s[14:15], 19
	s_add_u32 s18, s30, s18
	s_addc_u32 s19, s31, s19
	s_and_b64 s[24:25], s[2:3], exec
	s_cselect_b32 s15, s19, s23
	s_cselect_b32 s53, s18, s22
	s_add_u32 s20, s20, 0x40080
	s_addc_u32 s21, s21, 0
	s_add_u32 s62, s22, 0x100
	s_addc_u32 s63, s23, 0
	s_mov_b32 s64, -2
	s_add_u32 s22, s20, 0xfffc0080
	s_addc_u32 s23, s21, -1
	s_cmp_eq_u32 s64, 12
	s_cselect_b32 s25, s13, s23
	s_cselect_b32 s24, s52, s22
	s_cselect_b32 s23, s15, s63
	s_cselect_b32 s22, s53, s62
	s_add_u32 s98, s22, s46
	s_addc_u32 s99, s23, s47
	s_add_u32 s100, s24, s46
	s_addc_u32 s101, s25, s47
	s_add_i32 m0, s35, 0xc000
	s_nop 0
	global_load_lds_dwordx4 v154, s[20:21]
	s_add_i32 m0, s35, 0xe000
	s_nop 0
	global_load_lds_dwordx4 v156, s[20:21]
	v_add_u32_e32 v158, s90, v160
	ds_read_b128 v[164:167], v158
	ds_read_b128 v[168:171], v158 offset:1024
	ds_read_b128 v[172:175], v158 offset:2048
	ds_read_b128 v[176:179], v158 offset:3072
	v_add_u32_e32 v158, s81, v160
	ds_read_b128 v[180:183], v158
	ds_read_b128 v[184:187], v158 offset:1024
	ds_read_b128 v[188:191], v158 offset:2048
	ds_read_b128 v[192:195], v158 offset:3072
	ds_read_b128 v[196:199], v163
	ds_read_b128 v[200:203], v163 offset:1024
	ds_read_b128 v[216:219], v163 offset:2048
	ds_read_b128 v[220:223], v163 offset:3072
	ds_read_b128 v[224:227], v163 offset:4096
	ds_read_b128 v[228:231], v163 offset:5120
	ds_read_b128 v[232:235], v163 offset:6144
	ds_read_b128 v[236:239], v163 offset:7168
	s_waitcnt vmcnt(8) lgkmcnt(0)
	s_barrier
	s_setprio 1
	v_mfma_f32_16x16x32_bf16 v[142:145], v[164:167], v[196:199], 0
	v_mfma_f32_16x16x32_bf16 v[138:141], v[172:175], v[196:199], 0
	v_mfma_f32_16x16x32_bf16 v[126:129], v[164:167], v[216:219], 0
	v_mfma_f32_16x16x32_bf16 v[122:125], v[172:175], v[216:219], 0
	v_mfma_f32_16x16x32_bf16 v[110:113], v[164:167], v[224:227], 0
	v_mfma_f32_16x16x32_bf16 v[106:109], v[172:175], v[224:227], 0
	v_mfma_f32_16x16x32_bf16 v[94:97], v[164:167], v[232:235], 0
	v_mfma_f32_16x16x32_bf16 v[90:93], v[172:175], v[232:235], 0
	v_mfma_f32_16x16x32_bf16 v[142:145], v[168:171], v[200:203], v[142:145]
	v_mfma_f32_16x16x32_bf16 v[138:141], v[176:179], v[200:203], v[138:141]
	v_mfma_f32_16x16x32_bf16 v[126:129], v[168:171], v[220:223], v[126:129]
	v_mfma_f32_16x16x32_bf16 v[122:125], v[176:179], v[220:223], v[122:125]
	v_mfma_f32_16x16x32_bf16 v[110:113], v[168:171], v[228:231], v[110:113]
	v_mfma_f32_16x16x32_bf16 v[106:109], v[176:179], v[228:231], v[106:109]
	v_mfma_f32_16x16x32_bf16 v[94:97], v[168:171], v[236:239], v[94:97]
	v_mfma_f32_16x16x32_bf16 v[90:93], v[176:179], v[236:239], v[90:93]
	v_mfma_f32_16x16x32_bf16 v[134:137], v[180:183], v[196:199], 0
	v_mfma_f32_16x16x32_bf16 v[130:133], v[188:191], v[196:199], 0
	v_mfma_f32_16x16x32_bf16 v[118:121], v[180:183], v[216:219], 0
	v_mfma_f32_16x16x32_bf16 v[114:117], v[188:191], v[216:219], 0
	v_mfma_f32_16x16x32_bf16 v[102:105], v[180:183], v[224:227], 0
	v_mfma_f32_16x16x32_bf16 v[98:101], v[188:191], v[224:227], 0
	v_mfma_f32_16x16x32_bf16 v[86:89], v[180:183], v[232:235], 0
	v_mfma_f32_16x16x32_bf16 v[82:85], v[188:191], v[232:235], 0
	v_mfma_f32_16x16x32_bf16 v[134:137], v[184:187], v[200:203], v[134:137]
	v_mfma_f32_16x16x32_bf16 v[130:133], v[192:195], v[200:203], v[130:133]
	v_mfma_f32_16x16x32_bf16 v[118:121], v[184:187], v[220:223], v[118:121]
	v_mfma_f32_16x16x32_bf16 v[114:117], v[192:195], v[220:223], v[114:117]
	v_mfma_f32_16x16x32_bf16 v[102:105], v[184:187], v[228:231], v[102:105]
	v_mfma_f32_16x16x32_bf16 v[98:101], v[192:195], v[228:231], v[98:101]
	v_mfma_f32_16x16x32_bf16 v[86:89], v[184:187], v[236:239], v[86:89]
	v_mfma_f32_16x16x32_bf16 v[82:85], v[192:195], v[236:239], v[82:85]
	s_setprio 0
	s_barrier
	s_add_i32 s65, s90, s34
	s_mov_b32 m0, s65
	s_nop 0
	global_load_lds_dwordx4 v148, s[22:23]
	s_add_i32 m0, s65, 0x2000
	s_add_u32 s66, s22, 0x40000
	s_addc_u32 s67, s23, 0
	s_add_i32 s65, s81, s34
	global_load_lds_dwordx4 v152, s[22:23]
	s_mov_b32 m0, s65
	s_nop 0
	global_load_lds_dwordx4 v148, s[66:67]
	s_add_i32 m0, s65, 0x2000
	s_nop 0
	global_load_lds_dwordx4 v152, s[66:67]
	s_mov_b32 m0, s35
	s_nop 0
	global_load_lds_dwordx4 v146, s[24:25]
	s_mov_b32 m0, s36
	s_nop 0
	global_load_lds_dwordx4 v150, s[24:25]
	ds_read_b128 v[196:199], v163 offset:16384
	ds_read_b128 v[200:203], v163 offset:17408
	ds_read_b128 v[216:219], v163 offset:18432
	ds_read_b128 v[220:223], v163 offset:19456
	ds_read_b128 v[224:227], v163 offset:20480
	ds_read_b128 v[228:231], v163 offset:21504
	ds_read_b128 v[232:235], v163 offset:22528
	ds_read_b128 v[236:239], v163 offset:23552
	s_waitcnt vmcnt(8) lgkmcnt(0)
	s_barrier
; #define PG8_STAGE(bufoff, gbase, voff) do { _Pragma("unroll") for (int _i = 0; _i < 2; ++_i) \
;         __builtin_amdgcn_global_load_lds((const unsigned*)((const char*)(gbase) + (voff)[_i]), (PG8_LAS unsigned*)(lds + (bufoff) + ldsw + _i * 8192), 16, 0, 0); } while (0)
; #define PG8_LDA(dst, b, h) do { _Pragma("unroll") for (int m = 0; m < 4; ++m) _Pragma("unroll") for (int k = 0; k < 2; ++k) dst[m][k] = *(const PG8_LAS bf16x8*)(lds + PG8_SA(b, h) + aoff + m * 2048 + k * 1024); } while (0)
; #define PG8_LDB(dst, b, h) do { _Pragma("unroll") for (int n = 0; n < 2; ++n) _Pragma("unroll") for (int k = 0; k < 2; ++k) dst[n][k] = *(const PG8_LAS bf16x8*)(lds + PG8_SB(b, h) + boff + n * 2048 + k * 1024); } while (0)
; #define PG8_MMA(ai, bj, At, Bt) do { __builtin_amdgcn_s_setprio(1); _Pragma("unroll") for (int m = 0; m < 4; ++m) _Pragma("unroll") for (int n = 0; n < 2; ++n) _Pragma("unroll") for (int k = 0; k < 2; ++k) \
;         acc[ai][bj][m][n] = __builtin_amdgcn_mfma_f32_16x16x32_bf16(Bt[n][k], At[m][k], acc[ai][bj][m][n], 0, 0, 0); __builtin_amdgcn_s_setprio(0); } while (0)
; #define PG8_BAR __builtin_amdgcn_s_barrier()
; template <class Epi, class Sched, bool ALIGN_EPI = false, bool SP2 = false>
; __device__ __forceinline__ void gemm_phase(PG8_LAS unsigned char* lds, const Gemm g, const Sched& S, const Epi& E) {
;     ...
;             if constexpr (SP2) {
;             PG8_LDB(B0, 0, 0); PG8_LDB(B1, 0, 1); PG8_SCHED; PG8_LDA(At, 0, 0); PG8_STAGE(PG8_SA(1, 1), a1 + hstep, voffA);
;             PG8_WAIT_V(8); PG8_WAIT_L(0); PG8_BAR; PG8_MMA(0, 0, At, B0); PG8_MMA(0, 1, At, B1); PG8_BAR; PG8_SCHED;
;             PG8_LDA(At, 0, 1); PG8_STAGE(PG8_SB(0, 0), b2, voffB); PG8_STAGE(PG8_SB(0, 1), b2 + hstep, voffB); PG8_STAGE(PG8_SA(0, 0), a2, voffA);
;             PG8_WAIT_V(8); PG8_WAIT_L(0); PG8_BAR; PG8_MMA(1, 0, At, B0); PG8_MMA(1, 1, At, B1); PG8_BAR; PG8_SCHED;
;             PG8_LDB(B0, 1, 0); PG8_LDB(B1, 1, 1); PG8_SCHED; PG8_LDA(At, 1, 0); PG8_STAGE(PG8_SA(0, 1), a2 + hstep, voffA);
;             PG8_WAIT_V(8); PG8_WAIT_L(0); PG8_BAR; PG8_MMA(0, 0, At, B0); PG8_MMA(0, 1, At, B1); PG8_BAR; PG8_SCHED;
;             PG8_LDA(At, 1, 1); PG8_STAGE(PG8_SB(1, 0), b3, voffB); PG8_STAGE(PG8_SB(1, 1), b3 + hstep, voffB); PG8_STAGE(PG8_SA(1, 0), a3, voffA);
;             PG8_WAIT_V(8); PG8_WAIT_L(0); PG8_BAR; PG8_MMA(1, 0, At, B0); PG8_MMA(1, 1, At, B1); PG8_BAR; PG8_SCHED;
	s_setprio 1
	v_mfma_f32_16x16x32_bf16 v[78:81], v[164:167], v[196:199], 0
	v_mfma_f32_16x16x32_bf16 v[74:77], v[172:175], v[196:199], 0
	v_mfma_f32_16x16x32_bf16 v[62:65], v[164:167], v[216:219], 0
	v_mfma_f32_16x16x32_bf16 v[58:61], v[172:175], v[216:219], 0
	v_mfma_f32_16x16x32_bf16 v[46:49], v[164:167], v[224:227], 0
	v_mfma_f32_16x16x32_bf16 v[42:45], v[172:175], v[224:227], 0
	v_mfma_f32_16x16x32_bf16 v[30:33], v[164:167], v[232:235], 0
	v_mfma_f32_16x16x32_bf16 v[26:29], v[172:175], v[232:235], 0
	v_mfma_f32_16x16x32_bf16 v[78:81], v[168:171], v[200:203], v[78:81]
	v_mfma_f32_16x16x32_bf16 v[74:77], v[176:179], v[200:203], v[74:77]
	v_mfma_f32_16x16x32_bf16 v[62:65], v[168:171], v[220:223], v[62:65]
	v_mfma_f32_16x16x32_bf16 v[58:61], v[176:179], v[220:223], v[58:61]
	v_mfma_f32_16x16x32_bf16 v[46:49], v[168:171], v[228:231], v[46:49]
	v_mfma_f32_16x16x32_bf16 v[42:45], v[176:179], v[228:231], v[42:45]
	v_mfma_f32_16x16x32_bf16 v[30:33], v[168:171], v[236:239], v[30:33]
	v_mfma_f32_16x16x32_bf16 v[26:29], v[176:179], v[236:239], v[26:29]
	v_mfma_f32_16x16x32_bf16 v[70:73], v[180:183], v[196:199], 0
	v_mfma_f32_16x16x32_bf16 v[66:69], v[188:191], v[196:199], 0
	v_mfma_f32_16x16x32_bf16 v[54:57], v[180:183], v[216:219], 0
	v_mfma_f32_16x16x32_bf16 v[50:53], v[188:191], v[216:219], 0
	v_mfma_f32_16x16x32_bf16 v[38:41], v[180:183], v[224:227], 0
	v_mfma_f32_16x16x32_bf16 v[34:37], v[188:191], v[224:227], 0
	v_mfma_f32_16x16x32_bf16 v[22:25], v[180:183], v[232:235], 0
	v_mfma_f32_16x16x32_bf16 v[18:21], v[188:191], v[232:235], 0
	v_mfma_f32_16x16x32_bf16 v[70:73], v[184:187], v[200:203], v[70:73]
	v_mfma_f32_16x16x32_bf16 v[66:69], v[192:195], v[200:203], v[66:69]
	v_mfma_f32_16x16x32_bf16 v[54:57], v[184:187], v[220:223], v[54:57]
	v_mfma_f32_16x16x32_bf16 v[50:53], v[192:195], v[220:223], v[50:53]
	v_mfma_f32_16x16x32_bf16 v[38:41], v[184:187], v[228:231], v[38:41]
	v_mfma_f32_16x16x32_bf16 v[34:37], v[192:195], v[228:231], v[34:37]
	v_mfma_f32_16x16x32_bf16 v[22:25], v[184:187], v[236:239], v[22:25]
	v_mfma_f32_16x16x32_bf16 v[18:21], v[192:195], v[236:239], v[18:21]
	s_setprio 0
	s_barrier
	s_add_u32 s24, s24, 0x40000
	s_addc_u32 s25, s25, 0
	s_mov_b32 m0, s37
	s_nop 0
	global_load_lds_dwordx4 v146, s[24:25]
	s_mov_b32 m0, s38
	s_nop 0
	global_load_lds_dwordx4 v150, s[24:25]
	v_add_u32_e32 v176, s82, v160
	v_add_u32_e32 v192, s83, v160
	ds_read_b128 v[164:167], v176
	ds_read_b128 v[168:171], v176 offset:1024
	ds_read_b128 v[172:175], v176 offset:2048
	ds_read_b128 v[176:179], v176 offset:3072
	ds_read_b128 v[180:183], v192
	ds_read_b128 v[184:187], v192 offset:1024
	ds_read_b128 v[188:191], v192 offset:2048
	ds_read_b128 v[192:195], v192 offset:3072
	ds_read_b128 v[196:199], v163 offset:32768
	ds_read_b128 v[200:203], v163 offset:33792
	ds_read_b128 v[216:219], v163 offset:34816
	ds_read_b128 v[220:223], v163 offset:35840
	ds_read_b128 v[224:227], v163 offset:36864
	ds_read_b128 v[228:231], v163 offset:37888
	ds_read_b128 v[232:235], v163 offset:38912
	ds_read_b128 v[236:239], v163 offset:39936
	s_waitcnt vmcnt(8) lgkmcnt(0)
	s_barrier
	s_setprio 1
	v_mfma_f32_16x16x32_bf16 v[142:145], v[164:167], v[196:199], v[142:145]
	v_mfma_f32_16x16x32_bf16 v[138:141], v[172:175], v[196:199], v[138:141]
	v_mfma_f32_16x16x32_bf16 v[126:129], v[164:167], v[216:219], v[126:129]
	v_mfma_f32_16x16x32_bf16 v[122:125], v[172:175], v[216:219], v[122:125]
	v_mfma_f32_16x16x32_bf16 v[110:113], v[164:167], v[224:227], v[110:113]
	v_mfma_f32_16x16x32_bf16 v[106:109], v[172:175], v[224:227], v[106:109]
	v_mfma_f32_16x16x32_bf16 v[94:97], v[164:167], v[232:235], v[94:97]
	v_mfma_f32_16x16x32_bf16 v[90:93], v[172:175], v[232:235], v[90:93]
	v_mfma_f32_16x16x32_bf16 v[142:145], v[168:171], v[200:203], v[142:145]
	v_mfma_f32_16x16x32_bf16 v[138:141], v[176:179], v[200:203], v[138:141]
	v_mfma_f32_16x16x32_bf16 v[126:129], v[168:171], v[220:223], v[126:129]
	v_mfma_f32_16x16x32_bf16 v[122:125], v[176:179], v[220:223], v[122:125]
	v_mfma_f32_16x16x32_bf16 v[110:113], v[168:171], v[228:231], v[110:113]
	v_mfma_f32_16x16x32_bf16 v[106:109], v[176:179], v[228:231], v[106:109]
	v_mfma_f32_16x16x32_bf16 v[94:97], v[168:171], v[236:239], v[94:97]
	v_mfma_f32_16x16x32_bf16 v[90:93], v[176:179], v[236:239], v[90:93]
	v_mfma_f32_16x16x32_bf16 v[134:137], v[180:183], v[196:199], v[134:137]
	v_mfma_f32_16x16x32_bf16 v[130:133], v[188:191], v[196:199], v[130:133]
	v_mfma_f32_16x16x32_bf16 v[118:121], v[180:183], v[216:219], v[118:121]
	v_mfma_f32_16x16x32_bf16 v[114:117], v[188:191], v[216:219], v[114:117]
	v_mfma_f32_16x16x32_bf16 v[102:105], v[180:183], v[224:227], v[102:105]
	v_mfma_f32_16x16x32_bf16 v[98:101], v[188:191], v[224:227], v[98:101]
	v_mfma_f32_16x16x32_bf16 v[86:89], v[180:183], v[232:235], v[86:89]
	v_mfma_f32_16x16x32_bf16 v[82:85], v[188:191], v[232:235], v[82:85]
	v_mfma_f32_16x16x32_bf16 v[134:137], v[184:187], v[200:203], v[134:137]
	v_mfma_f32_16x16x32_bf16 v[130:133], v[192:195], v[200:203], v[130:133]
	v_mfma_f32_16x16x32_bf16 v[118:121], v[184:187], v[220:223], v[118:121]
	v_mfma_f32_16x16x32_bf16 v[114:117], v[192:195], v[220:223], v[114:117]
	v_mfma_f32_16x16x32_bf16 v[102:105], v[184:187], v[228:231], v[102:105]
	v_mfma_f32_16x16x32_bf16 v[98:101], v[192:195], v[228:231], v[98:101]
	v_mfma_f32_16x16x32_bf16 v[86:89], v[184:187], v[236:239], v[86:89]
	v_mfma_f32_16x16x32_bf16 v[82:85], v[192:195], v[236:239], v[82:85]
	s_setprio 0
	s_barrier
; #define PG8_STAGE(bufoff, gbase, voff) do { _Pragma("unroll") for (int _i = 0; _i < 2; ++_i) \
;         __builtin_amdgcn_global_load_lds((const unsigned*)((const char*)(gbase) + (voff)[_i]), (PG8_LAS unsigned*)(lds + (bufoff) + ldsw + _i * 8192), 16, 0, 0); } while (0)
; #define PG8_LDA(dst, b, h) do { _Pragma("unroll") for (int m = 0; m < 4; ++m) _Pragma("unroll") for (int k = 0; k < 2; ++k) dst[m][k] = *(const PG8_LAS bf16x8*)(lds + PG8_SA(b, h) + aoff + m * 2048 + k * 1024); } while (0)
; #define PG8_WAIT_V(n) asm volatile("s_waitcnt vmcnt(" #n ")" ::: "memory")
; #define PG8_WAIT_L(n) asm volatile("s_waitcnt lgkmcnt(" #n ")" ::: "memory")
; #define PG8_BAR __builtin_amdgcn_s_barrier()
; template <class Epi, class Sched, bool ALIGN_EPI = false, bool SP2 = false>
; __device__ __forceinline__ void gemm_phase(PG8_LAS unsigned char* lds, const Gemm g, const Sched& S, const Epi& E) {
;     ...
;         for (int t = t_lo; t < t_hi; t += 2) {
;             const bool last = (t == nt - 2);
;             const char* a1 = cA + (size_t)(t + 1) * kstep;
;             const char* a2 = last ? nA : cA + (size_t)(t + 2) * kstep; const char* b2 = last ? nB : cB + (size_t)(t + 2) * kstep;
;             const char* a3 = a2 + kstep; const char* b3 = b2 + kstep;
;             if (last && has_next) S.a_ready_inloop(nxt, ui + 1);
;             if constexpr (SP2) {
;             PG8_LDB(B0, 0, 0); PG8_LDB(B1, 0, 1); PG8_SCHED; PG8_LDA(At, 0, 0); PG8_STAGE(PG8_SA(1, 1), a1 + hstep, voffA);
;             PG8_WAIT_V(8); PG8_WAIT_L(0); PG8_BAR; PG8_MMA(0, 0, At, B0); PG8_MMA(0, 1, At, B1); PG8_BAR; PG8_SCHED;
;             PG8_LDA(At, 0, 1); PG8_STAGE(PG8_SB(0, 0), b2, voffB); PG8_STAGE(PG8_SB(0, 1), b2 + hstep, voffB); PG8_STAGE(PG8_SA(0, 0), a2, voffA);
;             PG8_WAIT_V(8); PG8_WAIT_L(0); PG8_BAR; PG8_MMA(1, 0, At, B0); PG8_MMA(1, 1, At, B1); PG8_BAR; PG8_SCHED;
;             PG8_LDB(B0, 1, 0); PG8_LDB(B1, 1, 1); PG8_SCHED; PG8_LDA(At, 1, 0); PG8_STAGE(PG8_SA(0, 1), a2 + hstep, voffA);
;             PG8_WAIT_V(8); PG8_WAIT_L(0); PG8_BAR; PG8_MMA(0, 0, At, B0); PG8_MMA(0, 1, At, B1); PG8_BAR; PG8_SCHED;
;             PG8_LDA(At, 1, 1); PG8_STAGE(PG8_SB(1, 0), b3, voffB); PG8_STAGE(PG8_SB(1, 1), b3 + hstep, voffB); PG8_STAGE(PG8_SA(1, 0), a3, voffA);
;             PG8_WAIT_V(8); PG8_WAIT_L(0); PG8_BAR; PG8_MMA(1, 0, At, B0); PG8_MMA(1, 1, At, B1); PG8_BAR; PG8_SCHED;
	s_add_i32 s24, s82, s34
	s_mov_b32 m0, s24
	s_nop 0
	global_load_lds_dwordx4 v148, s[98:99]
	s_add_i32 m0, s24, 0x2000
	s_add_u32 s22, s22, 0x40080
	s_addc_u32 s23, s23, 0
	s_add_i32 s24, s83, s34
	global_load_lds_dwordx4 v152, s[98:99]
	s_mov_b32 m0, s24
	s_nop 0
	global_load_lds_dwordx4 v148, s[22:23]
	s_add_i32 m0, s24, 0x2000
	s_nop 0
	global_load_lds_dwordx4 v152, s[22:23]
	s_mov_b32 m0, s39
	s_nop 0
	global_load_lds_dwordx4 v146, s[100:101]
	s_mov_b32 m0, s42
	s_nop 0
	global_load_lds_dwordx4 v150, s[100:101]
	ds_read_b128 v[196:199], v163 offset:49152
	ds_read_b128 v[200:203], v163 offset:50176
	ds_read_b128 v[216:219], v163 offset:51200
	ds_read_b128 v[220:223], v163 offset:52224
	ds_read_b128 v[224:227], v163 offset:53248
	ds_read_b128 v[228:231], v163 offset:54272
	ds_read_b128 v[232:235], v163 offset:55296
	ds_read_b128 v[236:239], v163 offset:56320
	s_waitcnt vmcnt(8) lgkmcnt(0)
	s_barrier
	s_setprio 1
	v_mfma_f32_16x16x32_bf16 v[78:81], v[164:167], v[196:199], v[78:81]
	v_mfma_f32_16x16x32_bf16 v[74:77], v[172:175], v[196:199], v[74:77]
	v_mfma_f32_16x16x32_bf16 v[62:65], v[164:167], v[216:219], v[62:65]
	v_mfma_f32_16x16x32_bf16 v[58:61], v[172:175], v[216:219], v[58:61]
	v_mfma_f32_16x16x32_bf16 v[46:49], v[164:167], v[224:227], v[46:49]
	v_mfma_f32_16x16x32_bf16 v[42:45], v[172:175], v[224:227], v[42:45]
	v_mfma_f32_16x16x32_bf16 v[30:33], v[164:167], v[232:235], v[30:33]
	v_mfma_f32_16x16x32_bf16 v[26:29], v[172:175], v[232:235], v[26:29]
	v_mfma_f32_16x16x32_bf16 v[78:81], v[168:171], v[200:203], v[78:81]
	v_mfma_f32_16x16x32_bf16 v[74:77], v[176:179], v[200:203], v[74:77]
	v_mfma_f32_16x16x32_bf16 v[62:65], v[168:171], v[220:223], v[62:65]
	v_mfma_f32_16x16x32_bf16 v[58:61], v[176:179], v[220:223], v[58:61]
	v_mfma_f32_16x16x32_bf16 v[46:49], v[168:171], v[228:231], v[46:49]
	v_mfma_f32_16x16x32_bf16 v[42:45], v[176:179], v[228:231], v[42:45]
	v_mfma_f32_16x16x32_bf16 v[30:33], v[168:171], v[236:239], v[30:33]
	v_mfma_f32_16x16x32_bf16 v[26:29], v[176:179], v[236:239], v[26:29]
	v_mfma_f32_16x16x32_bf16 v[70:73], v[180:183], v[196:199], v[70:73]
	v_mfma_f32_16x16x32_bf16 v[66:69], v[188:191], v[196:199], v[66:69]
	v_mfma_f32_16x16x32_bf16 v[54:57], v[180:183], v[216:219], v[54:57]
	v_mfma_f32_16x16x32_bf16 v[50:53], v[188:191], v[216:219], v[50:53]
	v_mfma_f32_16x16x32_bf16 v[38:41], v[180:183], v[224:227], v[38:41]
	v_mfma_f32_16x16x32_bf16 v[34:37], v[188:191], v[224:227], v[34:37]
	v_mfma_f32_16x16x32_bf16 v[22:25], v[180:183], v[232:235], v[22:25]
	v_mfma_f32_16x16x32_bf16 v[18:21], v[188:191], v[232:235], v[18:21]
	v_mfma_f32_16x16x32_bf16 v[70:73], v[184:187], v[200:203], v[70:73]
	v_mfma_f32_16x16x32_bf16 v[66:69], v[192:195], v[200:203], v[66:69]
	v_mfma_f32_16x16x32_bf16 v[54:57], v[184:187], v[220:223], v[54:57]
	v_mfma_f32_16x16x32_bf16 v[50:53], v[192:195], v[220:223], v[50:53]
	v_mfma_f32_16x16x32_bf16 v[38:41], v[184:187], v[228:231], v[38:41]
	v_mfma_f32_16x16x32_bf16 v[34:37], v[192:195], v[228:231], v[34:37]
	v_mfma_f32_16x16x32_bf16 v[22:25], v[184:187], v[236:239], v[22:25]
	v_mfma_f32_16x16x32_bf16 v[18:21], v[192:195], v[236:239], v[18:21]
	s_setprio 0
	s_barrier
	s_add_i32 s64, s64, 2
	s_add_u32 s20, s20, 0x100
	s_addc_u32 s21, s21, 0
	s_add_u32 s62, s62, 0x100
	s_addc_u32 s63, s63, 0
.LBB0_762:
	s_add_u32 s22, s20, 0xfffc0080
	s_addc_u32 s23, s21, -1
	s_cmp_eq_u32 s64, 12
	s_cselect_b32 s25, s13, s23
	s_cselect_b32 s24, s52, s22
	s_cselect_b32 s23, s15, s63
	s_cselect_b32 s22, s53, s62
	s_add_u32 s98, s22, s46
	s_addc_u32 s99, s23, s47
	s_add_u32 s100, s24, s46
	s_addc_u32 s101, s25, s47
	s_add_i32 m0, s35, 0xc000
	s_nop 0
	global_load_lds_dwordx4 v154, s[20:21]
	s_add_i32 m0, s35, 0xe000
	s_nop 0
	global_load_lds_dwordx4 v156, s[20:21]
	v_add_u32_e32 v158, s90, v160
	ds_read_b128 v[164:167], v158
	ds_read_b128 v[168:171], v158 offset:1024
	ds_read_b128 v[172:175], v158 offset:2048
	ds_read_b128 v[176:179], v158 offset:3072
	v_add_u32_e32 v158, s81, v160
	ds_read_b128 v[180:183], v158
	ds_read_b128 v[184:187], v158 offset:1024
	ds_read_b128 v[188:191], v158 offset:2048
	ds_read_b128 v[192:195], v158 offset:3072
	ds_read_b128 v[196:199], v163
	ds_read_b128 v[200:203], v163 offset:1024
	ds_read_b128 v[216:219], v163 offset:2048
	ds_read_b128 v[220:223], v163 offset:3072
	ds_read_b128 v[224:227], v163 offset:4096
	ds_read_b128 v[228:231], v163 offset:5120
	ds_read_b128 v[232:235], v163 offset:6144
	ds_read_b128 v[236:239], v163 offset:7168
	s_waitcnt vmcnt(8) lgkmcnt(0)
	s_barrier
; #define PG8_STAGE(bufoff, gbase, voff) do { _Pragma("unroll") for (int _i = 0; _i < 2; ++_i) \
;         __builtin_amdgcn_global_load_lds((const unsigned*)((const char*)(gbase) + (voff)[_i]), (PG8_LAS unsigned*)(lds + (bufoff) + ldsw + _i * 8192), 16, 0, 0); } while (0)
; #define PG8_LDA(dst, b, h) do { _Pragma("unroll") for (int m = 0; m < 4; ++m) _Pragma("unroll") for (int k = 0; k < 2; ++k) dst[m][k] = *(const PG8_LAS bf16x8*)(lds + PG8_SA(b, h) + aoff + m * 2048 + k * 1024); } while (0)
; #define PG8_LDB(dst, b, h) do { _Pragma("unroll") for (int n = 0; n < 2; ++n) _Pragma("unroll") for (int k = 0; k < 2; ++k) dst[n][k] = *(const PG8_LAS bf16x8*)(lds + PG8_SB(b, h) + boff + n * 2048 + k * 1024); } while (0)
; #define PG8_MMA(ai, bj, At, Bt) do { __builtin_amdgcn_s_setprio(1); _Pragma("unroll") for (int m = 0; m < 4; ++m) _Pragma("unroll") for (int n = 0; n < 2; ++n) _Pragma("unroll") for (int k = 0; k < 2; ++k) \
;         acc[ai][bj][m][n] = __builtin_amdgcn_mfma_f32_16x16x32_bf16(Bt[n][k], At[m][k], acc[ai][bj][m][n], 0, 0, 0); __builtin_amdgcn_s_setprio(0); } while (0)
; #define PG8_BAR __builtin_amdgcn_s_barrier()
; template <class Epi, class Sched, bool ALIGN_EPI = false, bool SP2 = false>
; __device__ __forceinline__ void gemm_phase(PG8_LAS unsigned char* lds, const Gemm g, const Sched& S, const Epi& E) {
;     ...
;             if constexpr (SP2) {
;             PG8_LDB(B0, 0, 0); PG8_LDB(B1, 0, 1); PG8_SCHED; PG8_LDA(At, 0, 0); PG8_STAGE(PG8_SA(1, 1), a1 + hstep, voffA);
;             PG8_WAIT_V(8); PG8_WAIT_L(0); PG8_BAR; PG8_MMA(0, 0, At, B0); PG8_MMA(0, 1, At, B1); PG8_BAR; PG8_SCHED;
;             PG8_LDA(At, 0, 1); PG8_STAGE(PG8_SB(0, 0), b2, voffB); PG8_STAGE(PG8_SB(0, 1), b2 + hstep, voffB); PG8_STAGE(PG8_SA(0, 0), a2, voffA);
;             PG8_WAIT_V(8); PG8_WAIT_L(0); PG8_BAR; PG8_MMA(1, 0, At, B0); PG8_MMA(1, 1, At, B1); PG8_BAR; PG8_SCHED;
;             PG8_LDB(B0, 1, 0); PG8_LDB(B1, 1, 1); PG8_SCHED; PG8_LDA(At, 1, 0); PG8_STAGE(PG8_SA(0, 1), a2 + hstep, voffA);
;             PG8_WAIT_V(8); PG8_WAIT_L(0); PG8_BAR; PG8_MMA(0, 0, At, B0); PG8_MMA(0, 1, At, B1); PG8_BAR; PG8_SCHED;
;             PG8_LDA(At, 1, 1); PG8_STAGE(PG8_SB(1, 0), b3, voffB); PG8_STAGE(PG8_SB(1, 1), b3 + hstep, voffB); PG8_STAGE(PG8_SA(1, 0), a3, voffA);
;             PG8_WAIT_V(8); PG8_WAIT_L(0); PG8_BAR; PG8_MMA(1, 0, At, B0); PG8_MMA(1, 1, At, B1); PG8_BAR; PG8_SCHED;
	s_setprio 1
	v_mfma_f32_16x16x32_bf16 v[142:145], v[164:167], v[196:199], v[142:145]
	v_mfma_f32_16x16x32_bf16 v[138:141], v[172:175], v[196:199], v[138:141]
	v_mfma_f32_16x16x32_bf16 v[126:129], v[164:167], v[216:219], v[126:129]
	v_mfma_f32_16x16x32_bf16 v[122:125], v[172:175], v[216:219], v[122:125]
	v_mfma_f32_16x16x32_bf16 v[110:113], v[164:167], v[224:227], v[110:113]
	v_mfma_f32_16x16x32_bf16 v[106:109], v[172:175], v[224:227], v[106:109]
	v_mfma_f32_16x16x32_bf16 v[94:97], v[164:167], v[232:235], v[94:97]
	v_mfma_f32_16x16x32_bf16 v[90:93], v[172:175], v[232:235], v[90:93]
	v_mfma_f32_16x16x32_bf16 v[142:145], v[168:171], v[200:203], v[142:145]
	v_mfma_f32_16x16x32_bf16 v[138:141], v[176:179], v[200:203], v[138:141]
	v_mfma_f32_16x16x32_bf16 v[126:129], v[168:171], v[220:223], v[126:129]
	v_mfma_f32_16x16x32_bf16 v[122:125], v[176:179], v[220:223], v[122:125]
	v_mfma_f32_16x16x32_bf16 v[110:113], v[168:171], v[228:231], v[110:113]
	v_mfma_f32_16x16x32_bf16 v[106:109], v[176:179], v[228:231], v[106:109]
	v_mfma_f32_16x16x32_bf16 v[94:97], v[168:171], v[236:239], v[94:97]
	v_mfma_f32_16x16x32_bf16 v[90:93], v[176:179], v[236:239], v[90:93]
	v_mfma_f32_16x16x32_bf16 v[134:137], v[180:183], v[196:199], v[134:137]
	v_mfma_f32_16x16x32_bf16 v[130:133], v[188:191], v[196:199], v[130:133]
	v_mfma_f32_16x16x32_bf16 v[118:121], v[180:183], v[216:219], v[118:121]
	v_mfma_f32_16x16x32_bf16 v[114:117], v[188:191], v[216:219], v[114:117]
	v_mfma_f32_16x16x32_bf16 v[102:105], v[180:183], v[224:227], v[102:105]
	v_mfma_f32_16x16x32_bf16 v[98:101], v[188:191], v[224:227], v[98:101]
	v_mfma_f32_16x16x32_bf16 v[86:89], v[180:183], v[232:235], v[86:89]
	v_mfma_f32_16x16x32_bf16 v[82:85], v[188:191], v[232:235], v[82:85]
	v_mfma_f32_16x16x32_bf16 v[134:137], v[184:187], v[200:203], v[134:137]
	v_mfma_f32_16x16x32_bf16 v[130:133], v[192:195], v[200:203], v[130:133]
	v_mfma_f32_16x16x32_bf16 v[118:121], v[184:187], v[220:223], v[118:121]
	v_mfma_f32_16x16x32_bf16 v[114:117], v[192:195], v[220:223], v[114:117]
	v_mfma_f32_16x16x32_bf16 v[102:105], v[184:187], v[228:231], v[102:105]
	v_mfma_f32_16x16x32_bf16 v[98:101], v[192:195], v[228:231], v[98:101]
	v_mfma_f32_16x16x32_bf16 v[86:89], v[184:187], v[236:239], v[86:89]
	v_mfma_f32_16x16x32_bf16 v[82:85], v[192:195], v[236:239], v[82:85]
	s_setprio 0
	s_barrier
	s_add_i32 s65, s90, s34
	s_mov_b32 m0, s65
	s_nop 0
	global_load_lds_dwordx4 v148, s[22:23]
	s_add_i32 m0, s65, 0x2000
	s_add_u32 s66, s22, 0x40000
	s_addc_u32 s67, s23, 0
	s_add_i32 s65, s81, s34
	global_load_lds_dwordx4 v152, s[22:23]
	s_mov_b32 m0, s65
	s_nop 0
	global_load_lds_dwordx4 v148, s[66:67]
	s_add_i32 m0, s65, 0x2000
	s_nop 0
	global_load_lds_dwordx4 v152, s[66:67]
	s_mov_b32 m0, s35
	s_nop 0
	global_load_lds_dwordx4 v146, s[24:25]
	s_mov_b32 m0, s36
	s_nop 0
	global_load_lds_dwordx4 v150, s[24:25]
	ds_read_b128 v[196:199], v163 offset:16384
	ds_read_b128 v[200:203], v163 offset:17408
	ds_read_b128 v[216:219], v163 offset:18432
	ds_read_b128 v[220:223], v163 offset:19456
	ds_read_b128 v[224:227], v163 offset:20480
	ds_read_b128 v[228:231], v163 offset:21504
	ds_read_b128 v[232:235], v163 offset:22528
	ds_read_b128 v[236:239], v163 offset:23552
	s_waitcnt vmcnt(8) lgkmcnt(0)
	s_barrier
	s_setprio 1
	v_mfma_f32_16x16x32_bf16 v[78:81], v[164:167], v[196:199], v[78:81]
	v_mfma_f32_16x16x32_bf16 v[74:77], v[172:175], v[196:199], v[74:77]
	v_mfma_f32_16x16x32_bf16 v[62:65], v[164:167], v[216:219], v[62:65]
	v_mfma_f32_16x16x32_bf16 v[58:61], v[172:175], v[216:219], v[58:61]
	v_mfma_f32_16x16x32_bf16 v[46:49], v[164:167], v[224:227], v[46:49]
	v_mfma_f32_16x16x32_bf16 v[42:45], v[172:175], v[224:227], v[42:45]
	v_mfma_f32_16x16x32_bf16 v[30:33], v[164:167], v[232:235], v[30:33]
	v_mfma_f32_16x16x32_bf16 v[26:29], v[172:175], v[232:235], v[26:29]
	v_mfma_f32_16x16x32_bf16 v[78:81], v[168:171], v[200:203], v[78:81]
	v_mfma_f32_16x16x32_bf16 v[74:77], v[176:179], v[200:203], v[74:77]
	v_mfma_f32_16x16x32_bf16 v[62:65], v[168:171], v[220:223], v[62:65]
	v_mfma_f32_16x16x32_bf16 v[58:61], v[176:179], v[220:223], v[58:61]
	v_mfma_f32_16x16x32_bf16 v[46:49], v[168:171], v[228:231], v[46:49]
	v_mfma_f32_16x16x32_bf16 v[42:45], v[176:179], v[228:231], v[42:45]
	v_mfma_f32_16x16x32_bf16 v[30:33], v[168:171], v[236:239], v[30:33]
	v_mfma_f32_16x16x32_bf16 v[26:29], v[176:179], v[236:239], v[26:29]
	v_mfma_f32_16x16x32_bf16 v[70:73], v[180:183], v[196:199], v[70:73]
	v_mfma_f32_16x16x32_bf16 v[66:69], v[188:191], v[196:199], v[66:69]
	v_mfma_f32_16x16x32_bf16 v[54:57], v[180:183], v[216:219], v[54:57]
	v_mfma_f32_16x16x32_bf16 v[50:53], v[188:191], v[216:219], v[50:53]
	v_mfma_f32_16x16x32_bf16 v[38:41], v[180:183], v[224:227], v[38:41]
	v_mfma_f32_16x16x32_bf16 v[34:37], v[188:191], v[224:227], v[34:37]
	v_mfma_f32_16x16x32_bf16 v[22:25], v[180:183], v[232:235], v[22:25]
	v_mfma_f32_16x16x32_bf16 v[18:21], v[188:191], v[232:235], v[18:21]
	v_mfma_f32_16x16x32_bf16 v[70:73], v[184:187], v[200:203], v[70:73]
	v_mfma_f32_16x16x32_bf16 v[66:69], v[192:195], v[200:203], v[66:69]
	v_mfma_f32_16x16x32_bf16 v[54:57], v[184:187], v[220:223], v[54:57]
	v_mfma_f32_16x16x32_bf16 v[50:53], v[192:195], v[220:223], v[50:53]
	v_mfma_f32_16x16x32_bf16 v[38:41], v[184:187], v[228:231], v[38:41]
	v_mfma_f32_16x16x32_bf16 v[34:37], v[192:195], v[228:231], v[34:37]
	v_mfma_f32_16x16x32_bf16 v[22:25], v[184:187], v[236:239], v[22:25]
	v_mfma_f32_16x16x32_bf16 v[18:21], v[192:195], v[236:239], v[18:21]
	s_setprio 0
	s_barrier
; #define PG8_STAGE(bufoff, gbase, voff) do { _Pragma("unroll") for (int _i = 0; _i < 2; ++_i) \
;         __builtin_amdgcn_global_load_lds((const unsigned*)((const char*)(gbase) + (voff)[_i]), (PG8_LAS unsigned*)(lds + (bufoff) + ldsw + _i * 8192), 16, 0, 0); } while (0)
; #define PG8_LDA(dst, b, h) do { _Pragma("unroll") for (int m = 0; m < 4; ++m) _Pragma("unroll") for (int k = 0; k < 2; ++k) dst[m][k] = *(const PG8_LAS bf16x8*)(lds + PG8_SA(b, h) + aoff + m * 2048 + k * 1024); } while (0)
; #define PG8_LDB(dst, b, h) do { _Pragma("unroll") for (int n = 0; n < 2; ++n) _Pragma("unroll") for (int k = 0; k < 2; ++k) dst[n][k] = *(const PG8_LAS bf16x8*)(lds + PG8_SB(b, h) + boff + n * 2048 + k * 1024); } while (0)
; #define PG8_MMA(ai, bj, At, Bt) do { __builtin_amdgcn_s_setprio(1); _Pragma("unroll") for (int m = 0; m < 4; ++m) _Pragma("unroll") for (int n = 0; n < 2; ++n) _Pragma("unroll") for (int k = 0; k < 2; ++k) \
;         acc[ai][bj][m][n] = __builtin_amdgcn_mfma_f32_16x16x32_bf16(Bt[n][k], At[m][k], acc[ai][bj][m][n], 0, 0, 0); __builtin_amdgcn_s_setprio(0); } while (0)
; #define PG8_BAR __builtin_amdgcn_s_barrier()
; template <class Epi, class Sched, bool ALIGN_EPI = false, bool SP2 = false>
; __device__ __forceinline__ void gemm_phase(PG8_LAS unsigned char* lds, const Gemm g, const Sched& S, const Epi& E) {
;     ...
;             if constexpr (SP2) {
;             PG8_LDB(B0, 0, 0); PG8_LDB(B1, 0, 1); PG8_SCHED; PG8_LDA(At, 0, 0); PG8_STAGE(PG8_SA(1, 1), a1 + hstep, voffA);
;             PG8_WAIT_V(8); PG8_WAIT_L(0); PG8_BAR; PG8_MMA(0, 0, At, B0); PG8_MMA(0, 1, At, B1); PG8_BAR; PG8_SCHED;
;             PG8_LDA(At, 0, 1); PG8_STAGE(PG8_SB(0, 0), b2, voffB); PG8_STAGE(PG8_SB(0, 1), b2 + hstep, voffB); PG8_STAGE(PG8_SA(0, 0), a2, voffA);
;             PG8_WAIT_V(8); PG8_WAIT_L(0); PG8_BAR; PG8_MMA(1, 0, At, B0); PG8_MMA(1, 1, At, B1); PG8_BAR; PG8_SCHED;
;             PG8_LDB(B0, 1, 0); PG8_LDB(B1, 1, 1); PG8_SCHED; PG8_LDA(At, 1, 0); PG8_STAGE(PG8_SA(0, 1), a2 + hstep, voffA);
;             PG8_WAIT_V(8); PG8_WAIT_L(0); PG8_BAR; PG8_MMA(0, 0, At, B0); PG8_MMA(0, 1, At, B1); PG8_BAR; PG8_SCHED;
;             PG8_LDA(At, 1, 1); PG8_STAGE(PG8_SB(1, 0), b3, voffB); PG8_STAGE(PG8_SB(1, 1), b3 + hstep, voffB); PG8_STAGE(PG8_SA(1, 0), a3, voffA);
;             PG8_WAIT_V(8); PG8_WAIT_L(0); PG8_BAR; PG8_MMA(1, 0, At, B0); PG8_MMA(1, 1, At, B1); PG8_BAR; PG8_SCHED;
	s_add_u32 s24, s24, 0x40000
	s_addc_u32 s25, s25, 0
	s_mov_b32 m0, s37
	s_nop 0
	global_load_lds_dwordx4 v146, s[24:25]
	s_mov_b32 m0, s38
	s_nop 0
	global_load_lds_dwordx4 v150, s[24:25]
	v_add_u32_e32 v176, s82, v160
	v_add_u32_e32 v192, s83, v160
	ds_read_b128 v[164:167], v176
	ds_read_b128 v[168:171], v176 offset:1024
	ds_read_b128 v[172:175], v176 offset:2048
	ds_read_b128 v[176:179], v176 offset:3072
	ds_read_b128 v[180:183], v192
	ds_read_b128 v[184:187], v192 offset:1024
	ds_read_b128 v[188:191], v192 offset:2048
	ds_read_b128 v[192:195], v192 offset:3072
	ds_read_b128 v[196:199], v163 offset:32768
	ds_read_b128 v[200:203], v163 offset:33792
	ds_read_b128 v[216:219], v163 offset:34816
	ds_read_b128 v[220:223], v163 offset:35840
	ds_read_b128 v[224:227], v163 offset:36864
	ds_read_b128 v[228:231], v163 offset:37888
	ds_read_b128 v[232:235], v163 offset:38912
	ds_read_b128 v[236:239], v163 offset:39936
	s_waitcnt vmcnt(8) lgkmcnt(0)
	s_barrier
	s_setprio 1
	v_mfma_f32_16x16x32_bf16 v[142:145], v[164:167], v[196:199], v[142:145]
	v_mfma_f32_16x16x32_bf16 v[138:141], v[172:175], v[196:199], v[138:141]
	v_mfma_f32_16x16x32_bf16 v[126:129], v[164:167], v[216:219], v[126:129]
	v_mfma_f32_16x16x32_bf16 v[122:125], v[172:175], v[216:219], v[122:125]
	v_mfma_f32_16x16x32_bf16 v[110:113], v[164:167], v[224:227], v[110:113]
	v_mfma_f32_16x16x32_bf16 v[106:109], v[172:175], v[224:227], v[106:109]
	v_mfma_f32_16x16x32_bf16 v[94:97], v[164:167], v[232:235], v[94:97]
	v_mfma_f32_16x16x32_bf16 v[90:93], v[172:175], v[232:235], v[90:93]
	v_mfma_f32_16x16x32_bf16 v[142:145], v[168:171], v[200:203], v[142:145]
	v_mfma_f32_16x16x32_bf16 v[138:141], v[176:179], v[200:203], v[138:141]
	v_mfma_f32_16x16x32_bf16 v[126:129], v[168:171], v[220:223], v[126:129]
	v_mfma_f32_16x16x32_bf16 v[122:125], v[176:179], v[220:223], v[122:125]
	v_mfma_f32_16x16x32_bf16 v[110:113], v[168:171], v[228:231], v[110:113]
	v_mfma_f32_16x16x32_bf16 v[106:109], v[176:179], v[228:231], v[106:109]
	v_mfma_f32_16x16x32_bf16 v[94:97], v[168:171], v[236:239], v[94:97]
	v_mfma_f32_16x16x32_bf16 v[90:93], v[176:179], v[236:239], v[90:93]
	v_mfma_f32_16x16x32_bf16 v[134:137], v[180:183], v[196:199], v[134:137]
	v_mfma_f32_16x16x32_bf16 v[130:133], v[188:191], v[196:199], v[130:133]
	v_mfma_f32_16x16x32_bf16 v[118:121], v[180:183], v[216:219], v[118:121]
	v_mfma_f32_16x16x32_bf16 v[114:117], v[188:191], v[216:219], v[114:117]
	v_mfma_f32_16x16x32_bf16 v[102:105], v[180:183], v[224:227], v[102:105]
	v_mfma_f32_16x16x32_bf16 v[98:101], v[188:191], v[224:227], v[98:101]
	v_mfma_f32_16x16x32_bf16 v[86:89], v[180:183], v[232:235], v[86:89]
	v_mfma_f32_16x16x32_bf16 v[82:85], v[188:191], v[232:235], v[82:85]
	v_mfma_f32_16x16x32_bf16 v[134:137], v[184:187], v[200:203], v[134:137]
	v_mfma_f32_16x16x32_bf16 v[130:133], v[192:195], v[200:203], v[130:133]
	v_mfma_f32_16x16x32_bf16 v[118:121], v[184:187], v[220:223], v[118:121]
	v_mfma_f32_16x16x32_bf16 v[114:117], v[192:195], v[220:223], v[114:117]
	v_mfma_f32_16x16x32_bf16 v[102:105], v[184:187], v[228:231], v[102:105]
	v_mfma_f32_16x16x32_bf16 v[98:101], v[192:195], v[228:231], v[98:101]
	v_mfma_f32_16x16x32_bf16 v[86:89], v[184:187], v[236:239], v[86:89]
	v_mfma_f32_16x16x32_bf16 v[82:85], v[192:195], v[236:239], v[82:85]
	s_setprio 0
	s_barrier
	s_add_i32 s24, s82, s34
	s_mov_b32 m0, s24
	s_nop 0
	global_load_lds_dwordx4 v148, s[98:99]
	s_add_i32 m0, s24, 0x2000
	s_add_u32 s22, s22, 0x40080
	s_addc_u32 s23, s23, 0
	s_add_i32 s24, s83, s34
	global_load_lds_dwordx4 v152, s[98:99]
	s_mov_b32 m0, s24
	s_nop 0
	global_load_lds_dwordx4 v148, s[22:23]
	s_add_i32 m0, s24, 0x2000
	s_nop 0
	global_load_lds_dwordx4 v152, s[22:23]
	s_mov_b32 m0, s39
	s_nop 0
	global_load_lds_dwordx4 v146, s[100:101]
	s_mov_b32 m0, s42
	s_nop 0
	global_load_lds_dwordx4 v150, s[100:101]
	ds_read_b128 v[196:199], v163 offset:49152
	ds_read_b128 v[200:203], v163 offset:50176
	ds_read_b128 v[216:219], v163 offset:51200
	ds_read_b128 v[220:223], v163 offset:52224
	ds_read_b128 v[224:227], v163 offset:53248
	ds_read_b128 v[228:231], v163 offset:54272
	ds_read_b128 v[232:235], v163 offset:55296
	ds_read_b128 v[236:239], v163 offset:56320
	s_waitcnt vmcnt(8) lgkmcnt(0)
	s_barrier
	s_setprio 1
	v_mfma_f32_16x16x32_bf16 v[78:81], v[164:167], v[196:199], v[78:81]
	v_mfma_f32_16x16x32_bf16 v[74:77], v[172:175], v[196:199], v[74:77]
	v_mfma_f32_16x16x32_bf16 v[62:65], v[164:167], v[216:219], v[62:65]
	v_mfma_f32_16x16x32_bf16 v[58:61], v[172:175], v[216:219], v[58:61]
	v_mfma_f32_16x16x32_bf16 v[46:49], v[164:167], v[224:227], v[46:49]
	v_mfma_f32_16x16x32_bf16 v[42:45], v[172:175], v[224:227], v[42:45]
	v_mfma_f32_16x16x32_bf16 v[30:33], v[164:167], v[232:235], v[30:33]
	v_mfma_f32_16x16x32_bf16 v[26:29], v[172:175], v[232:235], v[26:29]
	v_mfma_f32_16x16x32_bf16 v[78:81], v[168:171], v[200:203], v[78:81]
	v_mfma_f32_16x16x32_bf16 v[74:77], v[176:179], v[200:203], v[74:77]
	v_mfma_f32_16x16x32_bf16 v[62:65], v[168:171], v[220:223], v[62:65]
	v_mfma_f32_16x16x32_bf16 v[58:61], v[176:179], v[220:223], v[58:61]
	v_mfma_f32_16x16x32_bf16 v[46:49], v[168:171], v[228:231], v[46:49]
	v_mfma_f32_16x16x32_bf16 v[42:45], v[176:179], v[228:231], v[42:45]
	v_mfma_f32_16x16x32_bf16 v[30:33], v[168:171], v[236:239], v[30:33]
	v_mfma_f32_16x16x32_bf16 v[26:29], v[176:179], v[236:239], v[26:29]
	v_mfma_f32_16x16x32_bf16 v[70:73], v[180:183], v[196:199], v[70:73]
	v_mfma_f32_16x16x32_bf16 v[66:69], v[188:191], v[196:199], v[66:69]
	v_mfma_f32_16x16x32_bf16 v[54:57], v[180:183], v[216:219], v[54:57]
	v_mfma_f32_16x16x32_bf16 v[50:53], v[188:191], v[216:219], v[50:53]
	v_mfma_f32_16x16x32_bf16 v[38:41], v[180:183], v[224:227], v[38:41]
	v_mfma_f32_16x16x32_bf16 v[34:37], v[188:191], v[224:227], v[34:37]
	v_mfma_f32_16x16x32_bf16 v[22:25], v[180:183], v[232:235], v[22:25]
	v_mfma_f32_16x16x32_bf16 v[18:21], v[188:191], v[232:235], v[18:21]
	v_mfma_f32_16x16x32_bf16 v[70:73], v[184:187], v[200:203], v[70:73]
	v_mfma_f32_16x16x32_bf16 v[66:69], v[192:195], v[200:203], v[66:69]
	v_mfma_f32_16x16x32_bf16 v[54:57], v[184:187], v[220:223], v[54:57]
	v_mfma_f32_16x16x32_bf16 v[50:53], v[192:195], v[220:223], v[50:53]
	v_mfma_f32_16x16x32_bf16 v[38:41], v[184:187], v[228:231], v[38:41]
	v_mfma_f32_16x16x32_bf16 v[34:37], v[192:195], v[228:231], v[34:37]
	v_mfma_f32_16x16x32_bf16 v[22:25], v[184:187], v[236:239], v[22:25]
	v_mfma_f32_16x16x32_bf16 v[18:21], v[192:195], v[236:239], v[18:21]
	s_setprio 0
	s_barrier
	s_add_i32 s64, s64, 2
	s_add_u32 s20, s20, 0x100
	s_addc_u32 s21, s21, 0
	s_add_u32 s62, s62, 0x100
	s_addc_u32 s63, s63, 0
	s_cmp_gt_u32 s64, 13
	s_cbranch_scc0 .LBB0_762
	s_and_b64 vcc, exec, s[10:11]
	s_cbranch_vccz .LBB0_765
	s_barrier
